# v11 + accumulator zeroing removed (first K-iteration peeled, first MFMA per accumulator takes inline 0 as SrcC) + late-arriver threshold for background items 4 -> 8
# speedup vs baseline: 1.0041x; 1.0041x over previous
; #define PG8_STAGE(bufoff, gbase, voff) do { _Pragma("unroll") for (int _i = 0; _i < 2; ++_i) \
;         dma16((const char*)(gbase), (voff)[_i], ldsb + (bufoff) + ldsw + _i * 8192); } while (0)
; #define PG8_LDA(dst, b, h) do { const int a1_ = opqv(aoff0) ^ 64; _Pragma("unroll") for (int m = 0; m < 4; ++m) { dst[m][0] = *(const LAS bf16x8*)(lds + PG8_SA(b, h) + aoff0 + m * 2048); dst[m][1] = *(const LAS bf16x8*)(lds + PG8_SA(b, h) + a1_ + m * 2048); } } while (0)
; #define PG8_LDB(dst, b, h) do { const int b1_ = opqv(boff0) ^ 64; _Pragma("unroll") for (int n = 0; n < 2; ++n) { dst[n][0] = *(const LAS bf16x8*)(lds + PG8_SB(b, h) + boff0 + n * 2048); dst[n][1] = *(const LAS bf16x8*)(lds + PG8_SB(b, h) + b1_ + n * 2048); } } while (0)
; #define PG8_WAIT_V(n) asm volatile("s_waitcnt vmcnt(" #n ")" ::: "memory")
; #define PG8_WAIT_L(n) asm volatile("s_waitcnt lgkmcnt(" #n ")" ::: "memory")
; #define PG8_BAR __builtin_amdgcn_s_barrier()
; #define PG8_SCHED __builtin_amdgcn_sched_barrier(0)
; template <class Epi>
; __device__ __forceinline__ void gemm_phase(LAS unsigned char* lds, const Gemm g, const StaticOrder& S, const Epi& E, int wave_) {
;     ...
;                 for (int n = 0; n < 2; ++n) acc[a][b][m][n] = (f32x4){0.f, 0.f, 0.f, 0.f};
;     ...
;         const bool has_next = S.next(ui + 1, nxt);
;         const char* nA = has_next ? (const char*)g.A + (size_t)nxt.pm * tstepA : cA; const char* nB = has_next ? (const char*)g.Bt + (size_t)nxt.pn * tstepB : cB;
; #pragma unroll 1
;         for (int t = 0; t < nt; t += 2) {
;             const bool last = (t == nt - 2);
;             const char* a1 = cA + (size_t)(t + 1) * kstep;
;             const char* a2 = last ? nA : cA + (size_t)(t + 2) * kstep; const char* b2 = last ? nB : cB + (size_t)(t + 2) * kstep;
;             const char* a3 = a2 + kstep; const char* b3 = b2 + kstep;
;             PG8_STAGE(PG8_SA(1, 1), a1 + hstepA, voffA); PG8_LDB(B0, 0, 0); PG8_LDB(B1, 0, 1); PG8_SCHED; PG8_LDA(At, 0, 0);
;             PG8_WAIT_V(8); PG8_WAIT_L(0); PG8_BAR; PG8_MMA(0, 0, At, B0); PG8_MMA(0, 1, At, B1); PG8_BAR; PG8_SCHED;
;             PG8_STAGE(PG8_SB(0, 0), b2, voffB); PG8_STAGE(PG8_SB(0, 1), b2 + hstepB, voffB); PG8_STAGE(PG8_SA(0, 0), a2, voffA); PG8_LDA(At, 0, 1);
;             PG8_WAIT_V(8); PG8_WAIT_L(0); PG8_BAR; PG8_MMA(1, 0, At, B0); PG8_MMA(1, 1, At, B1); PG8_BAR; PG8_SCHED;
.LBB0_190:
	s_ashr_i32 s7, s6, 31
	s_lshl_b64 s[8:9], s[6:7], 20
	s_add_u32 s8, s16, s8
	s_addc_u32 s9, s17, s9
	s_and_b64 s[10:11], s[40:41], exec
	s_cselect_b32 s7, s9, s19
	s_cselect_b32 s45, s8, s18
	s_ashr_i32 s5, s4, 31
	s_lshl_b64 s[10:11], s[4:5], 20
	s_add_u32 s10, s21, s10
	s_addc_u32 s11, s30, s11
	s_and_b64 s[24:25], s[40:41], exec
	s_cselect_b32 s5, s11, s13
	s_cselect_b32 s46, s10, s12
	s_add_u32 s47, s12, 0x100
	s_addc_u32 s48, s13, 0
	s_add_u32 s12, s18, 0x80080
	s_addc_u32 s13, s19, 0
	s_mov_b32 s49, -2
	s_add_u32 s18, s12, 0xfff80080
	s_addc_u32 s19, s13, -1
	s_cmp_eq_u32 s49, 28
	s_cselect_b32 s26, s45, s18
	v_mov_b32_e32 v128, v139
	s_cselect_b32 s27, s7, s19
	s_cselect_b32 s24, s46, s47
	s_cselect_b32 s25, s5, s48
	s_add_u32 s18, s26, 0x80
	v_xad_u32 v128, v128, 64, s23
	v_add_u32_e32 v141, s23, v139
	s_addc_u32 s19, s27, 0
	ds_read_b128 v[130:133], v141
	ds_read_b128 v[142:145], v141 offset:2048
	ds_read_b128 v[146:149], v128
	ds_read_b128 v[150:153], v128 offset:2048
	v_mov_b32_e32 v128, v139
	s_add_i32 s52, 0, 0x14000
	v_add_u32_e32 v141, s52, v139
	v_xad_u32 v128, v128, 64, s52
	ds_read_b128 v[154:157], v141
	ds_read_b128 v[158:161], v141 offset:2048
	ds_read_b128 v[162:165], v128
	ds_read_b128 v[166:169], v128 offset:2048
	v_mov_b32_e32 v128, v138
	v_add_u32_e32 v141, 0, v138
	v_xad_u32 v128, v128, 64, 0
	ds_read_b128 v[170:173], v141
	ds_read_b128 v[174:177], v141 offset:2048
	ds_read_b128 v[178:181], v128
	ds_read_b128 v[192:195], v128 offset:2048
	ds_read_b128 v[196:199], v141 offset:4096
	ds_read_b128 v[200:203], v141 offset:6144
	ds_read_b128 v[204:207], v128 offset:4096
	ds_read_b128 v[208:211], v128 offset:6144
	s_mov_b32 m0, s14
	s_nop 0
	global_load_lds_dwordx4 v129, s[12:13]
	s_mov_b32 m0, s15
	s_nop 0
	global_load_lds_dwordx4 v135, s[12:13]
	s_waitcnt vmcnt(8)
	s_waitcnt lgkmcnt(0)
	s_barrier
	s_setprio 1
	s_waitcnt lgkmcnt(0)
	v_mfma_f32_16x16x32_bf16 v[124:127], v[130:133], v[170:173], 0
	v_mfma_f32_16x16x32_bf16 v[120:123], v[142:145], v[170:173], 0
	v_mfma_f32_16x16x32_bf16 v[112:115], v[130:133], v[174:177], 0
	v_mfma_f32_16x16x32_bf16 v[104:107], v[142:145], v[174:177], 0
	v_mfma_f32_16x16x32_bf16 v[96:99], v[130:133], v[196:199], 0
	v_mfma_f32_16x16x32_bf16 v[88:91], v[142:145], v[196:199], 0
	v_mfma_f32_16x16x32_bf16 v[80:83], v[130:133], v[200:203], 0
	v_mfma_f32_16x16x32_bf16 v[72:75], v[142:145], v[200:203], 0
	v_mfma_f32_16x16x32_bf16 v[124:127], v[146:149], v[178:181], v[124:127]
	v_mfma_f32_16x16x32_bf16 v[120:123], v[150:153], v[178:181], v[120:123]
	v_mfma_f32_16x16x32_bf16 v[112:115], v[146:149], v[192:195], v[112:115]
	v_mfma_f32_16x16x32_bf16 v[104:107], v[150:153], v[192:195], v[104:107]
	v_mfma_f32_16x16x32_bf16 v[96:99], v[146:149], v[204:207], v[96:99]
	v_mfma_f32_16x16x32_bf16 v[88:91], v[150:153], v[204:207], v[88:91]
	v_mfma_f32_16x16x32_bf16 v[80:83], v[146:149], v[208:211], v[80:83]
	v_mfma_f32_16x16x32_bf16 v[72:75], v[150:153], v[208:211], v[72:75]
	s_setprio 0
	s_setprio 1
	v_mfma_f32_16x16x32_bf16 v[116:119], v[154:157], v[170:173], 0
	v_mfma_f32_16x16x32_bf16 v[108:111], v[158:161], v[170:173], 0
	v_mfma_f32_16x16x32_bf16 v[100:103], v[154:157], v[174:177], 0
	v_mfma_f32_16x16x32_bf16 v[92:95], v[158:161], v[174:177], 0
	v_mfma_f32_16x16x32_bf16 v[84:87], v[154:157], v[196:199], 0
	v_mfma_f32_16x16x32_bf16 v[76:79], v[158:161], v[196:199], 0
	v_mfma_f32_16x16x32_bf16 v[68:71], v[154:157], v[200:203], 0
	v_mfma_f32_16x16x32_bf16 v[64:67], v[158:161], v[200:203], 0
	v_mfma_f32_16x16x32_bf16 v[116:119], v[162:165], v[178:181], v[116:119]
	v_mfma_f32_16x16x32_bf16 v[108:111], v[166:169], v[178:181], v[108:111]
	v_mfma_f32_16x16x32_bf16 v[100:103], v[162:165], v[192:195], v[100:103]
	v_mfma_f32_16x16x32_bf16 v[92:95], v[166:169], v[192:195], v[92:95]
	v_mfma_f32_16x16x32_bf16 v[84:87], v[162:165], v[204:207], v[84:87]
	v_mfma_f32_16x16x32_bf16 v[76:79], v[166:169], v[204:207], v[76:79]
	v_mfma_f32_16x16x32_bf16 v[68:71], v[162:165], v[208:211], v[68:71]
	v_mfma_f32_16x16x32_bf16 v[64:67], v[166:169], v[208:211], v[64:67]
	s_setprio 0
	s_barrier
	s_add_u32 s54, s24, 0x80000
	s_addc_u32 s55, s25, 0
	v_mov_b32_e32 v128, v138
	s_nop 0
	s_nop 0
	s_nop 0
	v_xad_u32 v128, v128, 64, 0
	ds_read_b128 v[170:173], v141 offset:16384
	ds_read_b128 v[174:177], v141 offset:18432
	ds_read_b128 v[178:181], v128 offset:16384
	ds_read_b128 v[192:195], v128 offset:18432
	ds_read_b128 v[196:199], v141 offset:20480
	ds_read_b128 v[200:203], v141 offset:22528
	ds_read_b128 v[204:207], v128 offset:20480
	ds_read_b128 v[208:211], v128 offset:22528
	s_mov_b32 m0, s80
	s_nop 0
	global_load_lds_dwordx4 v134, s[24:25]
	s_mov_b32 m0, s81
	s_nop 0
	global_load_lds_dwordx4 v136, s[24:25]
	s_mov_b32 m0, s29
	s_nop 0
	global_load_lds_dwordx4 v134, s[54:55]
	s_mov_b32 m0, s88
	s_nop 0
	global_load_lds_dwordx4 v136, s[54:55]
	s_mov_b32 m0, s76
	s_nop 0
	global_load_lds_dwordx4 v129, s[26:27]
	s_mov_b32 m0, s89
	s_nop 0
	global_load_lds_dwordx4 v135, s[26:27]
	s_waitcnt vmcnt(8)
	s_waitcnt lgkmcnt(0)
	s_barrier
; #define PG8_STAGE(bufoff, gbase, voff) do { _Pragma("unroll") for (int _i = 0; _i < 2; ++_i) \
;         dma16((const char*)(gbase), (voff)[_i], ldsb + (bufoff) + ldsw + _i * 8192); } while (0)
; #define PG8_LDA(dst, b, h) do { const int a1_ = opqv(aoff0) ^ 64; _Pragma("unroll") for (int m = 0; m < 4; ++m) { dst[m][0] = *(const LAS bf16x8*)(lds + PG8_SA(b, h) + aoff0 + m * 2048); dst[m][1] = *(const LAS bf16x8*)(lds + PG8_SA(b, h) + a1_ + m * 2048); } } while (0)
; #define PG8_LDB(dst, b, h) do { const int b1_ = opqv(boff0) ^ 64; _Pragma("unroll") for (int n = 0; n < 2; ++n) { dst[n][0] = *(const LAS bf16x8*)(lds + PG8_SB(b, h) + boff0 + n * 2048); dst[n][1] = *(const LAS bf16x8*)(lds + PG8_SB(b, h) + b1_ + n * 2048); } } while (0)
; #define PG8_MMA(ai, bj, At, Bt) do { __builtin_amdgcn_s_setprio(1); _Pragma("unroll") for (int m = 0; m < 4; ++m) _Pragma("unroll") for (int n = 0; n < 2; ++n) _Pragma("unroll") for (int k = 0; k < 2; ++k) \
;         acc[ai][bj][m][n] = __builtin_amdgcn_mfma_f32_16x16x32_bf16(Bt[n][k], At[m][k], acc[ai][bj][m][n], 0, 0, 0); __builtin_amdgcn_s_setprio(0); } while (0)
; #define PG8_WAIT_V(n) asm volatile("s_waitcnt vmcnt(" #n ")" ::: "memory")
; #define PG8_WAIT_L(n) asm volatile("s_waitcnt lgkmcnt(" #n ")" ::: "memory")
; #define PG8_BAR __builtin_amdgcn_s_barrier()
; #define PG8_SCHED __builtin_amdgcn_sched_barrier(0)
; template <class Epi>
; __device__ __forceinline__ void gemm_phase(LAS unsigned char* lds, const Gemm g, const StaticOrder& S, const Epi& E, int wave_) {
;     ...
;             PG8_WAIT_V(8); PG8_WAIT_L(0); PG8_BAR; PG8_MMA(1, 0, At, B0); PG8_MMA(1, 1, At, B1); PG8_BAR; PG8_SCHED;
;             PG8_STAGE(PG8_SA(0, 1), a2 + hstepA, voffA); PG8_LDB(B0, 1, 0); PG8_LDB(B1, 1, 1); PG8_SCHED; PG8_LDA(At, 1, 0);
;             PG8_WAIT_V(8); PG8_WAIT_L(0); PG8_BAR; PG8_MMA(0, 0, At, B0); PG8_MMA(0, 1, At, B1); PG8_BAR; PG8_SCHED;
;             PG8_STAGE(PG8_SB(1, 0), b3, voffB); PG8_STAGE(PG8_SB(1, 1), b3 + hstepB, voffB); PG8_STAGE(PG8_SA(1, 0), a3, voffA); PG8_LDA(At, 1, 1);
;             PG8_WAIT_V(8); PG8_WAIT_L(0); PG8_BAR; PG8_MMA(1, 0, At, B0); PG8_MMA(1, 1, At, B1); PG8_BAR; PG8_SCHED;
	s_setprio 1
	s_waitcnt lgkmcnt(0)
	v_mfma_f32_16x16x32_bf16 v[60:63], v[130:133], v[170:173], 0
	v_mfma_f32_16x16x32_bf16 v[56:59], v[142:145], v[170:173], 0
	v_mfma_f32_16x16x32_bf16 v[48:51], v[130:133], v[174:177], 0
	v_mfma_f32_16x16x32_bf16 v[40:43], v[142:145], v[174:177], 0
	v_mfma_f32_16x16x32_bf16 v[32:35], v[130:133], v[196:199], 0
	v_mfma_f32_16x16x32_bf16 v[24:27], v[142:145], v[196:199], 0
	v_mfma_f32_16x16x32_bf16 v[16:19], v[130:133], v[200:203], 0
	v_mfma_f32_16x16x32_bf16 v[8:11], v[142:145], v[200:203], 0
	v_mfma_f32_16x16x32_bf16 v[60:63], v[146:149], v[178:181], v[60:63]
	v_mfma_f32_16x16x32_bf16 v[56:59], v[150:153], v[178:181], v[56:59]
	v_mfma_f32_16x16x32_bf16 v[48:51], v[146:149], v[192:195], v[48:51]
	v_mfma_f32_16x16x32_bf16 v[40:43], v[150:153], v[192:195], v[40:43]
	v_mfma_f32_16x16x32_bf16 v[32:35], v[146:149], v[204:207], v[32:35]
	v_mfma_f32_16x16x32_bf16 v[24:27], v[150:153], v[204:207], v[24:27]
	v_mfma_f32_16x16x32_bf16 v[16:19], v[146:149], v[208:211], v[16:19]
	v_mfma_f32_16x16x32_bf16 v[8:11], v[150:153], v[208:211], v[8:11]
	s_setprio 0
	s_setprio 1
	v_mfma_f32_16x16x32_bf16 v[52:55], v[154:157], v[170:173], 0
	v_mfma_f32_16x16x32_bf16 v[44:47], v[158:161], v[170:173], 0
	v_mfma_f32_16x16x32_bf16 v[36:39], v[154:157], v[174:177], 0
	v_mfma_f32_16x16x32_bf16 v[28:31], v[158:161], v[174:177], 0
	v_mfma_f32_16x16x32_bf16 v[20:23], v[154:157], v[196:199], 0
	v_mfma_f32_16x16x32_bf16 v[12:15], v[158:161], v[196:199], 0
	v_mfma_f32_16x16x32_bf16 v[4:7], v[154:157], v[200:203], 0
	v_mfma_f32_16x16x32_bf16 v[0:3], v[158:161], v[200:203], 0
	v_mfma_f32_16x16x32_bf16 v[52:55], v[162:165], v[178:181], v[52:55]
	v_mfma_f32_16x16x32_bf16 v[44:47], v[166:169], v[178:181], v[44:47]
	v_mfma_f32_16x16x32_bf16 v[36:39], v[162:165], v[192:195], v[36:39]
	v_mfma_f32_16x16x32_bf16 v[28:31], v[166:169], v[192:195], v[28:31]
	v_mfma_f32_16x16x32_bf16 v[20:23], v[162:165], v[204:207], v[20:23]
	v_mfma_f32_16x16x32_bf16 v[12:15], v[166:169], v[204:207], v[12:15]
	v_mfma_f32_16x16x32_bf16 v[4:7], v[162:165], v[208:211], v[4:7]
	v_mfma_f32_16x16x32_bf16 v[0:3], v[166:169], v[208:211], v[0:3]
	s_setprio 0
	s_barrier
	s_add_u32 s26, s26, 0x80000
	s_addc_u32 s27, s27, 0
	s_mov_b32 m0, s1
	s_nop 0
	global_load_lds_dwordx4 v129, s[26:27]
	v_mov_b32_e32 v128, v139
	s_mov_b32 m0, s69
	s_nop 0
	global_load_lds_dwordx4 v135, s[26:27]
	v_add_u32_e32 v142, s34, v139
	v_xad_u32 v128, v128, 64, s34
	ds_read_b128 v[130:133], v142
	ds_read_b128 v[142:145], v142 offset:2048
	ds_read_b128 v[146:149], v128
	ds_read_b128 v[150:153], v128 offset:2048
	v_mov_b32_e32 v128, v139
	s_add_i32 s26, 0, 0x1c000
	v_add_u32_e32 v158, s26, v139
	v_xad_u32 v128, v128, 64, s26
	ds_read_b128 v[154:157], v158
	ds_read_b128 v[158:161], v158 offset:2048
	ds_read_b128 v[162:165], v128
	ds_read_b128 v[166:169], v128 offset:2048
	v_mov_b32_e32 v128, v138
	s_nop 0
	v_xad_u32 v128, v128, 64, 0
	ds_read_b128 v[170:173], v141 offset:32768
	ds_read_b128 v[174:177], v141 offset:34816
	ds_read_b128 v[178:181], v128 offset:32768
	ds_read_b128 v[192:195], v128 offset:34816
	ds_read_b128 v[196:199], v141 offset:36864
	ds_read_b128 v[200:203], v141 offset:38912
	ds_read_b128 v[204:207], v128 offset:36864
	ds_read_b128 v[208:211], v128 offset:38912
	s_waitcnt vmcnt(8)
	s_waitcnt lgkmcnt(0)
	s_barrier
	s_setprio 1
	s_waitcnt lgkmcnt(0)
	v_mfma_f32_16x16x32_bf16 v[124:127], v[130:133], v[170:173], v[124:127]
	v_mfma_f32_16x16x32_bf16 v[120:123], v[142:145], v[170:173], v[120:123]
	v_mfma_f32_16x16x32_bf16 v[112:115], v[130:133], v[174:177], v[112:115]
	v_mfma_f32_16x16x32_bf16 v[104:107], v[142:145], v[174:177], v[104:107]
	v_mfma_f32_16x16x32_bf16 v[96:99], v[130:133], v[196:199], v[96:99]
	v_mfma_f32_16x16x32_bf16 v[88:91], v[142:145], v[196:199], v[88:91]
	v_mfma_f32_16x16x32_bf16 v[80:83], v[130:133], v[200:203], v[80:83]
	v_mfma_f32_16x16x32_bf16 v[72:75], v[142:145], v[200:203], v[72:75]
	v_mfma_f32_16x16x32_bf16 v[124:127], v[146:149], v[178:181], v[124:127]
	v_mfma_f32_16x16x32_bf16 v[120:123], v[150:153], v[178:181], v[120:123]
	v_mfma_f32_16x16x32_bf16 v[112:115], v[146:149], v[192:195], v[112:115]
	v_mfma_f32_16x16x32_bf16 v[104:107], v[150:153], v[192:195], v[104:107]
	v_mfma_f32_16x16x32_bf16 v[96:99], v[146:149], v[204:207], v[96:99]
	v_mfma_f32_16x16x32_bf16 v[88:91], v[150:153], v[204:207], v[88:91]
	v_mfma_f32_16x16x32_bf16 v[80:83], v[146:149], v[208:211], v[80:83]
	v_mfma_f32_16x16x32_bf16 v[72:75], v[150:153], v[208:211], v[72:75]
	s_setprio 0
	s_setprio 1
	v_mfma_f32_16x16x32_bf16 v[116:119], v[154:157], v[170:173], v[116:119]
	s_add_u32 s26, s24, 0x80
	s_addc_u32 s27, s25, 0
	v_mfma_f32_16x16x32_bf16 v[108:111], v[158:161], v[170:173], v[108:111]
	v_mfma_f32_16x16x32_bf16 v[100:103], v[154:157], v[174:177], v[100:103]
	v_mfma_f32_16x16x32_bf16 v[92:95], v[158:161], v[174:177], v[92:95]
	v_mfma_f32_16x16x32_bf16 v[84:87], v[154:157], v[196:199], v[84:87]
	v_mfma_f32_16x16x32_bf16 v[76:79], v[158:161], v[196:199], v[76:79]
	v_mfma_f32_16x16x32_bf16 v[68:71], v[154:157], v[200:203], v[68:71]
	v_mfma_f32_16x16x32_bf16 v[64:67], v[158:161], v[200:203], v[64:67]
	v_mfma_f32_16x16x32_bf16 v[116:119], v[162:165], v[178:181], v[116:119]
	v_mfma_f32_16x16x32_bf16 v[108:111], v[166:169], v[178:181], v[108:111]
	v_mfma_f32_16x16x32_bf16 v[100:103], v[162:165], v[192:195], v[100:103]
	v_mfma_f32_16x16x32_bf16 v[92:95], v[166:169], v[192:195], v[92:95]
	v_mfma_f32_16x16x32_bf16 v[84:87], v[162:165], v[204:207], v[84:87]
	v_mfma_f32_16x16x32_bf16 v[76:79], v[166:169], v[204:207], v[76:79]
	v_mfma_f32_16x16x32_bf16 v[68:71], v[162:165], v[208:211], v[68:71]
	v_mfma_f32_16x16x32_bf16 v[64:67], v[166:169], v[208:211], v[64:67]
	s_setprio 0
	s_barrier
; #define PG8_STAGE(bufoff, gbase, voff) do { _Pragma("unroll") for (int _i = 0; _i < 2; ++_i) \
;         dma16((const char*)(gbase), (voff)[_i], ldsb + (bufoff) + ldsw + _i * 8192); } while (0)
; #define PG8_LDA(dst, b, h) do { const int a1_ = opqv(aoff0) ^ 64; _Pragma("unroll") for (int m = 0; m < 4; ++m) { dst[m][0] = *(const LAS bf16x8*)(lds + PG8_SA(b, h) + aoff0 + m * 2048); dst[m][1] = *(const LAS bf16x8*)(lds + PG8_SA(b, h) + a1_ + m * 2048); } } while (0)
; #define PG8_MMA(ai, bj, At, Bt) do { __builtin_amdgcn_s_setprio(1); _Pragma("unroll") for (int m = 0; m < 4; ++m) _Pragma("unroll") for (int n = 0; n < 2; ++n) _Pragma("unroll") for (int k = 0; k < 2; ++k) \
;         acc[ai][bj][m][n] = __builtin_amdgcn_mfma_f32_16x16x32_bf16(Bt[n][k], At[m][k], acc[ai][bj][m][n], 0, 0, 0); __builtin_amdgcn_s_setprio(0); } while (0)
; #define PG8_WAIT_V(n) asm volatile("s_waitcnt vmcnt(" #n ")" ::: "memory")
; #define PG8_WAIT_L(n) asm volatile("s_waitcnt lgkmcnt(" #n ")" ::: "memory")
; #define PG8_BAR __builtin_amdgcn_s_barrier()
; #define PG8_SCHED __builtin_amdgcn_sched_barrier(0)
; template <class Epi>
; __device__ __forceinline__ void gemm_phase(LAS unsigned char* lds, const Gemm g, const StaticOrder& S, const Epi& E, int wave_) {
;     ...
;         for (int t = 0; t < nt; t += 2) {
;     ...
;             PG8_STAGE(PG8_SB(1, 0), b3, voffB); PG8_STAGE(PG8_SB(1, 1), b3 + hstepB, voffB); PG8_STAGE(PG8_SA(1, 0), a3, voffA); PG8_LDA(At, 1, 1);
;             PG8_WAIT_V(8); PG8_WAIT_L(0); PG8_BAR; PG8_MMA(1, 0, At, B0); PG8_MMA(1, 1, At, B1); PG8_BAR; PG8_SCHED;
	s_add_u32 s24, s24, 0x80080
	s_addc_u32 s25, s25, 0
	v_mov_b32_e32 v128, v138
	s_nop 0
	s_nop 0
	v_xad_u32 v128, v128, 64, 0
	ds_read_b128 v[170:173], v141 offset:49152
	ds_read_b128 v[174:177], v141 offset:51200
	ds_read_b128 v[178:181], v128 offset:49152
	ds_read_b128 v[192:195], v128 offset:51200
	ds_read_b128 v[196:199], v141 offset:53248
	ds_read_b128 v[200:203], v141 offset:55296
	ds_read_b128 v[204:207], v128 offset:53248
	ds_read_b128 v[208:211], v128 offset:55296
	s_mov_b32 m0, s35
	s_nop 0
	global_load_lds_dwordx4 v134, s[26:27]
	s_mov_b32 m0, s33
	s_nop 0
	global_load_lds_dwordx4 v136, s[26:27]
	s_mov_b32 m0, s77
	s_nop 0
	global_load_lds_dwordx4 v134, s[24:25]
	s_mov_b32 m0, s3
	s_nop 0
	global_load_lds_dwordx4 v136, s[24:25]
	s_mov_b32 m0, s22
	s_nop 0
	global_load_lds_dwordx4 v129, s[18:19]
	s_mov_b32 m0, s2
	s_nop 0
	global_load_lds_dwordx4 v135, s[18:19]
	s_waitcnt vmcnt(8)
	s_waitcnt lgkmcnt(0)
	s_barrier
	s_setprio 1
	s_waitcnt lgkmcnt(0)
	v_mfma_f32_16x16x32_bf16 v[60:63], v[130:133], v[170:173], v[60:63]
	v_mfma_f32_16x16x32_bf16 v[56:59], v[142:145], v[170:173], v[56:59]
	v_mfma_f32_16x16x32_bf16 v[48:51], v[130:133], v[174:177], v[48:51]
	v_mfma_f32_16x16x32_bf16 v[40:43], v[142:145], v[174:177], v[40:43]
	v_mfma_f32_16x16x32_bf16 v[32:35], v[130:133], v[196:199], v[32:35]
	v_mfma_f32_16x16x32_bf16 v[24:27], v[142:145], v[196:199], v[24:27]
	v_mfma_f32_16x16x32_bf16 v[16:19], v[130:133], v[200:203], v[16:19]
	v_mfma_f32_16x16x32_bf16 v[8:11], v[142:145], v[200:203], v[8:11]
	v_mfma_f32_16x16x32_bf16 v[60:63], v[146:149], v[178:181], v[60:63]
	v_mfma_f32_16x16x32_bf16 v[56:59], v[150:153], v[178:181], v[56:59]
	v_mfma_f32_16x16x32_bf16 v[48:51], v[146:149], v[192:195], v[48:51]
	v_mfma_f32_16x16x32_bf16 v[40:43], v[150:153], v[192:195], v[40:43]
	v_mfma_f32_16x16x32_bf16 v[32:35], v[146:149], v[204:207], v[32:35]
	v_mfma_f32_16x16x32_bf16 v[24:27], v[150:153], v[204:207], v[24:27]
	v_mfma_f32_16x16x32_bf16 v[16:19], v[146:149], v[208:211], v[16:19]
	v_mfma_f32_16x16x32_bf16 v[8:11], v[150:153], v[208:211], v[8:11]
	s_setprio 0
	s_setprio 1
	v_mfma_f32_16x16x32_bf16 v[52:55], v[154:157], v[170:173], v[52:55]
	v_mfma_f32_16x16x32_bf16 v[44:47], v[158:161], v[170:173], v[44:47]
	v_mfma_f32_16x16x32_bf16 v[36:39], v[154:157], v[174:177], v[36:39]
	v_mfma_f32_16x16x32_bf16 v[28:31], v[158:161], v[174:177], v[28:31]
	v_mfma_f32_16x16x32_bf16 v[20:23], v[154:157], v[196:199], v[20:23]
	v_mfma_f32_16x16x32_bf16 v[12:15], v[158:161], v[196:199], v[12:15]
	v_mfma_f32_16x16x32_bf16 v[4:7], v[154:157], v[200:203], v[4:7]
	v_mfma_f32_16x16x32_bf16 v[0:3], v[158:161], v[200:203], v[0:3]
	v_mfma_f32_16x16x32_bf16 v[52:55], v[162:165], v[178:181], v[52:55]
	v_mfma_f32_16x16x32_bf16 v[44:47], v[166:169], v[178:181], v[44:47]
	v_mfma_f32_16x16x32_bf16 v[36:39], v[162:165], v[192:195], v[36:39]
	v_mfma_f32_16x16x32_bf16 v[28:31], v[166:169], v[192:195], v[28:31]
	v_mfma_f32_16x16x32_bf16 v[20:23], v[162:165], v[204:207], v[20:23]
	v_mfma_f32_16x16x32_bf16 v[12:15], v[166:169], v[204:207], v[12:15]
	v_mfma_f32_16x16x32_bf16 v[4:7], v[162:165], v[208:211], v[4:7]
	v_mfma_f32_16x16x32_bf16 v[0:3], v[166:169], v[208:211], v[0:3]
	s_setprio 0
	s_barrier
	s_add_i32 s49, s49, 2
	s_add_u32 s47, s47, 0x100
	s_addc_u32 s48, s48, 0
	s_add_u32 s12, s12, 0x100
	s_addc_u32 s13, s13, 0
	s_cmp_gt_u32 s49, 29
	s_cbranch_scc0 .LBB0_191
	s_branch .Lpeel_exit_8

; #define PG8_BAR __builtin_amdgcn_s_barrier()
; template <class Epi>
; __device__ __forceinline__ void gemm_phase(LAS unsigned char* lds, const Gemm g, const StaticOrder& S, const Epi& E, int wave_) {
;     ...
;         if (wr == 0) PG8_BAR;
.Lpeel_exit_8:
	v_readlane_b32 s12, v253, 13
	v_readlane_b32 s13, v253, 14
	s_and_b64 vcc, exec, s[12:13]
	s_cbranch_vccz .LBB0_194
	s_barrier

; __device__ __forceinline__ unsigned xb_add(unsigned* p, unsigned v) { return __hip_atomic_fetch_add(p, v, __ATOMIC_RELAXED, __HIP_MEMORY_SCOPE_AGENT); }
; __device__ __forceinline__ void xcd_barrier_bg(const XcdBarrier& b, const Frame& F, unsigned char* ws, int Ln, BgState& bg) {
;     ...
;         unsigned nloc = b.st[0], nx = b.st[1];
;         if (nloc == 0u) { xcd_barrier_complete(bar, b.x, nloc, nx); b.st[0] = nloc; b.st[1] = nx; }
;         const unsigned old = xb_add(&bar[XB_XSUB(b.x)], 1u);
;         const unsigned gen = old / nloc;
;         b.st[2] = gen; b.st[3] = (old + 1u == (gen + 1u) * nloc) ? 2u : ((old + BG_LATE >= (gen + 1u) * nloc) ? 1u : 0u);
.LBB0_213:
	v_readlane_b32 s8, v253, 5
	s_lshl_b32 s8, s8, 2
	s_add_u32 s8, s4, s8
	s_addc_u32 s9, s5, 0
	s_waitcnt lgkmcnt(0)
	v_mov_b32_e32 v1, s8
	v_add_co_u32_e32 v2, vcc, 0x1000, v1
	v_mov_b32_e32 v1, s9
	s_nop 0
	v_addc_co_u32_e32 v3, vcc, 0, v1, vcc
	v_mov_b32_e32 v1, 1
	flat_atomic_add v2, v[2:3], v1 offset:1024 sc0
	v_cvt_f32_u32_e32 v1, v0
	v_sub_u32_e32 v3, 0, v0
	v_readlane_b32 s8, v255, 9
	v_rcp_iflag_f32_e32 v1, v1
	s_nop 0
	v_mul_f32_e32 v1, 0x4f7ffffe, v1
	v_cvt_u32_f32_e32 v1, v1
	v_mul_lo_u32 v3, v3, v1
	v_mul_hi_u32 v3, v1, v3
	v_add_u32_e32 v1, v1, v3
	s_waitcnt vmcnt(0) lgkmcnt(0)
	v_mul_hi_u32 v1, v2, v1
	v_mul_lo_u32 v3, v1, v0
	v_sub_u32_e32 v3, v2, v3
	v_cmp_ge_u32_e32 vcc, v3, v0
	v_add_u32_e32 v4, 1, v1
	s_nop 0
	v_cndmask_b32_e32 v1, v1, v4, vcc
	v_sub_u32_e32 v4, v3, v0
	v_cndmask_b32_e32 v3, v3, v4, vcc
	v_cmp_ge_u32_e32 vcc, v3, v0
	v_add_u32_e32 v3, 1, v1
	s_nop 0
	v_cndmask_b32_e32 v1, v1, v3, vcc
	v_mov_b32_e32 v3, s8
	ds_write_b32 v3, v1
	v_mad_u64_u32 v[0:1], s[8:9], v0, v1, v[0:1]
	v_add_u32_e32 v1, 8, v2
	v_add_u32_e32 v3, 1, v2
	v_cmp_ge_u32_e32 vcc, v1, v0
	v_readlane_b32 s8, v255, 10
	s_nop 0
	v_cndmask_b32_e64 v1, 0, 1, vcc
	v_cmp_ne_u32_e32 vcc, v3, v0
	s_nop 1
	v_cndmask_b32_e32 v0, 2, v1, vcc
	v_mov_b32_e32 v1, s8
	ds_write_b32 v1, v0

; #define PG8_STAGE(bufoff, gbase, voff) do { _Pragma("unroll") for (int _i = 0; _i < 2; ++_i) \
;         dma16((const char*)(gbase), (voff)[_i], ldsb + (bufoff) + ldsw + _i * 8192); } while (0)
; #define PG8_LDA(dst, b, h) do { const int a1_ = opqv(aoff0) ^ 64; _Pragma("unroll") for (int m = 0; m < 4; ++m) { dst[m][0] = *(const LAS bf16x8*)(lds + PG8_SA(b, h) + aoff0 + m * 2048); dst[m][1] = *(const LAS bf16x8*)(lds + PG8_SA(b, h) + a1_ + m * 2048); } } while (0)
; #define PG8_LDB(dst, b, h) do { const int b1_ = opqv(boff0) ^ 64; _Pragma("unroll") for (int n = 0; n < 2; ++n) { dst[n][0] = *(const LAS bf16x8*)(lds + PG8_SB(b, h) + boff0 + n * 2048); dst[n][1] = *(const LAS bf16x8*)(lds + PG8_SB(b, h) + b1_ + n * 2048); } } while (0)
; #define PG8_MMA(ai, bj, At, Bt) do { __builtin_amdgcn_s_setprio(1); _Pragma("unroll") for (int m = 0; m < 4; ++m) _Pragma("unroll") for (int n = 0; n < 2; ++n) _Pragma("unroll") for (int k = 0; k < 2; ++k) \
;         acc[ai][bj][m][n] = __builtin_amdgcn_mfma_f32_16x16x32_bf16(Bt[n][k], At[m][k], acc[ai][bj][m][n], 0, 0, 0); __builtin_amdgcn_s_setprio(0); } while (0)
; #define PG8_WAIT_V(n) asm volatile("s_waitcnt vmcnt(" #n ")" ::: "memory")
; #define PG8_WAIT_L(n) asm volatile("s_waitcnt lgkmcnt(" #n ")" ::: "memory")
; template <class Epi>
; __device__ __forceinline__ void gemm_phase(LAS unsigned char* lds, const Gemm g, const StaticOrder& S, const Epi& E, int wave_) {
;     ...
;             const char* a1 = cA + (size_t)(t + 1) * kstep;
;             const char* a2 = last ? nA : cA + (size_t)(t + 2) * kstep; const char* b2 = last ? nB : cB + (size_t)(t + 2) * kstep;
;             const char* a3 = a2 + kstep; const char* b3 = b2 + kstep;
;             PG8_STAGE(PG8_SA(1, 1), a1 + hstepA, voffA); PG8_LDB(B0, 0, 0); PG8_LDB(B1, 0, 1); PG8_SCHED; PG8_LDA(At, 0, 0);
;             PG8_WAIT_V(8); PG8_WAIT_L(0); PG8_BAR; PG8_MMA(0, 0, At, B0); PG8_MMA(0, 1, At, B1); PG8_BAR; PG8_SCHED;
;             PG8_STAGE(PG8_SB(0, 0), b2, voffB); PG8_STAGE(PG8_SB(0, 1), b2 + hstepB, voffB); PG8_STAGE(PG8_SA(0, 0), a2, voffA); PG8_LDA(At, 0, 1);
;     ...
;         for (int a = 0; a < 2; ++a)
; #pragma unroll
;             for (int b = 0; b < 2; ++b)
; #pragma unroll
;                 for (int m = 0; m < 4; ++m)
; #pragma unroll
;                     for (int n = 0; n < 2; ++n) acc[a][b][m][n] = (f32x4){0.f, 0.f, 0.f, 0.f};
.LBB0_573:
	s_ashr_i32 s11, s10, 31
	s_lshl_b64 s[16:17], s[10:11], 20
	s_add_u32 s18, s21, s16
	s_addc_u32 s19, s44, s17
	s_and_b64 s[16:17], s[42:43], exec
	s_cselect_b32 s11, s19, s27
	s_cselect_b32 s16, s18, s26
	s_ashr_i32 s9, s8, 31
	s_lshl_b64 s[24:25], s[8:9], 20
	s_add_u32 s24, s45, s24
	s_addc_u32 s25, s46, s25
	s_and_b64 s[30:31], s[42:43], exec
	s_cselect_b32 s9, s25, s13
	s_cselect_b32 s17, s24, s12
	s_add_u32 s52, s12, 0x100
	s_addc_u32 s56, s13, 0
	s_add_u32 s12, s26, 0x80080
	s_addc_u32 s13, s27, 0
	s_mov_b32 s57, -2
	s_add_u32 s26, s12, 0xfff80080
	s_addc_u32 s27, s13, -1
	s_cmp_eq_u32 s57, 28
	s_cselect_b32 s36, s16, s26
	v_mov_b32_e32 v128, v144
	s_cselect_b32 s37, s11, s27
	s_cselect_b32 s30, s17, s52
	s_cselect_b32 s31, s9, s56
	s_add_u32 s26, s36, 0x80
	v_add_u32_e32 v137, s23, v144
	v_xad_u32 v136, v128, 64, s23
	s_addc_u32 s27, s37, 0
	ds_read_b128 v[128:131], v137
	ds_read_b128 v[146:149], v137 offset:2048
	ds_read_b128 v[150:153], v136
	ds_read_b128 v[154:157], v136 offset:2048
	v_mov_b32_e32 v136, v144
	s_add_i32 s58, 0, 0x14000
	v_add_u32_e32 v137, s58, v144
	v_xad_u32 v136, v136, 64, s58
	ds_read_b128 v[158:161], v137
	ds_read_b128 v[162:165], v137 offset:2048
	ds_read_b128 v[166:169], v136
	ds_read_b128 v[170:173], v136 offset:2048
	v_mov_b32_e32 v136, v143
	v_add_u32_e32 v137, 0, v143
	v_xad_u32 v136, v136, 64, 0
	ds_read_b128 v[174:177], v137
	ds_read_b128 v[178:181], v137 offset:2048
	ds_read_b128 v[192:195], v136
	ds_read_b128 v[196:199], v136 offset:2048
	ds_read_b128 v[200:203], v137 offset:4096
	ds_read_b128 v[204:207], v137 offset:6144
	ds_read_b128 v[208:211], v136 offset:4096
	ds_read_b128 v[212:215], v136 offset:6144
	s_mov_b32 m0, s14
	s_nop 0
	global_load_lds_dwordx4 v138, s[12:13]
	s_mov_b32 m0, s15
	s_nop 0
	global_load_lds_dwordx4 v140, s[12:13]
	s_waitcnt vmcnt(8)
	s_waitcnt lgkmcnt(0)
	s_barrier
	s_setprio 1
	s_waitcnt lgkmcnt(0)
	v_mfma_f32_16x16x32_bf16 v[124:127], v[128:131], v[174:177], 0
	v_mfma_f32_16x16x32_bf16 v[120:123], v[146:149], v[174:177], 0
	v_mfma_f32_16x16x32_bf16 v[108:111], v[128:131], v[178:181], 0
	v_mfma_f32_16x16x32_bf16 v[104:107], v[146:149], v[178:181], 0
	v_mfma_f32_16x16x32_bf16 v[92:95], v[128:131], v[200:203], 0
	v_mfma_f32_16x16x32_bf16 v[88:91], v[146:149], v[200:203], 0
	v_mfma_f32_16x16x32_bf16 v[76:79], v[128:131], v[204:207], 0
	v_mfma_f32_16x16x32_bf16 v[72:75], v[146:149], v[204:207], 0
	v_mfma_f32_16x16x32_bf16 v[124:127], v[150:153], v[192:195], v[124:127]
	v_mfma_f32_16x16x32_bf16 v[120:123], v[154:157], v[192:195], v[120:123]
	v_mfma_f32_16x16x32_bf16 v[108:111], v[150:153], v[196:199], v[108:111]
	v_mfma_f32_16x16x32_bf16 v[104:107], v[154:157], v[196:199], v[104:107]
	v_mfma_f32_16x16x32_bf16 v[92:95], v[150:153], v[208:211], v[92:95]
	v_mfma_f32_16x16x32_bf16 v[88:91], v[154:157], v[208:211], v[88:91]
	v_mfma_f32_16x16x32_bf16 v[76:79], v[150:153], v[212:215], v[76:79]
	v_mfma_f32_16x16x32_bf16 v[72:75], v[154:157], v[212:215], v[72:75]
	s_setprio 0
	s_setprio 1
	v_mfma_f32_16x16x32_bf16 v[116:119], v[158:161], v[174:177], 0
	v_mfma_f32_16x16x32_bf16 v[112:115], v[162:165], v[174:177], 0
	v_mfma_f32_16x16x32_bf16 v[100:103], v[158:161], v[178:181], 0
	v_mfma_f32_16x16x32_bf16 v[96:99], v[162:165], v[178:181], 0
	v_mfma_f32_16x16x32_bf16 v[84:87], v[158:161], v[200:203], 0
	v_mfma_f32_16x16x32_bf16 v[80:83], v[162:165], v[200:203], 0
	v_mfma_f32_16x16x32_bf16 v[68:71], v[158:161], v[204:207], 0
	v_mfma_f32_16x16x32_bf16 v[64:67], v[162:165], v[204:207], 0
	v_mfma_f32_16x16x32_bf16 v[116:119], v[166:169], v[192:195], v[116:119]
	v_mfma_f32_16x16x32_bf16 v[112:115], v[170:173], v[192:195], v[112:115]
	v_mfma_f32_16x16x32_bf16 v[100:103], v[166:169], v[196:199], v[100:103]
	v_mfma_f32_16x16x32_bf16 v[96:99], v[170:173], v[196:199], v[96:99]
	v_mfma_f32_16x16x32_bf16 v[84:87], v[166:169], v[208:211], v[84:87]
	v_mfma_f32_16x16x32_bf16 v[80:83], v[170:173], v[208:211], v[80:83]
	v_mfma_f32_16x16x32_bf16 v[68:71], v[166:169], v[212:215], v[68:71]
	v_mfma_f32_16x16x32_bf16 v[64:67], v[170:173], v[212:215], v[64:67]
	s_setprio 0
	s_barrier
	v_mov_b32_e32 v136, v143
	s_add_u32 s58, s30, 0x80000
	s_addc_u32 s59, s31, 0
	s_nop 0
	s_nop 0
	s_nop 0
	v_xad_u32 v136, v136, 64, 0
	ds_read_b128 v[174:177], v137 offset:16384
	ds_read_b128 v[178:181], v137 offset:18432
	ds_read_b128 v[192:195], v136 offset:16384
	ds_read_b128 v[196:199], v136 offset:18432
	ds_read_b128 v[200:203], v137 offset:20480
	ds_read_b128 v[204:207], v137 offset:22528
	ds_read_b128 v[208:211], v136 offset:20480
	ds_read_b128 v[212:215], v136 offset:22528
	s_mov_b32 m0, s80
	s_nop 0
	global_load_lds_dwordx4 v139, s[30:31]
	s_mov_b32 m0, s81
	s_nop 0
	global_load_lds_dwordx4 v141, s[30:31]
	s_mov_b32 m0, s29
	s_nop 0
	global_load_lds_dwordx4 v139, s[58:59]
	s_mov_b32 m0, s88
	s_nop 0
	global_load_lds_dwordx4 v141, s[58:59]
	s_mov_b32 m0, s76
	s_nop 0
	global_load_lds_dwordx4 v138, s[36:37]
	s_mov_b32 m0, s89
	s_nop 0
	global_load_lds_dwordx4 v140, s[36:37]
	s_waitcnt vmcnt(8)
	s_waitcnt lgkmcnt(0)
	s_barrier
; #define PG8_STAGE(bufoff, gbase, voff) do { _Pragma("unroll") for (int _i = 0; _i < 2; ++_i) \
;         dma16((const char*)(gbase), (voff)[_i], ldsb + (bufoff) + ldsw + _i * 8192); } while (0)
; #define PG8_LDA(dst, b, h) do { const int a1_ = opqv(aoff0) ^ 64; _Pragma("unroll") for (int m = 0; m < 4; ++m) { dst[m][0] = *(const LAS bf16x8*)(lds + PG8_SA(b, h) + aoff0 + m * 2048); dst[m][1] = *(const LAS bf16x8*)(lds + PG8_SA(b, h) + a1_ + m * 2048); } } while (0)
; #define PG8_LDB(dst, b, h) do { const int b1_ = opqv(boff0) ^ 64; _Pragma("unroll") for (int n = 0; n < 2; ++n) { dst[n][0] = *(const LAS bf16x8*)(lds + PG8_SB(b, h) + boff0 + n * 2048); dst[n][1] = *(const LAS bf16x8*)(lds + PG8_SB(b, h) + b1_ + n * 2048); } } while (0)
; #define PG8_MMA(ai, bj, At, Bt) do { __builtin_amdgcn_s_setprio(1); _Pragma("unroll") for (int m = 0; m < 4; ++m) _Pragma("unroll") for (int n = 0; n < 2; ++n) _Pragma("unroll") for (int k = 0; k < 2; ++k) \
;         acc[ai][bj][m][n] = __builtin_amdgcn_mfma_f32_16x16x32_bf16(Bt[n][k], At[m][k], acc[ai][bj][m][n], 0, 0, 0); __builtin_amdgcn_s_setprio(0); } while (0)
; #define PG8_WAIT_V(n) asm volatile("s_waitcnt vmcnt(" #n ")" ::: "memory")
; #define PG8_WAIT_L(n) asm volatile("s_waitcnt lgkmcnt(" #n ")" ::: "memory")
; #define PG8_BAR __builtin_amdgcn_s_barrier()
; #define PG8_SCHED __builtin_amdgcn_sched_barrier(0)
; template <class Epi>
; __device__ __forceinline__ void gemm_phase(LAS unsigned char* lds, const Gemm g, const StaticOrder& S, const Epi& E, int wave_) {
;     ...
;             PG8_WAIT_V(8); PG8_WAIT_L(0); PG8_BAR; PG8_MMA(1, 0, At, B0); PG8_MMA(1, 1, At, B1); PG8_BAR; PG8_SCHED;
;             PG8_STAGE(PG8_SA(0, 1), a2 + hstepA, voffA); PG8_LDB(B0, 1, 0); PG8_LDB(B1, 1, 1); PG8_SCHED; PG8_LDA(At, 1, 0);
;             PG8_WAIT_V(8); PG8_WAIT_L(0); PG8_BAR; PG8_MMA(0, 0, At, B0); PG8_MMA(0, 1, At, B1); PG8_BAR; PG8_SCHED;
	s_setprio 1
	s_waitcnt lgkmcnt(0)
	v_mfma_f32_16x16x32_bf16 v[60:63], v[128:131], v[174:177], 0
	v_mfma_f32_16x16x32_bf16 v[56:59], v[146:149], v[174:177], 0
	v_mfma_f32_16x16x32_bf16 v[44:47], v[128:131], v[178:181], 0
	v_mfma_f32_16x16x32_bf16 v[40:43], v[146:149], v[178:181], 0
	v_mfma_f32_16x16x32_bf16 v[28:31], v[128:131], v[200:203], 0
	v_mfma_f32_16x16x32_bf16 v[24:27], v[146:149], v[200:203], 0
	v_mfma_f32_16x16x32_bf16 v[12:15], v[128:131], v[204:207], 0
	v_mfma_f32_16x16x32_bf16 v[8:11], v[146:149], v[204:207], 0
	v_mfma_f32_16x16x32_bf16 v[60:63], v[150:153], v[192:195], v[60:63]
	v_mfma_f32_16x16x32_bf16 v[56:59], v[154:157], v[192:195], v[56:59]
	v_mfma_f32_16x16x32_bf16 v[44:47], v[150:153], v[196:199], v[44:47]
	v_mfma_f32_16x16x32_bf16 v[40:43], v[154:157], v[196:199], v[40:43]
	v_mfma_f32_16x16x32_bf16 v[28:31], v[150:153], v[208:211], v[28:31]
	v_mfma_f32_16x16x32_bf16 v[24:27], v[154:157], v[208:211], v[24:27]
	v_mfma_f32_16x16x32_bf16 v[12:15], v[150:153], v[212:215], v[12:15]
	v_mfma_f32_16x16x32_bf16 v[8:11], v[154:157], v[212:215], v[8:11]
	s_setprio 0
	s_setprio 1
	v_mfma_f32_16x16x32_bf16 v[52:55], v[158:161], v[174:177], 0
	v_mfma_f32_16x16x32_bf16 v[48:51], v[162:165], v[174:177], 0
	v_mfma_f32_16x16x32_bf16 v[36:39], v[158:161], v[178:181], 0
	v_mfma_f32_16x16x32_bf16 v[32:35], v[162:165], v[178:181], 0
	v_mfma_f32_16x16x32_bf16 v[20:23], v[158:161], v[200:203], 0
	v_mfma_f32_16x16x32_bf16 v[16:19], v[162:165], v[200:203], 0
	v_mfma_f32_16x16x32_bf16 v[4:7], v[158:161], v[204:207], 0
	v_mfma_f32_16x16x32_bf16 v[0:3], v[162:165], v[204:207], 0
	v_mfma_f32_16x16x32_bf16 v[52:55], v[166:169], v[192:195], v[52:55]
	v_mfma_f32_16x16x32_bf16 v[48:51], v[170:173], v[192:195], v[48:51]
	v_mfma_f32_16x16x32_bf16 v[36:39], v[166:169], v[196:199], v[36:39]
	v_mfma_f32_16x16x32_bf16 v[32:35], v[170:173], v[196:199], v[32:35]
	v_mfma_f32_16x16x32_bf16 v[20:23], v[166:169], v[208:211], v[20:23]
	v_mfma_f32_16x16x32_bf16 v[16:19], v[170:173], v[208:211], v[16:19]
	v_mfma_f32_16x16x32_bf16 v[4:7], v[166:169], v[212:215], v[4:7]
	v_mfma_f32_16x16x32_bf16 v[0:3], v[170:173], v[212:215], v[0:3]
	s_setprio 0
	s_barrier
	s_add_u32 s36, s36, 0x80000
	s_addc_u32 s37, s37, 0
	s_mov_b32 m0, s1
	s_nop 0
	global_load_lds_dwordx4 v138, s[36:37]
	v_mov_b32_e32 v128, v144
	s_mov_b32 m0, s69
	s_nop 0
	global_load_lds_dwordx4 v140, s[36:37]
	v_add_u32_e32 v146, s34, v144
	v_xad_u32 v136, v128, 64, s34
	ds_read_b128 v[128:131], v146
	ds_read_b128 v[146:149], v146 offset:2048
	ds_read_b128 v[150:153], v136
	ds_read_b128 v[154:157], v136 offset:2048
	v_mov_b32_e32 v136, v144
	s_add_i32 s36, 0, 0x1c000
	v_add_u32_e32 v162, s36, v144
	v_xad_u32 v136, v136, 64, s36
	ds_read_b128 v[158:161], v162
	ds_read_b128 v[162:165], v162 offset:2048
	ds_read_b128 v[166:169], v136
	ds_read_b128 v[170:173], v136 offset:2048
	v_mov_b32_e32 v136, v143
	s_nop 0
	v_xad_u32 v136, v136, 64, 0
	ds_read_b128 v[174:177], v137 offset:32768
	ds_read_b128 v[178:181], v137 offset:34816
	ds_read_b128 v[192:195], v136 offset:32768
	ds_read_b128 v[196:199], v136 offset:34816
	ds_read_b128 v[200:203], v137 offset:36864
	ds_read_b128 v[204:207], v137 offset:38912
	ds_read_b128 v[208:211], v136 offset:36864
	ds_read_b128 v[212:215], v136 offset:38912
	s_waitcnt vmcnt(8)
	s_waitcnt lgkmcnt(0)
	s_barrier
	s_setprio 1
	s_waitcnt lgkmcnt(0)
	v_mfma_f32_16x16x32_bf16 v[124:127], v[128:131], v[174:177], v[124:127]
	v_mfma_f32_16x16x32_bf16 v[120:123], v[146:149], v[174:177], v[120:123]
	v_mfma_f32_16x16x32_bf16 v[108:111], v[128:131], v[178:181], v[108:111]
	v_mfma_f32_16x16x32_bf16 v[104:107], v[146:149], v[178:181], v[104:107]
	v_mfma_f32_16x16x32_bf16 v[92:95], v[128:131], v[200:203], v[92:95]
	v_mfma_f32_16x16x32_bf16 v[88:91], v[146:149], v[200:203], v[88:91]
	v_mfma_f32_16x16x32_bf16 v[76:79], v[128:131], v[204:207], v[76:79]
	v_mfma_f32_16x16x32_bf16 v[72:75], v[146:149], v[204:207], v[72:75]
	v_mfma_f32_16x16x32_bf16 v[124:127], v[150:153], v[192:195], v[124:127]
	v_mfma_f32_16x16x32_bf16 v[120:123], v[154:157], v[192:195], v[120:123]
	v_mfma_f32_16x16x32_bf16 v[108:111], v[150:153], v[196:199], v[108:111]
	v_mfma_f32_16x16x32_bf16 v[104:107], v[154:157], v[196:199], v[104:107]
	v_mfma_f32_16x16x32_bf16 v[92:95], v[150:153], v[208:211], v[92:95]
	v_mfma_f32_16x16x32_bf16 v[88:91], v[154:157], v[208:211], v[88:91]
	v_mfma_f32_16x16x32_bf16 v[76:79], v[150:153], v[212:215], v[76:79]
	v_mfma_f32_16x16x32_bf16 v[72:75], v[154:157], v[212:215], v[72:75]
	s_setprio 0
	s_setprio 1
	v_mfma_f32_16x16x32_bf16 v[116:119], v[158:161], v[174:177], v[116:119]
	s_add_u32 s36, s30, 0x80
	s_addc_u32 s37, s31, 0
	v_mfma_f32_16x16x32_bf16 v[112:115], v[162:165], v[174:177], v[112:115]
	v_mfma_f32_16x16x32_bf16 v[100:103], v[158:161], v[178:181], v[100:103]
	v_mfma_f32_16x16x32_bf16 v[96:99], v[162:165], v[178:181], v[96:99]
	v_mfma_f32_16x16x32_bf16 v[84:87], v[158:161], v[200:203], v[84:87]
	v_mfma_f32_16x16x32_bf16 v[80:83], v[162:165], v[200:203], v[80:83]
	v_mfma_f32_16x16x32_bf16 v[68:71], v[158:161], v[204:207], v[68:71]
	v_mfma_f32_16x16x32_bf16 v[64:67], v[162:165], v[204:207], v[64:67]
	v_mfma_f32_16x16x32_bf16 v[116:119], v[166:169], v[192:195], v[116:119]
	v_mfma_f32_16x16x32_bf16 v[112:115], v[170:173], v[192:195], v[112:115]
	v_mfma_f32_16x16x32_bf16 v[100:103], v[166:169], v[196:199], v[100:103]
	v_mfma_f32_16x16x32_bf16 v[96:99], v[170:173], v[196:199], v[96:99]
	v_mfma_f32_16x16x32_bf16 v[84:87], v[166:169], v[208:211], v[84:87]
	v_mfma_f32_16x16x32_bf16 v[80:83], v[170:173], v[208:211], v[80:83]
	v_mfma_f32_16x16x32_bf16 v[68:71], v[166:169], v[212:215], v[68:71]
	v_mfma_f32_16x16x32_bf16 v[64:67], v[170:173], v[212:215], v[64:67]
	s_setprio 0
	s_barrier
; #define PG8_STAGE(bufoff, gbase, voff) do { _Pragma("unroll") for (int _i = 0; _i < 2; ++_i) \
;         dma16((const char*)(gbase), (voff)[_i], ldsb + (bufoff) + ldsw + _i * 8192); } while (0)
; #define PG8_LDA(dst, b, h) do { const int a1_ = opqv(aoff0) ^ 64; _Pragma("unroll") for (int m = 0; m < 4; ++m) { dst[m][0] = *(const LAS bf16x8*)(lds + PG8_SA(b, h) + aoff0 + m * 2048); dst[m][1] = *(const LAS bf16x8*)(lds + PG8_SA(b, h) + a1_ + m * 2048); } } while (0)
; #define PG8_MMA(ai, bj, At, Bt) do { __builtin_amdgcn_s_setprio(1); _Pragma("unroll") for (int m = 0; m < 4; ++m) _Pragma("unroll") for (int n = 0; n < 2; ++n) _Pragma("unroll") for (int k = 0; k < 2; ++k) \
;         acc[ai][bj][m][n] = __builtin_amdgcn_mfma_f32_16x16x32_bf16(Bt[n][k], At[m][k], acc[ai][bj][m][n], 0, 0, 0); __builtin_amdgcn_s_setprio(0); } while (0)
; #define PG8_WAIT_V(n) asm volatile("s_waitcnt vmcnt(" #n ")" ::: "memory")
; #define PG8_WAIT_L(n) asm volatile("s_waitcnt lgkmcnt(" #n ")" ::: "memory")
; #define PG8_BAR __builtin_amdgcn_s_barrier()
; #define PG8_SCHED __builtin_amdgcn_sched_barrier(0)
; template <class Epi>
; __device__ __forceinline__ void gemm_phase(LAS unsigned char* lds, const Gemm g, const StaticOrder& S, const Epi& E, int wave_) {
;     ...
;             PG8_STAGE(PG8_SB(1, 0), b3, voffB); PG8_STAGE(PG8_SB(1, 1), b3 + hstepB, voffB); PG8_STAGE(PG8_SA(1, 0), a3, voffA); PG8_LDA(At, 1, 1);
;             PG8_WAIT_V(8); PG8_WAIT_L(0); PG8_BAR; PG8_MMA(1, 0, At, B0); PG8_MMA(1, 1, At, B1); PG8_BAR; PG8_SCHED;
	s_add_u32 s30, s30, 0x80080
	s_addc_u32 s31, s31, 0
	v_mov_b32_e32 v136, v143
	s_nop 0
	s_nop 0
	v_xad_u32 v136, v136, 64, 0
	ds_read_b128 v[174:177], v137 offset:49152
	ds_read_b128 v[178:181], v137 offset:51200
	ds_read_b128 v[192:195], v136 offset:49152
	ds_read_b128 v[196:199], v136 offset:51200
	ds_read_b128 v[200:203], v137 offset:53248
	ds_read_b128 v[204:207], v137 offset:55296
	ds_read_b128 v[208:211], v136 offset:53248
	ds_read_b128 v[212:215], v136 offset:55296
	s_mov_b32 m0, s35
	s_nop 0
	global_load_lds_dwordx4 v139, s[36:37]
	s_mov_b32 m0, s33
	s_nop 0
	global_load_lds_dwordx4 v141, s[36:37]
	s_mov_b32 m0, s77
	s_nop 0
	global_load_lds_dwordx4 v139, s[30:31]
	s_mov_b32 m0, s3
	s_nop 0
	global_load_lds_dwordx4 v141, s[30:31]
	s_mov_b32 m0, s22
	s_nop 0
	global_load_lds_dwordx4 v138, s[26:27]
	s_mov_b32 m0, s2
	s_nop 0
	global_load_lds_dwordx4 v140, s[26:27]
	s_waitcnt vmcnt(8)
	s_waitcnt lgkmcnt(0)
	s_barrier
	s_setprio 1
	s_waitcnt lgkmcnt(0)
	v_mfma_f32_16x16x32_bf16 v[60:63], v[128:131], v[174:177], v[60:63]
	v_mfma_f32_16x16x32_bf16 v[56:59], v[146:149], v[174:177], v[56:59]
	v_mfma_f32_16x16x32_bf16 v[44:47], v[128:131], v[178:181], v[44:47]
	v_mfma_f32_16x16x32_bf16 v[40:43], v[146:149], v[178:181], v[40:43]
	v_mfma_f32_16x16x32_bf16 v[28:31], v[128:131], v[200:203], v[28:31]
	v_mfma_f32_16x16x32_bf16 v[24:27], v[146:149], v[200:203], v[24:27]
	v_mfma_f32_16x16x32_bf16 v[12:15], v[128:131], v[204:207], v[12:15]
	v_mfma_f32_16x16x32_bf16 v[8:11], v[146:149], v[204:207], v[8:11]
	v_mfma_f32_16x16x32_bf16 v[60:63], v[150:153], v[192:195], v[60:63]
	v_mfma_f32_16x16x32_bf16 v[56:59], v[154:157], v[192:195], v[56:59]
	v_mfma_f32_16x16x32_bf16 v[44:47], v[150:153], v[196:199], v[44:47]
	v_mfma_f32_16x16x32_bf16 v[40:43], v[154:157], v[196:199], v[40:43]
	v_mfma_f32_16x16x32_bf16 v[28:31], v[150:153], v[208:211], v[28:31]
	v_mfma_f32_16x16x32_bf16 v[24:27], v[154:157], v[208:211], v[24:27]
	v_mfma_f32_16x16x32_bf16 v[12:15], v[150:153], v[212:215], v[12:15]
	v_mfma_f32_16x16x32_bf16 v[8:11], v[154:157], v[212:215], v[8:11]
	s_setprio 0
	s_setprio 1
	v_mfma_f32_16x16x32_bf16 v[52:55], v[158:161], v[174:177], v[52:55]
	v_mfma_f32_16x16x32_bf16 v[48:51], v[162:165], v[174:177], v[48:51]
	v_mfma_f32_16x16x32_bf16 v[36:39], v[158:161], v[178:181], v[36:39]
	v_mfma_f32_16x16x32_bf16 v[32:35], v[162:165], v[178:181], v[32:35]
	v_mfma_f32_16x16x32_bf16 v[20:23], v[158:161], v[200:203], v[20:23]
	v_mfma_f32_16x16x32_bf16 v[16:19], v[162:165], v[200:203], v[16:19]
	v_mfma_f32_16x16x32_bf16 v[4:7], v[158:161], v[204:207], v[4:7]
	v_mfma_f32_16x16x32_bf16 v[0:3], v[162:165], v[204:207], v[0:3]
	v_mfma_f32_16x16x32_bf16 v[52:55], v[166:169], v[192:195], v[52:55]
	v_mfma_f32_16x16x32_bf16 v[48:51], v[170:173], v[192:195], v[48:51]
	v_mfma_f32_16x16x32_bf16 v[36:39], v[166:169], v[196:199], v[36:39]
	v_mfma_f32_16x16x32_bf16 v[32:35], v[170:173], v[196:199], v[32:35]
	v_mfma_f32_16x16x32_bf16 v[20:23], v[166:169], v[208:211], v[20:23]
	v_mfma_f32_16x16x32_bf16 v[16:19], v[170:173], v[208:211], v[16:19]
	v_mfma_f32_16x16x32_bf16 v[4:7], v[166:169], v[212:215], v[4:7]
	v_mfma_f32_16x16x32_bf16 v[0:3], v[170:173], v[212:215], v[0:3]
	s_setprio 0
	s_barrier
	s_add_i32 s57, s57, 2
	s_add_u32 s52, s52, 0x100
	s_addc_u32 s56, s56, 0
	s_add_u32 s12, s12, 0x100
	s_addc_u32 s13, s13, 0
	s_cmp_gt_u32 s57, 29
	s_cbranch_scc0 .LBB0_574
	s_branch .Lpeel_exit_7

; #define PG8_STAGE(bufoff, gbase, voff) do { _Pragma("unroll") for (int _i = 0; _i < 2; ++_i) \
;         dma16((const char*)(gbase), (voff)[_i], ldsb + (bufoff) + ldsw + _i * 8192); } while (0)
; #define PG8_LDA(dst, b, h) do { const int a1_ = opqv(aoff0) ^ 64; _Pragma("unroll") for (int m = 0; m < 4; ++m) { dst[m][0] = *(const LAS bf16x8*)(lds + PG8_SA(b, h) + aoff0 + m * 2048); dst[m][1] = *(const LAS bf16x8*)(lds + PG8_SA(b, h) + a1_ + m * 2048); } } while (0)
; #define PG8_LDB(dst, b, h) do { const int b1_ = opqv(boff0) ^ 64; _Pragma("unroll") for (int n = 0; n < 2; ++n) { dst[n][0] = *(const LAS bf16x8*)(lds + PG8_SB(b, h) + boff0 + n * 2048); dst[n][1] = *(const LAS bf16x8*)(lds + PG8_SB(b, h) + b1_ + n * 2048); } } while (0)
; #define PG8_MMA(ai, bj, At, Bt) do { __builtin_amdgcn_s_setprio(1); _Pragma("unroll") for (int m = 0; m < 4; ++m) _Pragma("unroll") for (int n = 0; n < 2; ++n) _Pragma("unroll") for (int k = 0; k < 2; ++k) \
;         acc[ai][bj][m][n] = __builtin_amdgcn_mfma_f32_16x16x32_bf16(Bt[n][k], At[m][k], acc[ai][bj][m][n], 0, 0, 0); __builtin_amdgcn_s_setprio(0); } while (0)
; #define PG8_WAIT_V(n) asm volatile("s_waitcnt vmcnt(" #n ")" ::: "memory")
; #define PG8_WAIT_L(n) asm volatile("s_waitcnt lgkmcnt(" #n ")" ::: "memory")
; template <class Epi>
; __device__ __forceinline__ void gemm_phase(LAS unsigned char* lds, const Gemm g, const StaticOrder& S, const Epi& E, int wave_) {
;     ...
;             const char* a1 = cA + (size_t)(t + 1) * kstep;
;             const char* a2 = last ? nA : cA + (size_t)(t + 2) * kstep; const char* b2 = last ? nB : cB + (size_t)(t + 2) * kstep;
;             const char* a3 = a2 + kstep; const char* b3 = b2 + kstep;
;             PG8_STAGE(PG8_SA(1, 1), a1 + hstepA, voffA); PG8_LDB(B0, 0, 0); PG8_LDB(B1, 0, 1); PG8_SCHED; PG8_LDA(At, 0, 0);
;             PG8_WAIT_V(8); PG8_WAIT_L(0); PG8_BAR; PG8_MMA(0, 0, At, B0); PG8_MMA(0, 1, At, B1); PG8_BAR; PG8_SCHED;
;             PG8_STAGE(PG8_SB(0, 0), b2, voffB); PG8_STAGE(PG8_SB(0, 1), b2 + hstepB, voffB); PG8_STAGE(PG8_SA(0, 0), a2, voffA); PG8_LDA(At, 0, 1);
;     ...
;         for (int a = 0; a < 2; ++a)
; #pragma unroll
;             for (int b = 0; b < 2; ++b)
; #pragma unroll
;                 for (int m = 0; m < 4; ++m)
; #pragma unroll
;                     for (int n = 0; n < 2; ++n) acc[a][b][m][n] = (f32x4){0.f, 0.f, 0.f, 0.f};
.LBB0_743:
	s_ashr_i32 s19, s18, 31
	s_lshl_b64 s[16:17], s[18:19], 19
	s_add_u32 s24, s21, s16
	s_addc_u32 s25, s46, s17
	s_and_b64 s[16:17], s[40:41], exec
	s_cselect_b32 s16, s25, s31
	s_cselect_b32 s17, s24, s30
	s_ashr_i32 s11, s10, 31
	s_lshl_b64 s[26:27], s[10:11], 18
	s_add_u32 s26, s47, s26
	s_addc_u32 s27, s48, s27
	s_and_b64 s[36:37], s[40:41], exec
	s_cselect_b32 s11, s27, s13
	s_cselect_b32 s19, s26, s12
	s_add_u32 s52, s12, 0x100
	s_addc_u32 s56, s13, 0
	s_add_u32 s12, s30, 0x40080
	s_addc_u32 s13, s31, 0
	s_mov_b32 s57, -2
	s_add_u32 s30, s12, 0xfffc0080
	s_addc_u32 s31, s13, -1
	s_cmp_eq_u32 s57, 4
	s_cselect_b32 s42, s17, s30
	s_cselect_b32 s43, s16, s31
	s_cselect_b32 s36, s19, s52
	s_cselect_b32 s37, s11, s56
	s_add_u32 s30, s42, 0x80
	v_mov_b32_e32 v128, v180
	s_addc_u32 s31, s43, 0
	v_add_u32_e32 v132, s23, v180
	v_xad_u32 v144, v128, 64, s23
	v_mov_b32_e32 v148, v180
	s_add_i32 s58, 0, 0x14000
	ds_read_b128 v[128:131], v132
	ds_read_b128 v[132:135], v132 offset:2048
	ds_read_b128 v[140:143], v144
	ds_read_b128 v[144:147], v144 offset:2048
	v_add_u32_e32 v152, s58, v180
	v_xad_u32 v160, v148, 64, s58
	ds_read_b128 v[148:151], v152
	ds_read_b128 v[152:155], v152 offset:2048
	ds_read_b128 v[156:159], v160
	ds_read_b128 v[160:163], v160 offset:2048
	v_mov_b32_e32 v164, v179
	v_add_u32_e32 v182, 0, v179
	v_xad_u32 v172, v164, 64, 0
	ds_read_b128 v[164:167], v182
	ds_read_b128 v[168:171], v182 offset:2048
	ds_read_b128 v[192:195], v172
	ds_read_b128 v[196:199], v172 offset:2048
	ds_read_b128 v[200:203], v182 offset:4096
	ds_read_b128 v[204:207], v182 offset:6144
	ds_read_b128 v[208:211], v172 offset:4096
	ds_read_b128 v[212:215], v172 offset:6144
	s_mov_b32 m0, s14
	s_nop 0
	global_load_lds_dwordx4 v137, s[12:13]
	s_mov_b32 m0, s15
	s_nop 0
	global_load_lds_dwordx4 v176, s[12:13]
	s_waitcnt vmcnt(8)
	s_waitcnt lgkmcnt(0)
	s_barrier
	s_setprio 1
	s_waitcnt lgkmcnt(0)
	v_mfma_f32_16x16x32_bf16 v[124:127], v[128:131], v[164:167], 0
	v_mfma_f32_16x16x32_bf16 v[120:123], v[132:135], v[164:167], 0
	v_mfma_f32_16x16x32_bf16 v[108:111], v[128:131], v[168:171], 0
	v_mfma_f32_16x16x32_bf16 v[104:107], v[132:135], v[168:171], 0
	v_mfma_f32_16x16x32_bf16 v[92:95], v[128:131], v[200:203], 0
	v_mfma_f32_16x16x32_bf16 v[88:91], v[132:135], v[200:203], 0
	v_mfma_f32_16x16x32_bf16 v[76:79], v[128:131], v[204:207], 0
	v_mfma_f32_16x16x32_bf16 v[72:75], v[132:135], v[204:207], 0
	v_mfma_f32_16x16x32_bf16 v[124:127], v[140:143], v[192:195], v[124:127]
	v_mfma_f32_16x16x32_bf16 v[120:123], v[144:147], v[192:195], v[120:123]
	v_mfma_f32_16x16x32_bf16 v[108:111], v[140:143], v[196:199], v[108:111]
	v_mfma_f32_16x16x32_bf16 v[104:107], v[144:147], v[196:199], v[104:107]
	v_mfma_f32_16x16x32_bf16 v[92:95], v[140:143], v[208:211], v[92:95]
	v_mfma_f32_16x16x32_bf16 v[88:91], v[144:147], v[208:211], v[88:91]
	v_mfma_f32_16x16x32_bf16 v[76:79], v[140:143], v[212:215], v[76:79]
	v_mfma_f32_16x16x32_bf16 v[72:75], v[144:147], v[212:215], v[72:75]
	s_setprio 0
	s_setprio 1
	v_mfma_f32_16x16x32_bf16 v[116:119], v[148:151], v[164:167], 0
	v_mfma_f32_16x16x32_bf16 v[112:115], v[152:155], v[164:167], 0
	v_mfma_f32_16x16x32_bf16 v[100:103], v[148:151], v[168:171], 0
	v_mfma_f32_16x16x32_bf16 v[96:99], v[152:155], v[168:171], 0
	v_mfma_f32_16x16x32_bf16 v[84:87], v[148:151], v[200:203], 0
	v_mfma_f32_16x16x32_bf16 v[80:83], v[152:155], v[200:203], 0
	v_mfma_f32_16x16x32_bf16 v[68:71], v[148:151], v[204:207], 0
	v_mfma_f32_16x16x32_bf16 v[64:67], v[152:155], v[204:207], 0
	v_mfma_f32_16x16x32_bf16 v[116:119], v[156:159], v[192:195], v[116:119]
	v_mfma_f32_16x16x32_bf16 v[112:115], v[160:163], v[192:195], v[112:115]
	v_mfma_f32_16x16x32_bf16 v[100:103], v[156:159], v[196:199], v[100:103]
	v_mfma_f32_16x16x32_bf16 v[96:99], v[160:163], v[196:199], v[96:99]
	v_mfma_f32_16x16x32_bf16 v[84:87], v[156:159], v[208:211], v[84:87]
	v_mfma_f32_16x16x32_bf16 v[80:83], v[160:163], v[208:211], v[80:83]
	v_mfma_f32_16x16x32_bf16 v[68:71], v[156:159], v[212:215], v[68:71]
	v_mfma_f32_16x16x32_bf16 v[64:67], v[160:163], v[212:215], v[64:67]
	s_setprio 0
	s_barrier
	v_mov_b32_e32 v164, v179
	s_add_u32 s58, s36, 0x20000
	s_addc_u32 s59, s37, 0
	s_nop 0
	s_nop 0
	s_nop 0
	v_xad_u32 v172, v164, 64, 0
	ds_read_b128 v[164:167], v182 offset:16384
	ds_read_b128 v[168:171], v182 offset:18432
	ds_read_b128 v[192:195], v172 offset:16384
	ds_read_b128 v[196:199], v172 offset:18432
	ds_read_b128 v[200:203], v182 offset:20480
	ds_read_b128 v[204:207], v182 offset:22528
	ds_read_b128 v[208:211], v172 offset:20480
	ds_read_b128 v[212:215], v172 offset:22528
	s_mov_b32 m0, s80
	s_nop 0
	global_load_lds_dwordx4 v175, s[36:37]
	s_mov_b32 m0, s81
	s_nop 0
	global_load_lds_dwordx4 v177, s[36:37]
	s_mov_b32 m0, s29
	s_nop 0
	global_load_lds_dwordx4 v175, s[58:59]
	s_mov_b32 m0, s88
	s_nop 0
	global_load_lds_dwordx4 v177, s[58:59]
	s_mov_b32 m0, s76
	s_nop 0
	global_load_lds_dwordx4 v137, s[42:43]
	s_mov_b32 m0, s89
	s_nop 0
	global_load_lds_dwordx4 v176, s[42:43]
	s_waitcnt vmcnt(8)
	s_waitcnt lgkmcnt(0)
	s_barrier
; #define PG8_STAGE(bufoff, gbase, voff) do { _Pragma("unroll") for (int _i = 0; _i < 2; ++_i) \
;         dma16((const char*)(gbase), (voff)[_i], ldsb + (bufoff) + ldsw + _i * 8192); } while (0)
; #define PG8_LDA(dst, b, h) do { const int a1_ = opqv(aoff0) ^ 64; _Pragma("unroll") for (int m = 0; m < 4; ++m) { dst[m][0] = *(const LAS bf16x8*)(lds + PG8_SA(b, h) + aoff0 + m * 2048); dst[m][1] = *(const LAS bf16x8*)(lds + PG8_SA(b, h) + a1_ + m * 2048); } } while (0)
; #define PG8_LDB(dst, b, h) do { const int b1_ = opqv(boff0) ^ 64; _Pragma("unroll") for (int n = 0; n < 2; ++n) { dst[n][0] = *(const LAS bf16x8*)(lds + PG8_SB(b, h) + boff0 + n * 2048); dst[n][1] = *(const LAS bf16x8*)(lds + PG8_SB(b, h) + b1_ + n * 2048); } } while (0)
; #define PG8_MMA(ai, bj, At, Bt) do { __builtin_amdgcn_s_setprio(1); _Pragma("unroll") for (int m = 0; m < 4; ++m) _Pragma("unroll") for (int n = 0; n < 2; ++n) _Pragma("unroll") for (int k = 0; k < 2; ++k) \
;         acc[ai][bj][m][n] = __builtin_amdgcn_mfma_f32_16x16x32_bf16(Bt[n][k], At[m][k], acc[ai][bj][m][n], 0, 0, 0); __builtin_amdgcn_s_setprio(0); } while (0)
; #define PG8_WAIT_V(n) asm volatile("s_waitcnt vmcnt(" #n ")" ::: "memory")
; #define PG8_WAIT_L(n) asm volatile("s_waitcnt lgkmcnt(" #n ")" ::: "memory")
; #define PG8_BAR __builtin_amdgcn_s_barrier()
; #define PG8_SCHED __builtin_amdgcn_sched_barrier(0)
; template <class Epi>
; __device__ __forceinline__ void gemm_phase(LAS unsigned char* lds, const Gemm g, const StaticOrder& S, const Epi& E, int wave_) {
;     ...
;             PG8_WAIT_V(8); PG8_WAIT_L(0); PG8_BAR; PG8_MMA(1, 0, At, B0); PG8_MMA(1, 1, At, B1); PG8_BAR; PG8_SCHED;
;             PG8_STAGE(PG8_SA(0, 1), a2 + hstepA, voffA); PG8_LDB(B0, 1, 0); PG8_LDB(B1, 1, 1); PG8_SCHED; PG8_LDA(At, 1, 0);
;             PG8_WAIT_V(8); PG8_WAIT_L(0); PG8_BAR; PG8_MMA(0, 0, At, B0); PG8_MMA(0, 1, At, B1); PG8_BAR; PG8_SCHED;
	s_setprio 1
	s_waitcnt lgkmcnt(0)
	v_mfma_f32_16x16x32_bf16 v[60:63], v[128:131], v[164:167], 0
	v_mfma_f32_16x16x32_bf16 v[56:59], v[132:135], v[164:167], 0
	v_mfma_f32_16x16x32_bf16 v[44:47], v[128:131], v[168:171], 0
	v_mfma_f32_16x16x32_bf16 v[40:43], v[132:135], v[168:171], 0
	v_mfma_f32_16x16x32_bf16 v[28:31], v[128:131], v[200:203], 0
	v_mfma_f32_16x16x32_bf16 v[24:27], v[132:135], v[200:203], 0
	v_mfma_f32_16x16x32_bf16 v[12:15], v[128:131], v[204:207], 0
	v_mfma_f32_16x16x32_bf16 v[8:11], v[132:135], v[204:207], 0
	v_mfma_f32_16x16x32_bf16 v[60:63], v[140:143], v[192:195], v[60:63]
	v_mfma_f32_16x16x32_bf16 v[56:59], v[144:147], v[192:195], v[56:59]
	v_mfma_f32_16x16x32_bf16 v[44:47], v[140:143], v[196:199], v[44:47]
	v_mfma_f32_16x16x32_bf16 v[40:43], v[144:147], v[196:199], v[40:43]
	v_mfma_f32_16x16x32_bf16 v[28:31], v[140:143], v[208:211], v[28:31]
	v_mfma_f32_16x16x32_bf16 v[24:27], v[144:147], v[208:211], v[24:27]
	v_mfma_f32_16x16x32_bf16 v[12:15], v[140:143], v[212:215], v[12:15]
	v_mfma_f32_16x16x32_bf16 v[8:11], v[144:147], v[212:215], v[8:11]
	s_setprio 0
	s_setprio 1
	v_mfma_f32_16x16x32_bf16 v[52:55], v[148:151], v[164:167], 0
	v_mfma_f32_16x16x32_bf16 v[48:51], v[152:155], v[164:167], 0
	v_mfma_f32_16x16x32_bf16 v[36:39], v[148:151], v[168:171], 0
	v_mfma_f32_16x16x32_bf16 v[32:35], v[152:155], v[168:171], 0
	v_mfma_f32_16x16x32_bf16 v[20:23], v[148:151], v[200:203], 0
	v_mfma_f32_16x16x32_bf16 v[16:19], v[152:155], v[200:203], 0
	v_mfma_f32_16x16x32_bf16 v[4:7], v[148:151], v[204:207], 0
	v_mfma_f32_16x16x32_bf16 v[0:3], v[152:155], v[204:207], 0
	v_mfma_f32_16x16x32_bf16 v[52:55], v[156:159], v[192:195], v[52:55]
	v_mfma_f32_16x16x32_bf16 v[48:51], v[160:163], v[192:195], v[48:51]
	v_mfma_f32_16x16x32_bf16 v[36:39], v[156:159], v[196:199], v[36:39]
	v_mfma_f32_16x16x32_bf16 v[32:35], v[160:163], v[196:199], v[32:35]
	v_mfma_f32_16x16x32_bf16 v[20:23], v[156:159], v[208:211], v[20:23]
	v_mfma_f32_16x16x32_bf16 v[16:19], v[160:163], v[208:211], v[16:19]
	v_mfma_f32_16x16x32_bf16 v[4:7], v[156:159], v[212:215], v[4:7]
	v_mfma_f32_16x16x32_bf16 v[0:3], v[160:163], v[212:215], v[0:3]
	s_setprio 0
	s_barrier
	s_add_u32 s42, s42, 0x40000
	s_addc_u32 s43, s43, 0
	s_mov_b32 m0, s1
	s_nop 0
	global_load_lds_dwordx4 v137, s[42:43]
	v_mov_b32_e32 v128, v180
	s_mov_b32 m0, s69
	s_nop 0
	global_load_lds_dwordx4 v176, s[42:43]
	v_add_u32_e32 v132, s34, v180
	v_xad_u32 v144, v128, 64, s34
	v_mov_b32_e32 v148, v180
	s_add_i32 s42, 0, 0x1c000
	ds_read_b128 v[128:131], v132
	ds_read_b128 v[132:135], v132 offset:2048
	ds_read_b128 v[140:143], v144
	ds_read_b128 v[144:147], v144 offset:2048
	v_add_u32_e32 v152, s42, v180
	v_xad_u32 v160, v148, 64, s42
	ds_read_b128 v[148:151], v152
	ds_read_b128 v[152:155], v152 offset:2048
	ds_read_b128 v[156:159], v160
	ds_read_b128 v[160:163], v160 offset:2048
	v_mov_b32_e32 v164, v179
	s_nop 0
	v_xad_u32 v172, v164, 64, 0
	ds_read_b128 v[164:167], v182 offset:32768
	ds_read_b128 v[168:171], v182 offset:34816
	ds_read_b128 v[192:195], v172 offset:32768
	ds_read_b128 v[196:199], v172 offset:34816
	ds_read_b128 v[200:203], v182 offset:36864
	ds_read_b128 v[204:207], v182 offset:38912
	ds_read_b128 v[208:211], v172 offset:36864
	ds_read_b128 v[212:215], v172 offset:38912
	s_waitcnt vmcnt(8)
	s_waitcnt lgkmcnt(0)
	s_barrier
	s_setprio 1
	s_waitcnt lgkmcnt(0)
	v_mfma_f32_16x16x32_bf16 v[124:127], v[128:131], v[164:167], v[124:127]
	v_mfma_f32_16x16x32_bf16 v[120:123], v[132:135], v[164:167], v[120:123]
	v_mfma_f32_16x16x32_bf16 v[108:111], v[128:131], v[168:171], v[108:111]
	v_mfma_f32_16x16x32_bf16 v[104:107], v[132:135], v[168:171], v[104:107]
	v_mfma_f32_16x16x32_bf16 v[92:95], v[128:131], v[200:203], v[92:95]
	v_mfma_f32_16x16x32_bf16 v[88:91], v[132:135], v[200:203], v[88:91]
	v_mfma_f32_16x16x32_bf16 v[76:79], v[128:131], v[204:207], v[76:79]
	v_mfma_f32_16x16x32_bf16 v[72:75], v[132:135], v[204:207], v[72:75]
	v_mfma_f32_16x16x32_bf16 v[124:127], v[140:143], v[192:195], v[124:127]
	v_mfma_f32_16x16x32_bf16 v[120:123], v[144:147], v[192:195], v[120:123]
	v_mfma_f32_16x16x32_bf16 v[108:111], v[140:143], v[196:199], v[108:111]
	v_mfma_f32_16x16x32_bf16 v[104:107], v[144:147], v[196:199], v[104:107]
	v_mfma_f32_16x16x32_bf16 v[92:95], v[140:143], v[208:211], v[92:95]
	v_mfma_f32_16x16x32_bf16 v[88:91], v[144:147], v[208:211], v[88:91]
	v_mfma_f32_16x16x32_bf16 v[76:79], v[140:143], v[212:215], v[76:79]
	v_mfma_f32_16x16x32_bf16 v[72:75], v[144:147], v[212:215], v[72:75]
	s_setprio 0
	s_setprio 1
	v_mfma_f32_16x16x32_bf16 v[116:119], v[148:151], v[164:167], v[116:119]
	s_add_u32 s42, s36, 0x80
	s_addc_u32 s43, s37, 0
	v_mfma_f32_16x16x32_bf16 v[112:115], v[152:155], v[164:167], v[112:115]
	v_mfma_f32_16x16x32_bf16 v[100:103], v[148:151], v[168:171], v[100:103]
	v_mfma_f32_16x16x32_bf16 v[96:99], v[152:155], v[168:171], v[96:99]
	v_mfma_f32_16x16x32_bf16 v[84:87], v[148:151], v[200:203], v[84:87]
	v_mfma_f32_16x16x32_bf16 v[80:83], v[152:155], v[200:203], v[80:83]
	v_mfma_f32_16x16x32_bf16 v[68:71], v[148:151], v[204:207], v[68:71]
	v_mfma_f32_16x16x32_bf16 v[64:67], v[152:155], v[204:207], v[64:67]
	v_mfma_f32_16x16x32_bf16 v[116:119], v[156:159], v[192:195], v[116:119]
	v_mfma_f32_16x16x32_bf16 v[112:115], v[160:163], v[192:195], v[112:115]
	v_mfma_f32_16x16x32_bf16 v[100:103], v[156:159], v[196:199], v[100:103]
	v_mfma_f32_16x16x32_bf16 v[96:99], v[160:163], v[196:199], v[96:99]
	v_mfma_f32_16x16x32_bf16 v[84:87], v[156:159], v[208:211], v[84:87]
	v_mfma_f32_16x16x32_bf16 v[80:83], v[160:163], v[208:211], v[80:83]
	v_mfma_f32_16x16x32_bf16 v[68:71], v[156:159], v[212:215], v[68:71]
	v_mfma_f32_16x16x32_bf16 v[64:67], v[160:163], v[212:215], v[64:67]
	s_setprio 0
	s_barrier
; #define PG8_STAGE(bufoff, gbase, voff) do { _Pragma("unroll") for (int _i = 0; _i < 2; ++_i) \
;         dma16((const char*)(gbase), (voff)[_i], ldsb + (bufoff) + ldsw + _i * 8192); } while (0)
; #define PG8_LDA(dst, b, h) do { const int a1_ = opqv(aoff0) ^ 64; _Pragma("unroll") for (int m = 0; m < 4; ++m) { dst[m][0] = *(const LAS bf16x8*)(lds + PG8_SA(b, h) + aoff0 + m * 2048); dst[m][1] = *(const LAS bf16x8*)(lds + PG8_SA(b, h) + a1_ + m * 2048); } } while (0)
; #define PG8_MMA(ai, bj, At, Bt) do { __builtin_amdgcn_s_setprio(1); _Pragma("unroll") for (int m = 0; m < 4; ++m) _Pragma("unroll") for (int n = 0; n < 2; ++n) _Pragma("unroll") for (int k = 0; k < 2; ++k) \
;         acc[ai][bj][m][n] = __builtin_amdgcn_mfma_f32_16x16x32_bf16(Bt[n][k], At[m][k], acc[ai][bj][m][n], 0, 0, 0); __builtin_amdgcn_s_setprio(0); } while (0)
; #define PG8_WAIT_V(n) asm volatile("s_waitcnt vmcnt(" #n ")" ::: "memory")
; #define PG8_WAIT_L(n) asm volatile("s_waitcnt lgkmcnt(" #n ")" ::: "memory")
; #define PG8_BAR __builtin_amdgcn_s_barrier()
; #define PG8_SCHED __builtin_amdgcn_sched_barrier(0)
; template <class Epi>
; __device__ __forceinline__ void gemm_phase(LAS unsigned char* lds, const Gemm g, const StaticOrder& S, const Epi& E, int wave_) {
;     ...
;             PG8_STAGE(PG8_SB(1, 0), b3, voffB); PG8_STAGE(PG8_SB(1, 1), b3 + hstepB, voffB); PG8_STAGE(PG8_SA(1, 0), a3, voffA); PG8_LDA(At, 1, 1);
;             PG8_WAIT_V(8); PG8_WAIT_L(0); PG8_BAR; PG8_MMA(1, 0, At, B0); PG8_MMA(1, 1, At, B1); PG8_BAR; PG8_SCHED;
	s_add_u32 s36, s36, 0x20080
	s_addc_u32 s37, s37, 0
	v_mov_b32_e32 v164, v179
	s_nop 0
	s_nop 0
	v_xad_u32 v172, v164, 64, 0
	ds_read_b128 v[164:167], v182 offset:49152
	ds_read_b128 v[168:171], v182 offset:51200
	ds_read_b128 v[192:195], v172 offset:49152
	ds_read_b128 v[196:199], v172 offset:51200
	ds_read_b128 v[200:203], v182 offset:53248
	ds_read_b128 v[204:207], v182 offset:55296
	ds_read_b128 v[208:211], v172 offset:53248
	ds_read_b128 v[212:215], v172 offset:55296
	s_mov_b32 m0, s35
	s_nop 0
	global_load_lds_dwordx4 v175, s[42:43]
	s_mov_b32 m0, s33
	s_nop 0
	global_load_lds_dwordx4 v177, s[42:43]
	s_mov_b32 m0, s77
	s_nop 0
	global_load_lds_dwordx4 v175, s[36:37]
	s_mov_b32 m0, s3
	s_nop 0
	global_load_lds_dwordx4 v177, s[36:37]
	s_mov_b32 m0, s22
	s_nop 0
	global_load_lds_dwordx4 v137, s[30:31]
	s_mov_b32 m0, s2
	s_nop 0
	global_load_lds_dwordx4 v176, s[30:31]
	s_waitcnt vmcnt(8)
	s_waitcnt lgkmcnt(0)
	s_barrier
	s_setprio 1
	s_waitcnt lgkmcnt(0)
	v_mfma_f32_16x16x32_bf16 v[60:63], v[128:131], v[164:167], v[60:63]
	v_mfma_f32_16x16x32_bf16 v[56:59], v[132:135], v[164:167], v[56:59]
	v_mfma_f32_16x16x32_bf16 v[44:47], v[128:131], v[168:171], v[44:47]
	v_mfma_f32_16x16x32_bf16 v[40:43], v[132:135], v[168:171], v[40:43]
	v_mfma_f32_16x16x32_bf16 v[28:31], v[128:131], v[200:203], v[28:31]
	v_mfma_f32_16x16x32_bf16 v[24:27], v[132:135], v[200:203], v[24:27]
	v_mfma_f32_16x16x32_bf16 v[12:15], v[128:131], v[204:207], v[12:15]
	v_mfma_f32_16x16x32_bf16 v[8:11], v[132:135], v[204:207], v[8:11]
	v_mfma_f32_16x16x32_bf16 v[60:63], v[140:143], v[192:195], v[60:63]
	v_mfma_f32_16x16x32_bf16 v[56:59], v[144:147], v[192:195], v[56:59]
	v_mfma_f32_16x16x32_bf16 v[44:47], v[140:143], v[196:199], v[44:47]
	v_mfma_f32_16x16x32_bf16 v[40:43], v[144:147], v[196:199], v[40:43]
	v_mfma_f32_16x16x32_bf16 v[28:31], v[140:143], v[208:211], v[28:31]
	v_mfma_f32_16x16x32_bf16 v[24:27], v[144:147], v[208:211], v[24:27]
	v_mfma_f32_16x16x32_bf16 v[12:15], v[140:143], v[212:215], v[12:15]
	v_mfma_f32_16x16x32_bf16 v[8:11], v[144:147], v[212:215], v[8:11]
	s_setprio 0
	s_setprio 1
	v_mfma_f32_16x16x32_bf16 v[52:55], v[148:151], v[164:167], v[52:55]
	v_mfma_f32_16x16x32_bf16 v[48:51], v[152:155], v[164:167], v[48:51]
	v_mfma_f32_16x16x32_bf16 v[36:39], v[148:151], v[168:171], v[36:39]
	v_mfma_f32_16x16x32_bf16 v[32:35], v[152:155], v[168:171], v[32:35]
	v_mfma_f32_16x16x32_bf16 v[20:23], v[148:151], v[200:203], v[20:23]
	v_mfma_f32_16x16x32_bf16 v[16:19], v[152:155], v[200:203], v[16:19]
	v_mfma_f32_16x16x32_bf16 v[4:7], v[148:151], v[204:207], v[4:7]
	v_mfma_f32_16x16x32_bf16 v[0:3], v[152:155], v[204:207], v[0:3]
	v_mfma_f32_16x16x32_bf16 v[52:55], v[156:159], v[192:195], v[52:55]
	v_mfma_f32_16x16x32_bf16 v[48:51], v[160:163], v[192:195], v[48:51]
	v_mfma_f32_16x16x32_bf16 v[36:39], v[156:159], v[196:199], v[36:39]
	v_mfma_f32_16x16x32_bf16 v[32:35], v[160:163], v[196:199], v[32:35]
	v_mfma_f32_16x16x32_bf16 v[20:23], v[156:159], v[208:211], v[20:23]
	v_mfma_f32_16x16x32_bf16 v[16:19], v[160:163], v[208:211], v[16:19]
	v_mfma_f32_16x16x32_bf16 v[4:7], v[156:159], v[212:215], v[4:7]
	v_mfma_f32_16x16x32_bf16 v[0:3], v[160:163], v[212:215], v[0:3]
	s_setprio 0
	s_barrier
	s_add_i32 s57, s57, 2
	s_add_u32 s52, s52, 0x100
	s_addc_u32 s56, s56, 0
	s_add_u32 s12, s12, 0x100
	s_addc_u32 s13, s13, 0
	s_cmp_gt_u32 s57, 5
	s_cbranch_scc0 .LBB0_744
	s_branch .Lpeel_exit_6

; #define PG8_STAGE(bufoff, gbase, voff) do { _Pragma("unroll") for (int _i = 0; _i < 2; ++_i) \
;         dma16((const char*)(gbase), (voff)[_i], ldsb + (bufoff) + ldsw + _i * 8192); } while (0)
; #define PG8_LDA(dst, b, h) do { const int a1_ = opqv(aoff0) ^ 64; _Pragma("unroll") for (int m = 0; m < 4; ++m) { dst[m][0] = *(const LAS bf16x8*)(lds + PG8_SA(b, h) + aoff0 + m * 2048); dst[m][1] = *(const LAS bf16x8*)(lds + PG8_SA(b, h) + a1_ + m * 2048); } } while (0)
; #define PG8_LDB(dst, b, h) do { const int b1_ = opqv(boff0) ^ 64; _Pragma("unroll") for (int n = 0; n < 2; ++n) { dst[n][0] = *(const LAS bf16x8*)(lds + PG8_SB(b, h) + boff0 + n * 2048); dst[n][1] = *(const LAS bf16x8*)(lds + PG8_SB(b, h) + b1_ + n * 2048); } } while (0)
; #define PG8_MMA(ai, bj, At, Bt) do { __builtin_amdgcn_s_setprio(1); _Pragma("unroll") for (int m = 0; m < 4; ++m) _Pragma("unroll") for (int n = 0; n < 2; ++n) _Pragma("unroll") for (int k = 0; k < 2; ++k) \
;         acc[ai][bj][m][n] = __builtin_amdgcn_mfma_f32_16x16x32_bf16(Bt[n][k], At[m][k], acc[ai][bj][m][n], 0, 0, 0); __builtin_amdgcn_s_setprio(0); } while (0)
; #define PG8_WAIT_V(n) asm volatile("s_waitcnt vmcnt(" #n ")" ::: "memory")
; #define PG8_WAIT_L(n) asm volatile("s_waitcnt lgkmcnt(" #n ")" ::: "memory")
; template <class Epi>
; __device__ __forceinline__ void gemm_phase(LAS unsigned char* lds, const Gemm g, const StaticOrder& S, const Epi& E, int wave_) {
;     ...
;             const char* a1 = cA + (size_t)(t + 1) * kstep;
;             const char* a2 = last ? nA : cA + (size_t)(t + 2) * kstep; const char* b2 = last ? nB : cB + (size_t)(t + 2) * kstep;
;             const char* a3 = a2 + kstep; const char* b3 = b2 + kstep;
;             PG8_STAGE(PG8_SA(1, 1), a1 + hstepA, voffA); PG8_LDB(B0, 0, 0); PG8_LDB(B1, 0, 1); PG8_SCHED; PG8_LDA(At, 0, 0);
;             PG8_WAIT_V(8); PG8_WAIT_L(0); PG8_BAR; PG8_MMA(0, 0, At, B0); PG8_MMA(0, 1, At, B1); PG8_BAR; PG8_SCHED;
;             PG8_STAGE(PG8_SB(0, 0), b2, voffB); PG8_STAGE(PG8_SB(0, 1), b2 + hstepB, voffB); PG8_STAGE(PG8_SA(0, 0), a2, voffA); PG8_LDA(At, 0, 1);
;     ...
;         for (int a = 0; a < 2; ++a)
; #pragma unroll
;             for (int b = 0; b < 2; ++b)
; #pragma unroll
;                 for (int m = 0; m < 4; ++m)
; #pragma unroll
;                     for (int n = 0; n < 2; ++n) acc[a][b][m][n] = (f32x4){0.f, 0.f, 0.f, 0.f};
.LBB0_795:
	s_ashr_i32 s19, s18, 31
	s_lshl_b64 s[16:17], s[18:19], 19
	s_add_u32 s24, s21, s16
	s_addc_u32 s25, s44, s17
	s_and_b64 s[16:17], s[40:41], exec
	s_cselect_b32 s16, s25, s31
	s_cselect_b32 s17, s24, s30
	s_ashr_i32 s11, s10, 31
	s_lshl_b64 s[26:27], s[10:11], 18
	s_add_u32 s26, s45, s26
	s_addc_u32 s27, s46, s27
	s_and_b64 s[36:37], s[40:41], exec
	s_cselect_b32 s11, s27, s13
	s_cselect_b32 s19, s26, s12
	s_add_u32 s52, s12, 0x100
	s_addc_u32 s54, s13, 0
	s_add_u32 s12, s30, 0x40080
	s_addc_u32 s13, s31, 0
	s_mov_b32 s55, -2
	s_add_u32 s30, s12, 0xfffc0080
	s_addc_u32 s31, s13, -1
	s_cmp_eq_u32 s55, 4
	s_cselect_b32 s42, s17, s30
	s_cselect_b32 s43, s16, s31
	s_cselect_b32 s36, s19, s52
	s_cselect_b32 s37, s11, s54
	s_add_u32 s30, s42, 0x80
	v_mov_b32_e32 v130, v161
	s_addc_u32 s31, s43, 0
	v_add_u32_e32 v134, s23, v161
	v_xad_u32 v142, v130, 64, s23
	v_mov_b32_e32 v146, v161
	s_add_i32 s56, 0, 0x14000
	ds_read_b128 v[130:133], v134
	ds_read_b128 v[134:137], v134 offset:2048
	ds_read_b128 v[138:141], v142
	ds_read_b128 v[142:145], v142 offset:2048
	v_add_u32_e32 v150, s56, v161
	v_xad_u32 v154, v146, 64, s56
	ds_read_b128 v[146:149], v150
	ds_read_b128 v[150:153], v150 offset:2048
	ds_read_b128 v[162:165], v154
	ds_read_b128 v[166:169], v154 offset:2048
	v_mov_b32_e32 v154, v160
	v_add_u32_e32 v155, 0, v160
	v_xad_u32 v154, v154, 64, 0
	ds_read_b128 v[176:179], v155
	ds_read_b128 v[180:183], v155 offset:2048
	ds_read_b128 v[192:195], v154
	ds_read_b128 v[196:199], v154 offset:2048
	ds_read_b128 v[200:203], v155 offset:4096
	ds_read_b128 v[204:207], v155 offset:6144
	ds_read_b128 v[208:211], v154 offset:4096
	ds_read_b128 v[212:215], v154 offset:6144
	s_mov_b32 m0, s14
	s_nop 0
	global_load_lds_dwordx4 v129, s[12:13]
	s_mov_b32 m0, s15
	s_nop 0
	global_load_lds_dwordx4 v157, s[12:13]
	s_waitcnt vmcnt(8)
	s_waitcnt lgkmcnt(0)
	s_barrier
	s_setprio 1
	s_waitcnt lgkmcnt(0)
	v_mfma_f32_16x16x32_bf16 v[124:127], v[130:133], v[176:179], 0
	v_mfma_f32_16x16x32_bf16 v[120:123], v[134:137], v[176:179], 0
	v_mfma_f32_16x16x32_bf16 v[108:111], v[130:133], v[180:183], 0
	v_mfma_f32_16x16x32_bf16 v[104:107], v[134:137], v[180:183], 0
	v_mfma_f32_16x16x32_bf16 v[92:95], v[130:133], v[200:203], 0
	v_mfma_f32_16x16x32_bf16 v[88:91], v[134:137], v[200:203], 0
	v_mfma_f32_16x16x32_bf16 v[76:79], v[130:133], v[204:207], 0
	v_mfma_f32_16x16x32_bf16 v[72:75], v[134:137], v[204:207], 0
	v_mfma_f32_16x16x32_bf16 v[124:127], v[138:141], v[192:195], v[124:127]
	v_mfma_f32_16x16x32_bf16 v[120:123], v[142:145], v[192:195], v[120:123]
	v_mfma_f32_16x16x32_bf16 v[108:111], v[138:141], v[196:199], v[108:111]
	v_mfma_f32_16x16x32_bf16 v[104:107], v[142:145], v[196:199], v[104:107]
	v_mfma_f32_16x16x32_bf16 v[92:95], v[138:141], v[208:211], v[92:95]
	v_mfma_f32_16x16x32_bf16 v[88:91], v[142:145], v[208:211], v[88:91]
	v_mfma_f32_16x16x32_bf16 v[76:79], v[138:141], v[212:215], v[76:79]
	v_mfma_f32_16x16x32_bf16 v[72:75], v[142:145], v[212:215], v[72:75]
	s_setprio 0
	s_setprio 1
	v_mfma_f32_16x16x32_bf16 v[116:119], v[146:149], v[176:179], 0
	v_mfma_f32_16x16x32_bf16 v[112:115], v[150:153], v[176:179], 0
	v_mfma_f32_16x16x32_bf16 v[100:103], v[146:149], v[180:183], 0
	v_mfma_f32_16x16x32_bf16 v[96:99], v[150:153], v[180:183], 0
	v_mfma_f32_16x16x32_bf16 v[84:87], v[146:149], v[200:203], 0
	v_mfma_f32_16x16x32_bf16 v[80:83], v[150:153], v[200:203], 0
	v_mfma_f32_16x16x32_bf16 v[68:71], v[146:149], v[204:207], 0
	v_mfma_f32_16x16x32_bf16 v[64:67], v[150:153], v[204:207], 0
	v_mfma_f32_16x16x32_bf16 v[116:119], v[162:165], v[192:195], v[116:119]
	v_mfma_f32_16x16x32_bf16 v[112:115], v[166:169], v[192:195], v[112:115]
	v_mfma_f32_16x16x32_bf16 v[100:103], v[162:165], v[196:199], v[100:103]
	v_mfma_f32_16x16x32_bf16 v[96:99], v[166:169], v[196:199], v[96:99]
	v_mfma_f32_16x16x32_bf16 v[84:87], v[162:165], v[208:211], v[84:87]
	v_mfma_f32_16x16x32_bf16 v[80:83], v[166:169], v[208:211], v[80:83]
	v_mfma_f32_16x16x32_bf16 v[68:71], v[162:165], v[212:215], v[68:71]
	v_mfma_f32_16x16x32_bf16 v[64:67], v[166:169], v[212:215], v[64:67]
	s_setprio 0
	s_barrier
	v_mov_b32_e32 v154, v160
	s_add_u32 s56, s36, 0x20000
	s_addc_u32 s57, s37, 0
	s_nop 0
	s_nop 0
	s_nop 0
	v_xad_u32 v154, v154, 64, 0
	ds_read_b128 v[176:179], v155 offset:16384
	ds_read_b128 v[180:183], v155 offset:18432
	ds_read_b128 v[192:195], v154 offset:16384
	ds_read_b128 v[196:199], v154 offset:18432
	ds_read_b128 v[200:203], v155 offset:20480
	ds_read_b128 v[204:207], v155 offset:22528
	ds_read_b128 v[208:211], v154 offset:20480
	ds_read_b128 v[212:215], v154 offset:22528
	s_mov_b32 m0, s80
	s_nop 0
	global_load_lds_dwordx4 v156, s[36:37]
	s_mov_b32 m0, s81
	s_nop 0
	global_load_lds_dwordx4 v158, s[36:37]
	s_mov_b32 m0, s29
	s_nop 0
	global_load_lds_dwordx4 v156, s[56:57]
	s_mov_b32 m0, s88
	s_nop 0
	global_load_lds_dwordx4 v158, s[56:57]
	s_mov_b32 m0, s76
	s_nop 0
	global_load_lds_dwordx4 v129, s[42:43]
	s_mov_b32 m0, s89
	s_nop 0
	global_load_lds_dwordx4 v157, s[42:43]
	s_waitcnt vmcnt(8)
	s_waitcnt lgkmcnt(0)
	s_barrier
; #define PG8_STAGE(bufoff, gbase, voff) do { _Pragma("unroll") for (int _i = 0; _i < 2; ++_i) \
;         dma16((const char*)(gbase), (voff)[_i], ldsb + (bufoff) + ldsw + _i * 8192); } while (0)
; #define PG8_LDA(dst, b, h) do { const int a1_ = opqv(aoff0) ^ 64; _Pragma("unroll") for (int m = 0; m < 4; ++m) { dst[m][0] = *(const LAS bf16x8*)(lds + PG8_SA(b, h) + aoff0 + m * 2048); dst[m][1] = *(const LAS bf16x8*)(lds + PG8_SA(b, h) + a1_ + m * 2048); } } while (0)
; #define PG8_LDB(dst, b, h) do { const int b1_ = opqv(boff0) ^ 64; _Pragma("unroll") for (int n = 0; n < 2; ++n) { dst[n][0] = *(const LAS bf16x8*)(lds + PG8_SB(b, h) + boff0 + n * 2048); dst[n][1] = *(const LAS bf16x8*)(lds + PG8_SB(b, h) + b1_ + n * 2048); } } while (0)
; #define PG8_MMA(ai, bj, At, Bt) do { __builtin_amdgcn_s_setprio(1); _Pragma("unroll") for (int m = 0; m < 4; ++m) _Pragma("unroll") for (int n = 0; n < 2; ++n) _Pragma("unroll") for (int k = 0; k < 2; ++k) \
;         acc[ai][bj][m][n] = __builtin_amdgcn_mfma_f32_16x16x32_bf16(Bt[n][k], At[m][k], acc[ai][bj][m][n], 0, 0, 0); __builtin_amdgcn_s_setprio(0); } while (0)
; #define PG8_WAIT_V(n) asm volatile("s_waitcnt vmcnt(" #n ")" ::: "memory")
; #define PG8_WAIT_L(n) asm volatile("s_waitcnt lgkmcnt(" #n ")" ::: "memory")
; #define PG8_BAR __builtin_amdgcn_s_barrier()
; #define PG8_SCHED __builtin_amdgcn_sched_barrier(0)
; template <class Epi>
; __device__ __forceinline__ void gemm_phase(LAS unsigned char* lds, const Gemm g, const StaticOrder& S, const Epi& E, int wave_) {
;     ...
;             PG8_WAIT_V(8); PG8_WAIT_L(0); PG8_BAR; PG8_MMA(1, 0, At, B0); PG8_MMA(1, 1, At, B1); PG8_BAR; PG8_SCHED;
;             PG8_STAGE(PG8_SA(0, 1), a2 + hstepA, voffA); PG8_LDB(B0, 1, 0); PG8_LDB(B1, 1, 1); PG8_SCHED; PG8_LDA(At, 1, 0);
;             PG8_WAIT_V(8); PG8_WAIT_L(0); PG8_BAR; PG8_MMA(0, 0, At, B0); PG8_MMA(0, 1, At, B1); PG8_BAR; PG8_SCHED;
	s_setprio 1
	s_waitcnt lgkmcnt(0)
	v_mfma_f32_16x16x32_bf16 v[60:63], v[130:133], v[176:179], 0
	v_mfma_f32_16x16x32_bf16 v[56:59], v[134:137], v[176:179], 0
	v_mfma_f32_16x16x32_bf16 v[44:47], v[130:133], v[180:183], 0
	v_mfma_f32_16x16x32_bf16 v[40:43], v[134:137], v[180:183], 0
	v_mfma_f32_16x16x32_bf16 v[28:31], v[130:133], v[200:203], 0
	v_mfma_f32_16x16x32_bf16 v[24:27], v[134:137], v[200:203], 0
	v_mfma_f32_16x16x32_bf16 v[12:15], v[130:133], v[204:207], 0
	v_mfma_f32_16x16x32_bf16 v[8:11], v[134:137], v[204:207], 0
	v_mfma_f32_16x16x32_bf16 v[60:63], v[138:141], v[192:195], v[60:63]
	v_mfma_f32_16x16x32_bf16 v[56:59], v[142:145], v[192:195], v[56:59]
	v_mfma_f32_16x16x32_bf16 v[44:47], v[138:141], v[196:199], v[44:47]
	v_mfma_f32_16x16x32_bf16 v[40:43], v[142:145], v[196:199], v[40:43]
	v_mfma_f32_16x16x32_bf16 v[28:31], v[138:141], v[208:211], v[28:31]
	v_mfma_f32_16x16x32_bf16 v[24:27], v[142:145], v[208:211], v[24:27]
	v_mfma_f32_16x16x32_bf16 v[12:15], v[138:141], v[212:215], v[12:15]
	v_mfma_f32_16x16x32_bf16 v[8:11], v[142:145], v[212:215], v[8:11]
	s_setprio 0
	s_setprio 1
	v_mfma_f32_16x16x32_bf16 v[52:55], v[146:149], v[176:179], 0
	v_mfma_f32_16x16x32_bf16 v[48:51], v[150:153], v[176:179], 0
	v_mfma_f32_16x16x32_bf16 v[36:39], v[146:149], v[180:183], 0
	v_mfma_f32_16x16x32_bf16 v[32:35], v[150:153], v[180:183], 0
	v_mfma_f32_16x16x32_bf16 v[20:23], v[146:149], v[200:203], 0
	v_mfma_f32_16x16x32_bf16 v[16:19], v[150:153], v[200:203], 0
	v_mfma_f32_16x16x32_bf16 v[4:7], v[146:149], v[204:207], 0
	v_mfma_f32_16x16x32_bf16 v[0:3], v[150:153], v[204:207], 0
	v_mfma_f32_16x16x32_bf16 v[52:55], v[162:165], v[192:195], v[52:55]
	v_mfma_f32_16x16x32_bf16 v[48:51], v[166:169], v[192:195], v[48:51]
	v_mfma_f32_16x16x32_bf16 v[36:39], v[162:165], v[196:199], v[36:39]
	v_mfma_f32_16x16x32_bf16 v[32:35], v[166:169], v[196:199], v[32:35]
	v_mfma_f32_16x16x32_bf16 v[20:23], v[162:165], v[208:211], v[20:23]
	v_mfma_f32_16x16x32_bf16 v[16:19], v[166:169], v[208:211], v[16:19]
	v_mfma_f32_16x16x32_bf16 v[4:7], v[162:165], v[212:215], v[4:7]
	v_mfma_f32_16x16x32_bf16 v[0:3], v[166:169], v[212:215], v[0:3]
	s_setprio 0
	s_barrier
	s_add_u32 s42, s42, 0x40000
	s_addc_u32 s43, s43, 0
	s_mov_b32 m0, s1
	s_nop 0
	global_load_lds_dwordx4 v129, s[42:43]
	v_mov_b32_e32 v130, v161
	s_mov_b32 m0, s69
	s_nop 0
	global_load_lds_dwordx4 v157, s[42:43]
	v_add_u32_e32 v134, s34, v161
	v_xad_u32 v142, v130, 64, s34
	v_mov_b32_e32 v146, v161
	s_add_i32 s42, 0, 0x1c000
	ds_read_b128 v[130:133], v134
	ds_read_b128 v[134:137], v134 offset:2048
	ds_read_b128 v[138:141], v142
	ds_read_b128 v[142:145], v142 offset:2048
	v_add_u32_e32 v150, s42, v161
	v_xad_u32 v154, v146, 64, s42
	ds_read_b128 v[146:149], v150
	ds_read_b128 v[150:153], v150 offset:2048
	ds_read_b128 v[162:165], v154
	ds_read_b128 v[166:169], v154 offset:2048
	v_mov_b32_e32 v154, v160
	s_nop 0
	v_xad_u32 v154, v154, 64, 0
	ds_read_b128 v[176:179], v155 offset:32768
	ds_read_b128 v[180:183], v155 offset:34816
	ds_read_b128 v[192:195], v154 offset:32768
	ds_read_b128 v[196:199], v154 offset:34816
	ds_read_b128 v[200:203], v155 offset:36864
	ds_read_b128 v[204:207], v155 offset:38912
	ds_read_b128 v[208:211], v154 offset:36864
	ds_read_b128 v[212:215], v154 offset:38912
	s_waitcnt vmcnt(8)
	s_waitcnt lgkmcnt(0)
	s_barrier
	s_setprio 1
	s_waitcnt lgkmcnt(0)
	v_mfma_f32_16x16x32_bf16 v[124:127], v[130:133], v[176:179], v[124:127]
	v_mfma_f32_16x16x32_bf16 v[120:123], v[134:137], v[176:179], v[120:123]
	v_mfma_f32_16x16x32_bf16 v[108:111], v[130:133], v[180:183], v[108:111]
	v_mfma_f32_16x16x32_bf16 v[104:107], v[134:137], v[180:183], v[104:107]
	v_mfma_f32_16x16x32_bf16 v[92:95], v[130:133], v[200:203], v[92:95]
	v_mfma_f32_16x16x32_bf16 v[88:91], v[134:137], v[200:203], v[88:91]
	v_mfma_f32_16x16x32_bf16 v[76:79], v[130:133], v[204:207], v[76:79]
	v_mfma_f32_16x16x32_bf16 v[72:75], v[134:137], v[204:207], v[72:75]
	v_mfma_f32_16x16x32_bf16 v[124:127], v[138:141], v[192:195], v[124:127]
	v_mfma_f32_16x16x32_bf16 v[120:123], v[142:145], v[192:195], v[120:123]
	v_mfma_f32_16x16x32_bf16 v[108:111], v[138:141], v[196:199], v[108:111]
	v_mfma_f32_16x16x32_bf16 v[104:107], v[142:145], v[196:199], v[104:107]
	v_mfma_f32_16x16x32_bf16 v[92:95], v[138:141], v[208:211], v[92:95]
	v_mfma_f32_16x16x32_bf16 v[88:91], v[142:145], v[208:211], v[88:91]
	v_mfma_f32_16x16x32_bf16 v[76:79], v[138:141], v[212:215], v[76:79]
	v_mfma_f32_16x16x32_bf16 v[72:75], v[142:145], v[212:215], v[72:75]
	s_setprio 0
	s_setprio 1
	v_mfma_f32_16x16x32_bf16 v[116:119], v[146:149], v[176:179], v[116:119]
	s_add_u32 s42, s36, 0x80
	s_addc_u32 s43, s37, 0
	v_mfma_f32_16x16x32_bf16 v[112:115], v[150:153], v[176:179], v[112:115]
	v_mfma_f32_16x16x32_bf16 v[100:103], v[146:149], v[180:183], v[100:103]
	v_mfma_f32_16x16x32_bf16 v[96:99], v[150:153], v[180:183], v[96:99]
	v_mfma_f32_16x16x32_bf16 v[84:87], v[146:149], v[200:203], v[84:87]
	v_mfma_f32_16x16x32_bf16 v[80:83], v[150:153], v[200:203], v[80:83]
	v_mfma_f32_16x16x32_bf16 v[68:71], v[146:149], v[204:207], v[68:71]
	v_mfma_f32_16x16x32_bf16 v[64:67], v[150:153], v[204:207], v[64:67]
	v_mfma_f32_16x16x32_bf16 v[116:119], v[162:165], v[192:195], v[116:119]
	v_mfma_f32_16x16x32_bf16 v[112:115], v[166:169], v[192:195], v[112:115]
	v_mfma_f32_16x16x32_bf16 v[100:103], v[162:165], v[196:199], v[100:103]
	v_mfma_f32_16x16x32_bf16 v[96:99], v[166:169], v[196:199], v[96:99]
	v_mfma_f32_16x16x32_bf16 v[84:87], v[162:165], v[208:211], v[84:87]
	v_mfma_f32_16x16x32_bf16 v[80:83], v[166:169], v[208:211], v[80:83]
	v_mfma_f32_16x16x32_bf16 v[68:71], v[162:165], v[212:215], v[68:71]
	v_mfma_f32_16x16x32_bf16 v[64:67], v[166:169], v[212:215], v[64:67]
	s_setprio 0
	s_barrier
; #define PG8_STAGE(bufoff, gbase, voff) do { _Pragma("unroll") for (int _i = 0; _i < 2; ++_i) \
;         dma16((const char*)(gbase), (voff)[_i], ldsb + (bufoff) + ldsw + _i * 8192); } while (0)
; #define PG8_LDA(dst, b, h) do { const int a1_ = opqv(aoff0) ^ 64; _Pragma("unroll") for (int m = 0; m < 4; ++m) { dst[m][0] = *(const LAS bf16x8*)(lds + PG8_SA(b, h) + aoff0 + m * 2048); dst[m][1] = *(const LAS bf16x8*)(lds + PG8_SA(b, h) + a1_ + m * 2048); } } while (0)
; #define PG8_MMA(ai, bj, At, Bt) do { __builtin_amdgcn_s_setprio(1); _Pragma("unroll") for (int m = 0; m < 4; ++m) _Pragma("unroll") for (int n = 0; n < 2; ++n) _Pragma("unroll") for (int k = 0; k < 2; ++k) \
;         acc[ai][bj][m][n] = __builtin_amdgcn_mfma_f32_16x16x32_bf16(Bt[n][k], At[m][k], acc[ai][bj][m][n], 0, 0, 0); __builtin_amdgcn_s_setprio(0); } while (0)
; #define PG8_WAIT_V(n) asm volatile("s_waitcnt vmcnt(" #n ")" ::: "memory")
; #define PG8_WAIT_L(n) asm volatile("s_waitcnt lgkmcnt(" #n ")" ::: "memory")
; #define PG8_BAR __builtin_amdgcn_s_barrier()
; #define PG8_SCHED __builtin_amdgcn_sched_barrier(0)
; template <class Epi>
; __device__ __forceinline__ void gemm_phase(LAS unsigned char* lds, const Gemm g, const StaticOrder& S, const Epi& E, int wave_) {
;     ...
;             PG8_STAGE(PG8_SB(1, 0), b3, voffB); PG8_STAGE(PG8_SB(1, 1), b3 + hstepB, voffB); PG8_STAGE(PG8_SA(1, 0), a3, voffA); PG8_LDA(At, 1, 1);
;             PG8_WAIT_V(8); PG8_WAIT_L(0); PG8_BAR; PG8_MMA(1, 0, At, B0); PG8_MMA(1, 1, At, B1); PG8_BAR; PG8_SCHED;
	s_add_u32 s36, s36, 0x20080
	s_addc_u32 s37, s37, 0
	v_mov_b32_e32 v154, v160
	s_nop 0
	s_nop 0
	v_xad_u32 v154, v154, 64, 0
	ds_read_b128 v[176:179], v155 offset:49152
	ds_read_b128 v[180:183], v155 offset:51200
	ds_read_b128 v[192:195], v154 offset:49152
	ds_read_b128 v[196:199], v154 offset:51200
	ds_read_b128 v[200:203], v155 offset:53248
	ds_read_b128 v[204:207], v155 offset:55296
	ds_read_b128 v[208:211], v154 offset:53248
	ds_read_b128 v[212:215], v154 offset:55296
	s_mov_b32 m0, s35
	s_nop 0
	global_load_lds_dwordx4 v156, s[42:43]
	s_mov_b32 m0, s33
	s_nop 0
	global_load_lds_dwordx4 v158, s[42:43]
	s_mov_b32 m0, s77
	s_nop 0
	global_load_lds_dwordx4 v156, s[36:37]
	s_mov_b32 m0, s3
	s_nop 0
	global_load_lds_dwordx4 v158, s[36:37]
	s_mov_b32 m0, s22
	s_nop 0
	global_load_lds_dwordx4 v129, s[30:31]
	s_mov_b32 m0, s2
	s_nop 0
	global_load_lds_dwordx4 v157, s[30:31]
	s_waitcnt vmcnt(8)
	s_waitcnt lgkmcnt(0)
	s_barrier
	s_setprio 1
	s_waitcnt lgkmcnt(0)
	v_mfma_f32_16x16x32_bf16 v[60:63], v[130:133], v[176:179], v[60:63]
	v_mfma_f32_16x16x32_bf16 v[56:59], v[134:137], v[176:179], v[56:59]
	v_mfma_f32_16x16x32_bf16 v[44:47], v[130:133], v[180:183], v[44:47]
	v_mfma_f32_16x16x32_bf16 v[40:43], v[134:137], v[180:183], v[40:43]
	v_mfma_f32_16x16x32_bf16 v[28:31], v[130:133], v[200:203], v[28:31]
	v_mfma_f32_16x16x32_bf16 v[24:27], v[134:137], v[200:203], v[24:27]
	v_mfma_f32_16x16x32_bf16 v[12:15], v[130:133], v[204:207], v[12:15]
	v_mfma_f32_16x16x32_bf16 v[8:11], v[134:137], v[204:207], v[8:11]
	v_mfma_f32_16x16x32_bf16 v[60:63], v[138:141], v[192:195], v[60:63]
	v_mfma_f32_16x16x32_bf16 v[56:59], v[142:145], v[192:195], v[56:59]
	v_mfma_f32_16x16x32_bf16 v[44:47], v[138:141], v[196:199], v[44:47]
	v_mfma_f32_16x16x32_bf16 v[40:43], v[142:145], v[196:199], v[40:43]
	v_mfma_f32_16x16x32_bf16 v[28:31], v[138:141], v[208:211], v[28:31]
	v_mfma_f32_16x16x32_bf16 v[24:27], v[142:145], v[208:211], v[24:27]
	v_mfma_f32_16x16x32_bf16 v[12:15], v[138:141], v[212:215], v[12:15]
	v_mfma_f32_16x16x32_bf16 v[8:11], v[142:145], v[212:215], v[8:11]
	s_setprio 0
	s_setprio 1
	v_mfma_f32_16x16x32_bf16 v[52:55], v[146:149], v[176:179], v[52:55]
	v_mfma_f32_16x16x32_bf16 v[48:51], v[150:153], v[176:179], v[48:51]
	v_mfma_f32_16x16x32_bf16 v[36:39], v[146:149], v[180:183], v[36:39]
	v_mfma_f32_16x16x32_bf16 v[32:35], v[150:153], v[180:183], v[32:35]
	v_mfma_f32_16x16x32_bf16 v[20:23], v[146:149], v[200:203], v[20:23]
	v_mfma_f32_16x16x32_bf16 v[16:19], v[150:153], v[200:203], v[16:19]
	v_mfma_f32_16x16x32_bf16 v[4:7], v[146:149], v[204:207], v[4:7]
	v_mfma_f32_16x16x32_bf16 v[0:3], v[150:153], v[204:207], v[0:3]
	v_mfma_f32_16x16x32_bf16 v[52:55], v[162:165], v[192:195], v[52:55]
	v_mfma_f32_16x16x32_bf16 v[48:51], v[166:169], v[192:195], v[48:51]
	v_mfma_f32_16x16x32_bf16 v[36:39], v[162:165], v[196:199], v[36:39]
	v_mfma_f32_16x16x32_bf16 v[32:35], v[166:169], v[196:199], v[32:35]
	v_mfma_f32_16x16x32_bf16 v[20:23], v[162:165], v[208:211], v[20:23]
	v_mfma_f32_16x16x32_bf16 v[16:19], v[166:169], v[208:211], v[16:19]
	v_mfma_f32_16x16x32_bf16 v[4:7], v[162:165], v[212:215], v[4:7]
	v_mfma_f32_16x16x32_bf16 v[0:3], v[166:169], v[212:215], v[0:3]
	s_setprio 0
	s_barrier
	s_add_i32 s55, s55, 2
	s_add_u32 s52, s52, 0x100
	s_addc_u32 s54, s54, 0
	s_add_u32 s12, s12, 0x100
	s_addc_u32 s13, s13, 0
	s_cmp_gt_u32 s55, 5
	s_cbranch_scc0 .LBB0_796
	s_branch .Lpeel_exit_5

; #define PG8_STAGE(bufoff, gbase, voff) do { _Pragma("unroll") for (int _i = 0; _i < 2; ++_i) \
;         dma16((const char*)(gbase), (voff)[_i], ldsb + (bufoff) + ldsw + _i * 8192); } while (0)
; #define PG8_LDA(dst, b, h) do { const int a1_ = opqv(aoff0) ^ 64; _Pragma("unroll") for (int m = 0; m < 4; ++m) { dst[m][0] = *(const LAS bf16x8*)(lds + PG8_SA(b, h) + aoff0 + m * 2048); dst[m][1] = *(const LAS bf16x8*)(lds + PG8_SA(b, h) + a1_ + m * 2048); } } while (0)
; #define PG8_LDB(dst, b, h) do { const int b1_ = opqv(boff0) ^ 64; _Pragma("unroll") for (int n = 0; n < 2; ++n) { dst[n][0] = *(const LAS bf16x8*)(lds + PG8_SB(b, h) + boff0 + n * 2048); dst[n][1] = *(const LAS bf16x8*)(lds + PG8_SB(b, h) + b1_ + n * 2048); } } while (0)
; #define PG8_MMA(ai, bj, At, Bt) do { __builtin_amdgcn_s_setprio(1); _Pragma("unroll") for (int m = 0; m < 4; ++m) _Pragma("unroll") for (int n = 0; n < 2; ++n) _Pragma("unroll") for (int k = 0; k < 2; ++k) \
;         acc[ai][bj][m][n] = __builtin_amdgcn_mfma_f32_16x16x32_bf16(Bt[n][k], At[m][k], acc[ai][bj][m][n], 0, 0, 0); __builtin_amdgcn_s_setprio(0); } while (0)
; #define PG8_WAIT_V(n) asm volatile("s_waitcnt vmcnt(" #n ")" ::: "memory")
; #define PG8_WAIT_L(n) asm volatile("s_waitcnt lgkmcnt(" #n ")" ::: "memory")
; template <class Epi>
; __device__ __forceinline__ void gemm_phase(LAS unsigned char* lds, const Gemm g, const StaticOrder& S, const Epi& E, int wave_) {
;     ...
;             const char* a1 = cA + (size_t)(t + 1) * kstep;
;             const char* a2 = last ? nA : cA + (size_t)(t + 2) * kstep; const char* b2 = last ? nB : cB + (size_t)(t + 2) * kstep;
;             const char* a3 = a2 + kstep; const char* b3 = b2 + kstep;
;             PG8_STAGE(PG8_SA(1, 1), a1 + hstepA, voffA); PG8_LDB(B0, 0, 0); PG8_LDB(B1, 0, 1); PG8_SCHED; PG8_LDA(At, 0, 0);
;             PG8_WAIT_V(8); PG8_WAIT_L(0); PG8_BAR; PG8_MMA(0, 0, At, B0); PG8_MMA(0, 1, At, B1); PG8_BAR; PG8_SCHED;
;             PG8_STAGE(PG8_SB(0, 0), b2, voffB); PG8_STAGE(PG8_SB(0, 1), b2 + hstepB, voffB); PG8_STAGE(PG8_SA(0, 0), a2, voffA); PG8_LDA(At, 0, 1);
;     ...
;         for (int a = 0; a < 2; ++a)
; #pragma unroll
;             for (int b = 0; b < 2; ++b)
; #pragma unroll
;                 for (int m = 0; m < 4; ++m)
; #pragma unroll
;                     for (int n = 0; n < 2; ++n) acc[a][b][m][n] = (f32x4){0.f, 0.f, 0.f, 0.f};
.LBB0_1103:
	s_ashr_i32 s19, s18, 31
	s_lshl_b64 s[16:17], s[18:19], 20
	s_add_u32 s24, s21, s16
	s_addc_u32 s25, s46, s17
	s_and_b64 s[16:17], s[44:45], exec
	s_cselect_b32 s16, s25, s31
	s_cselect_b32 s17, s24, s30
	s_ashr_i32 s11, s10, 31
	s_lshl_b64 s[26:27], s[10:11], 20
	s_add_u32 s26, s47, s26
	s_addc_u32 s27, s48, s27
	s_and_b64 s[36:37], s[44:45], exec
	s_cselect_b32 s11, s27, s13
	s_cselect_b32 s19, s26, s12
	s_add_u32 s55, s12, 0x100
	s_addc_u32 s56, s13, 0
	s_add_u32 s12, s30, 0x80080
	s_addc_u32 s13, s31, 0
	s_mov_b32 s57, -2
	s_add_u32 s30, s12, 0xfff80080
	s_addc_u32 s31, s13, -1
	s_cmp_eq_u32 s57, 28
	s_cselect_b32 s40, s17, s30
	s_cselect_b32 s41, s16, s31
	s_cselect_b32 s36, s19, s55
	s_cselect_b32 s37, s11, s56
	s_add_u32 s30, s40, 0x80
	v_mov_b32_e32 v128, v172
	s_addc_u32 s31, s41, 0
	v_add_u32_e32 v132, s23, v172
	v_xad_u32 v140, v128, 64, s23
	v_mov_b32_e32 v144, v172
	s_add_i32 s60, 0, 0x14000
	ds_read_b128 v[128:131], v132
	ds_read_b128 v[132:135], v132 offset:2048
	ds_read_b128 v[136:139], v140
	ds_read_b128 v[140:143], v140 offset:2048
	v_add_u32_e32 v148, s60, v172
	v_xad_u32 v156, v144, 64, s60
	ds_read_b128 v[144:147], v148
	ds_read_b128 v[148:151], v148 offset:2048
	ds_read_b128 v[152:155], v156
	ds_read_b128 v[156:159], v156 offset:2048
	v_mov_b32_e32 v160, v171
	v_add_u32_e32 v183, 0, v171
	v_xad_u32 v182, v160, 64, 0
	ds_read_b128 v[160:163], v183
	ds_read_b128 v[174:177], v183 offset:2048
	ds_read_b128 v[178:181], v182
	ds_read_b128 v[192:195], v182 offset:2048
	ds_read_b128 v[196:199], v183 offset:4096
	ds_read_b128 v[200:203], v183 offset:6144
	ds_read_b128 v[204:207], v182 offset:4096
	ds_read_b128 v[208:211], v182 offset:6144
	s_mov_b32 m0, s14
	s_nop 0
	global_load_lds_dwordx4 v166, s[12:13]
	s_mov_b32 m0, s15
	s_nop 0
	global_load_lds_dwordx4 v168, s[12:13]
	s_waitcnt vmcnt(8)
	s_waitcnt lgkmcnt(0)
	s_barrier
	s_setprio 1
	s_waitcnt lgkmcnt(0)
	v_mfma_f32_16x16x32_bf16 v[124:127], v[128:131], v[160:163], 0
	v_mfma_f32_16x16x32_bf16 v[120:123], v[132:135], v[160:163], 0
	v_mfma_f32_16x16x32_bf16 v[108:111], v[128:131], v[174:177], 0
	v_mfma_f32_16x16x32_bf16 v[104:107], v[132:135], v[174:177], 0
	v_mfma_f32_16x16x32_bf16 v[92:95], v[128:131], v[196:199], 0
	v_mfma_f32_16x16x32_bf16 v[88:91], v[132:135], v[196:199], 0
	v_mfma_f32_16x16x32_bf16 v[76:79], v[128:131], v[200:203], 0
	v_mfma_f32_16x16x32_bf16 v[72:75], v[132:135], v[200:203], 0
	v_mfma_f32_16x16x32_bf16 v[124:127], v[136:139], v[178:181], v[124:127]
	v_mfma_f32_16x16x32_bf16 v[120:123], v[140:143], v[178:181], v[120:123]
	v_mfma_f32_16x16x32_bf16 v[108:111], v[136:139], v[192:195], v[108:111]
	v_mfma_f32_16x16x32_bf16 v[104:107], v[140:143], v[192:195], v[104:107]
	v_mfma_f32_16x16x32_bf16 v[92:95], v[136:139], v[204:207], v[92:95]
	v_mfma_f32_16x16x32_bf16 v[88:91], v[140:143], v[204:207], v[88:91]
	v_mfma_f32_16x16x32_bf16 v[76:79], v[136:139], v[208:211], v[76:79]
	v_mfma_f32_16x16x32_bf16 v[72:75], v[140:143], v[208:211], v[72:75]
	s_setprio 0
	s_setprio 1
	v_mfma_f32_16x16x32_bf16 v[116:119], v[144:147], v[160:163], 0
	v_mfma_f32_16x16x32_bf16 v[112:115], v[148:151], v[160:163], 0
	v_mfma_f32_16x16x32_bf16 v[100:103], v[144:147], v[174:177], 0
	v_mfma_f32_16x16x32_bf16 v[96:99], v[148:151], v[174:177], 0
	v_mfma_f32_16x16x32_bf16 v[84:87], v[144:147], v[196:199], 0
	v_mfma_f32_16x16x32_bf16 v[80:83], v[148:151], v[196:199], 0
	v_mfma_f32_16x16x32_bf16 v[68:71], v[144:147], v[200:203], 0
	v_mfma_f32_16x16x32_bf16 v[64:67], v[148:151], v[200:203], 0
	v_mfma_f32_16x16x32_bf16 v[116:119], v[152:155], v[178:181], v[116:119]
	v_mfma_f32_16x16x32_bf16 v[112:115], v[156:159], v[178:181], v[112:115]
	v_mfma_f32_16x16x32_bf16 v[100:103], v[152:155], v[192:195], v[100:103]
	v_mfma_f32_16x16x32_bf16 v[96:99], v[156:159], v[192:195], v[96:99]
	v_mfma_f32_16x16x32_bf16 v[84:87], v[152:155], v[204:207], v[84:87]
	v_mfma_f32_16x16x32_bf16 v[80:83], v[156:159], v[204:207], v[80:83]
	v_mfma_f32_16x16x32_bf16 v[68:71], v[152:155], v[208:211], v[68:71]
	v_mfma_f32_16x16x32_bf16 v[64:67], v[156:159], v[208:211], v[64:67]
	s_setprio 0
	s_barrier
	v_mov_b32_e32 v160, v171
	s_add_u32 s60, s36, 0x80000
	s_addc_u32 s61, s37, 0
	s_nop 0
	s_nop 0
	s_nop 0
	v_xad_u32 v182, v160, 64, 0
	ds_read_b128 v[160:163], v183 offset:16384
	ds_read_b128 v[174:177], v183 offset:18432
	ds_read_b128 v[178:181], v182 offset:16384
	ds_read_b128 v[192:195], v182 offset:18432
	ds_read_b128 v[196:199], v183 offset:20480
	ds_read_b128 v[200:203], v183 offset:22528
	ds_read_b128 v[204:207], v182 offset:20480
	ds_read_b128 v[208:211], v182 offset:22528
	s_mov_b32 m0, s80
	s_nop 0
	global_load_lds_dwordx4 v167, s[36:37]
	s_mov_b32 m0, s81
	s_nop 0
	global_load_lds_dwordx4 v169, s[36:37]
	s_mov_b32 m0, s29
	s_nop 0
	global_load_lds_dwordx4 v167, s[60:61]
	s_mov_b32 m0, s88
	s_nop 0
	global_load_lds_dwordx4 v169, s[60:61]
	s_mov_b32 m0, s76
	s_nop 0
	global_load_lds_dwordx4 v166, s[40:41]
	s_mov_b32 m0, s89
	s_nop 0
	global_load_lds_dwordx4 v168, s[40:41]
	s_waitcnt vmcnt(8)
	s_waitcnt lgkmcnt(0)
	s_barrier
; #define PG8_STAGE(bufoff, gbase, voff) do { _Pragma("unroll") for (int _i = 0; _i < 2; ++_i) \
;         dma16((const char*)(gbase), (voff)[_i], ldsb + (bufoff) + ldsw + _i * 8192); } while (0)
; #define PG8_LDA(dst, b, h) do { const int a1_ = opqv(aoff0) ^ 64; _Pragma("unroll") for (int m = 0; m < 4; ++m) { dst[m][0] = *(const LAS bf16x8*)(lds + PG8_SA(b, h) + aoff0 + m * 2048); dst[m][1] = *(const LAS bf16x8*)(lds + PG8_SA(b, h) + a1_ + m * 2048); } } while (0)
; #define PG8_LDB(dst, b, h) do { const int b1_ = opqv(boff0) ^ 64; _Pragma("unroll") for (int n = 0; n < 2; ++n) { dst[n][0] = *(const LAS bf16x8*)(lds + PG8_SB(b, h) + boff0 + n * 2048); dst[n][1] = *(const LAS bf16x8*)(lds + PG8_SB(b, h) + b1_ + n * 2048); } } while (0)
; #define PG8_MMA(ai, bj, At, Bt) do { __builtin_amdgcn_s_setprio(1); _Pragma("unroll") for (int m = 0; m < 4; ++m) _Pragma("unroll") for (int n = 0; n < 2; ++n) _Pragma("unroll") for (int k = 0; k < 2; ++k) \
;         acc[ai][bj][m][n] = __builtin_amdgcn_mfma_f32_16x16x32_bf16(Bt[n][k], At[m][k], acc[ai][bj][m][n], 0, 0, 0); __builtin_amdgcn_s_setprio(0); } while (0)
; #define PG8_WAIT_V(n) asm volatile("s_waitcnt vmcnt(" #n ")" ::: "memory")
; #define PG8_WAIT_L(n) asm volatile("s_waitcnt lgkmcnt(" #n ")" ::: "memory")
; #define PG8_BAR __builtin_amdgcn_s_barrier()
; #define PG8_SCHED __builtin_amdgcn_sched_barrier(0)
; template <class Epi>
; __device__ __forceinline__ void gemm_phase(LAS unsigned char* lds, const Gemm g, const StaticOrder& S, const Epi& E, int wave_) {
;     ...
;             PG8_WAIT_V(8); PG8_WAIT_L(0); PG8_BAR; PG8_MMA(1, 0, At, B0); PG8_MMA(1, 1, At, B1); PG8_BAR; PG8_SCHED;
;             PG8_STAGE(PG8_SA(0, 1), a2 + hstepA, voffA); PG8_LDB(B0, 1, 0); PG8_LDB(B1, 1, 1); PG8_SCHED; PG8_LDA(At, 1, 0);
;             PG8_WAIT_V(8); PG8_WAIT_L(0); PG8_BAR; PG8_MMA(0, 0, At, B0); PG8_MMA(0, 1, At, B1); PG8_BAR; PG8_SCHED;
	s_setprio 1
	s_waitcnt lgkmcnt(0)
	v_mfma_f32_16x16x32_bf16 v[60:63], v[128:131], v[160:163], 0
	v_mfma_f32_16x16x32_bf16 v[56:59], v[132:135], v[160:163], 0
	v_mfma_f32_16x16x32_bf16 v[44:47], v[128:131], v[174:177], 0
	v_mfma_f32_16x16x32_bf16 v[40:43], v[132:135], v[174:177], 0
	v_mfma_f32_16x16x32_bf16 v[28:31], v[128:131], v[196:199], 0
	v_mfma_f32_16x16x32_bf16 v[24:27], v[132:135], v[196:199], 0
	v_mfma_f32_16x16x32_bf16 v[12:15], v[128:131], v[200:203], 0
	v_mfma_f32_16x16x32_bf16 v[8:11], v[132:135], v[200:203], 0
	v_mfma_f32_16x16x32_bf16 v[60:63], v[136:139], v[178:181], v[60:63]
	v_mfma_f32_16x16x32_bf16 v[56:59], v[140:143], v[178:181], v[56:59]
	v_mfma_f32_16x16x32_bf16 v[44:47], v[136:139], v[192:195], v[44:47]
	v_mfma_f32_16x16x32_bf16 v[40:43], v[140:143], v[192:195], v[40:43]
	v_mfma_f32_16x16x32_bf16 v[28:31], v[136:139], v[204:207], v[28:31]
	v_mfma_f32_16x16x32_bf16 v[24:27], v[140:143], v[204:207], v[24:27]
	v_mfma_f32_16x16x32_bf16 v[12:15], v[136:139], v[208:211], v[12:15]
	v_mfma_f32_16x16x32_bf16 v[8:11], v[140:143], v[208:211], v[8:11]
	s_setprio 0
	s_setprio 1
	v_mfma_f32_16x16x32_bf16 v[52:55], v[144:147], v[160:163], 0
	v_mfma_f32_16x16x32_bf16 v[48:51], v[148:151], v[160:163], 0
	v_mfma_f32_16x16x32_bf16 v[36:39], v[144:147], v[174:177], 0
	v_mfma_f32_16x16x32_bf16 v[32:35], v[148:151], v[174:177], 0
	v_mfma_f32_16x16x32_bf16 v[20:23], v[144:147], v[196:199], 0
	v_mfma_f32_16x16x32_bf16 v[16:19], v[148:151], v[196:199], 0
	v_mfma_f32_16x16x32_bf16 v[4:7], v[144:147], v[200:203], 0
	v_mfma_f32_16x16x32_bf16 v[0:3], v[148:151], v[200:203], 0
	v_mfma_f32_16x16x32_bf16 v[52:55], v[152:155], v[178:181], v[52:55]
	v_mfma_f32_16x16x32_bf16 v[48:51], v[156:159], v[178:181], v[48:51]
	v_mfma_f32_16x16x32_bf16 v[36:39], v[152:155], v[192:195], v[36:39]
	v_mfma_f32_16x16x32_bf16 v[32:35], v[156:159], v[192:195], v[32:35]
	v_mfma_f32_16x16x32_bf16 v[20:23], v[152:155], v[204:207], v[20:23]
	v_mfma_f32_16x16x32_bf16 v[16:19], v[156:159], v[204:207], v[16:19]
	v_mfma_f32_16x16x32_bf16 v[4:7], v[152:155], v[208:211], v[4:7]
	v_mfma_f32_16x16x32_bf16 v[0:3], v[156:159], v[208:211], v[0:3]
	s_setprio 0
	s_barrier
	s_add_u32 s40, s40, 0x80000
	s_addc_u32 s41, s41, 0
	s_mov_b32 m0, s1
	s_nop 0
	global_load_lds_dwordx4 v166, s[40:41]
	v_mov_b32_e32 v128, v172
	s_mov_b32 m0, s69
	s_nop 0
	global_load_lds_dwordx4 v168, s[40:41]
	v_add_u32_e32 v132, s34, v172
	v_xad_u32 v140, v128, 64, s34
	v_mov_b32_e32 v144, v172
	s_add_i32 s40, 0, 0x1c000
	ds_read_b128 v[128:131], v132
	ds_read_b128 v[132:135], v132 offset:2048
	ds_read_b128 v[136:139], v140
	ds_read_b128 v[140:143], v140 offset:2048
	v_add_u32_e32 v148, s40, v172
	v_xad_u32 v156, v144, 64, s40
	ds_read_b128 v[144:147], v148
	ds_read_b128 v[148:151], v148 offset:2048
	ds_read_b128 v[152:155], v156
	ds_read_b128 v[156:159], v156 offset:2048
	v_mov_b32_e32 v160, v171
	s_nop 0
	v_xad_u32 v182, v160, 64, 0
	ds_read_b128 v[160:163], v183 offset:32768
	ds_read_b128 v[174:177], v183 offset:34816
	ds_read_b128 v[178:181], v182 offset:32768
	ds_read_b128 v[192:195], v182 offset:34816
	ds_read_b128 v[196:199], v183 offset:36864
	ds_read_b128 v[200:203], v183 offset:38912
	ds_read_b128 v[204:207], v182 offset:36864
	ds_read_b128 v[208:211], v182 offset:38912
	s_waitcnt vmcnt(8)
	s_waitcnt lgkmcnt(0)
	s_barrier
	s_setprio 1
	s_waitcnt lgkmcnt(0)
	v_mfma_f32_16x16x32_bf16 v[124:127], v[128:131], v[160:163], v[124:127]
	v_mfma_f32_16x16x32_bf16 v[120:123], v[132:135], v[160:163], v[120:123]
	v_mfma_f32_16x16x32_bf16 v[108:111], v[128:131], v[174:177], v[108:111]
	v_mfma_f32_16x16x32_bf16 v[104:107], v[132:135], v[174:177], v[104:107]
	v_mfma_f32_16x16x32_bf16 v[92:95], v[128:131], v[196:199], v[92:95]
	v_mfma_f32_16x16x32_bf16 v[88:91], v[132:135], v[196:199], v[88:91]
	v_mfma_f32_16x16x32_bf16 v[76:79], v[128:131], v[200:203], v[76:79]
	v_mfma_f32_16x16x32_bf16 v[72:75], v[132:135], v[200:203], v[72:75]
	v_mfma_f32_16x16x32_bf16 v[124:127], v[136:139], v[178:181], v[124:127]
	v_mfma_f32_16x16x32_bf16 v[120:123], v[140:143], v[178:181], v[120:123]
	v_mfma_f32_16x16x32_bf16 v[108:111], v[136:139], v[192:195], v[108:111]
	v_mfma_f32_16x16x32_bf16 v[104:107], v[140:143], v[192:195], v[104:107]
	v_mfma_f32_16x16x32_bf16 v[92:95], v[136:139], v[204:207], v[92:95]
	v_mfma_f32_16x16x32_bf16 v[88:91], v[140:143], v[204:207], v[88:91]
	v_mfma_f32_16x16x32_bf16 v[76:79], v[136:139], v[208:211], v[76:79]
	v_mfma_f32_16x16x32_bf16 v[72:75], v[140:143], v[208:211], v[72:75]
	s_setprio 0
	s_setprio 1
	v_mfma_f32_16x16x32_bf16 v[116:119], v[144:147], v[160:163], v[116:119]
	s_add_u32 s40, s36, 0x80
	s_addc_u32 s41, s37, 0
	v_mfma_f32_16x16x32_bf16 v[112:115], v[148:151], v[160:163], v[112:115]
	v_mfma_f32_16x16x32_bf16 v[100:103], v[144:147], v[174:177], v[100:103]
	v_mfma_f32_16x16x32_bf16 v[96:99], v[148:151], v[174:177], v[96:99]
	v_mfma_f32_16x16x32_bf16 v[84:87], v[144:147], v[196:199], v[84:87]
	v_mfma_f32_16x16x32_bf16 v[80:83], v[148:151], v[196:199], v[80:83]
	v_mfma_f32_16x16x32_bf16 v[68:71], v[144:147], v[200:203], v[68:71]
	v_mfma_f32_16x16x32_bf16 v[64:67], v[148:151], v[200:203], v[64:67]
	v_mfma_f32_16x16x32_bf16 v[116:119], v[152:155], v[178:181], v[116:119]
	v_mfma_f32_16x16x32_bf16 v[112:115], v[156:159], v[178:181], v[112:115]
	v_mfma_f32_16x16x32_bf16 v[100:103], v[152:155], v[192:195], v[100:103]
	v_mfma_f32_16x16x32_bf16 v[96:99], v[156:159], v[192:195], v[96:99]
	v_mfma_f32_16x16x32_bf16 v[84:87], v[152:155], v[204:207], v[84:87]
	v_mfma_f32_16x16x32_bf16 v[80:83], v[156:159], v[204:207], v[80:83]
	v_mfma_f32_16x16x32_bf16 v[68:71], v[152:155], v[208:211], v[68:71]
	v_mfma_f32_16x16x32_bf16 v[64:67], v[156:159], v[208:211], v[64:67]
	s_setprio 0
	s_barrier
; #define PG8_STAGE(bufoff, gbase, voff) do { _Pragma("unroll") for (int _i = 0; _i < 2; ++_i) \
;         dma16((const char*)(gbase), (voff)[_i], ldsb + (bufoff) + ldsw + _i * 8192); } while (0)
; #define PG8_LDA(dst, b, h) do { const int a1_ = opqv(aoff0) ^ 64; _Pragma("unroll") for (int m = 0; m < 4; ++m) { dst[m][0] = *(const LAS bf16x8*)(lds + PG8_SA(b, h) + aoff0 + m * 2048); dst[m][1] = *(const LAS bf16x8*)(lds + PG8_SA(b, h) + a1_ + m * 2048); } } while (0)
; #define PG8_MMA(ai, bj, At, Bt) do { __builtin_amdgcn_s_setprio(1); _Pragma("unroll") for (int m = 0; m < 4; ++m) _Pragma("unroll") for (int n = 0; n < 2; ++n) _Pragma("unroll") for (int k = 0; k < 2; ++k) \
;         acc[ai][bj][m][n] = __builtin_amdgcn_mfma_f32_16x16x32_bf16(Bt[n][k], At[m][k], acc[ai][bj][m][n], 0, 0, 0); __builtin_amdgcn_s_setprio(0); } while (0)
; #define PG8_WAIT_V(n) asm volatile("s_waitcnt vmcnt(" #n ")" ::: "memory")
; #define PG8_WAIT_L(n) asm volatile("s_waitcnt lgkmcnt(" #n ")" ::: "memory")
; #define PG8_BAR __builtin_amdgcn_s_barrier()
; #define PG8_SCHED __builtin_amdgcn_sched_barrier(0)
; template <class Epi>
; __device__ __forceinline__ void gemm_phase(LAS unsigned char* lds, const Gemm g, const StaticOrder& S, const Epi& E, int wave_) {
;     ...
;             PG8_STAGE(PG8_SB(1, 0), b3, voffB); PG8_STAGE(PG8_SB(1, 1), b3 + hstepB, voffB); PG8_STAGE(PG8_SA(1, 0), a3, voffA); PG8_LDA(At, 1, 1);
;             PG8_WAIT_V(8); PG8_WAIT_L(0); PG8_BAR; PG8_MMA(1, 0, At, B0); PG8_MMA(1, 1, At, B1); PG8_BAR; PG8_SCHED;
	s_add_u32 s36, s36, 0x80080
	s_addc_u32 s37, s37, 0
	v_mov_b32_e32 v160, v171
	s_nop 0
	s_nop 0
	v_xad_u32 v182, v160, 64, 0
	ds_read_b128 v[160:163], v183 offset:49152
	ds_read_b128 v[174:177], v183 offset:51200
	ds_read_b128 v[178:181], v182 offset:49152
	ds_read_b128 v[192:195], v182 offset:51200
	ds_read_b128 v[196:199], v183 offset:53248
	ds_read_b128 v[200:203], v183 offset:55296
	ds_read_b128 v[204:207], v182 offset:53248
	ds_read_b128 v[208:211], v182 offset:55296
	s_mov_b32 m0, s35
	s_nop 0
	global_load_lds_dwordx4 v167, s[40:41]
	s_mov_b32 m0, s33
	s_nop 0
	global_load_lds_dwordx4 v169, s[40:41]
	s_mov_b32 m0, s77
	s_nop 0
	global_load_lds_dwordx4 v167, s[36:37]
	s_mov_b32 m0, s3
	s_nop 0
	global_load_lds_dwordx4 v169, s[36:37]
	s_mov_b32 m0, s22
	s_nop 0
	global_load_lds_dwordx4 v166, s[30:31]
	s_mov_b32 m0, s2
	s_nop 0
	global_load_lds_dwordx4 v168, s[30:31]
	s_waitcnt vmcnt(8)
	s_waitcnt lgkmcnt(0)
	s_barrier
	s_setprio 1
	s_waitcnt lgkmcnt(0)
	v_mfma_f32_16x16x32_bf16 v[60:63], v[128:131], v[160:163], v[60:63]
	v_mfma_f32_16x16x32_bf16 v[56:59], v[132:135], v[160:163], v[56:59]
	v_mfma_f32_16x16x32_bf16 v[44:47], v[128:131], v[174:177], v[44:47]
	v_mfma_f32_16x16x32_bf16 v[40:43], v[132:135], v[174:177], v[40:43]
	v_mfma_f32_16x16x32_bf16 v[28:31], v[128:131], v[196:199], v[28:31]
	v_mfma_f32_16x16x32_bf16 v[24:27], v[132:135], v[196:199], v[24:27]
	v_mfma_f32_16x16x32_bf16 v[12:15], v[128:131], v[200:203], v[12:15]
	v_mfma_f32_16x16x32_bf16 v[8:11], v[132:135], v[200:203], v[8:11]
	v_mfma_f32_16x16x32_bf16 v[60:63], v[136:139], v[178:181], v[60:63]
	v_mfma_f32_16x16x32_bf16 v[56:59], v[140:143], v[178:181], v[56:59]
	v_mfma_f32_16x16x32_bf16 v[44:47], v[136:139], v[192:195], v[44:47]
	v_mfma_f32_16x16x32_bf16 v[40:43], v[140:143], v[192:195], v[40:43]
	v_mfma_f32_16x16x32_bf16 v[28:31], v[136:139], v[204:207], v[28:31]
	v_mfma_f32_16x16x32_bf16 v[24:27], v[140:143], v[204:207], v[24:27]
	v_mfma_f32_16x16x32_bf16 v[12:15], v[136:139], v[208:211], v[12:15]
	v_mfma_f32_16x16x32_bf16 v[8:11], v[140:143], v[208:211], v[8:11]
	s_setprio 0
	s_setprio 1
	v_mfma_f32_16x16x32_bf16 v[52:55], v[144:147], v[160:163], v[52:55]
	v_mfma_f32_16x16x32_bf16 v[48:51], v[148:151], v[160:163], v[48:51]
	v_mfma_f32_16x16x32_bf16 v[36:39], v[144:147], v[174:177], v[36:39]
	v_mfma_f32_16x16x32_bf16 v[32:35], v[148:151], v[174:177], v[32:35]
	v_mfma_f32_16x16x32_bf16 v[20:23], v[144:147], v[196:199], v[20:23]
	v_mfma_f32_16x16x32_bf16 v[16:19], v[148:151], v[196:199], v[16:19]
	v_mfma_f32_16x16x32_bf16 v[4:7], v[144:147], v[200:203], v[4:7]
	v_mfma_f32_16x16x32_bf16 v[0:3], v[148:151], v[200:203], v[0:3]
	v_mfma_f32_16x16x32_bf16 v[52:55], v[152:155], v[178:181], v[52:55]
	v_mfma_f32_16x16x32_bf16 v[48:51], v[156:159], v[178:181], v[48:51]
	v_mfma_f32_16x16x32_bf16 v[36:39], v[152:155], v[192:195], v[36:39]
	v_mfma_f32_16x16x32_bf16 v[32:35], v[156:159], v[192:195], v[32:35]
	v_mfma_f32_16x16x32_bf16 v[20:23], v[152:155], v[204:207], v[20:23]
	v_mfma_f32_16x16x32_bf16 v[16:19], v[156:159], v[204:207], v[16:19]
	v_mfma_f32_16x16x32_bf16 v[4:7], v[152:155], v[208:211], v[4:7]
	v_mfma_f32_16x16x32_bf16 v[0:3], v[156:159], v[208:211], v[0:3]
	s_setprio 0
	s_barrier
	s_add_i32 s57, s57, 2
	s_add_u32 s55, s55, 0x100
	s_addc_u32 s56, s56, 0
	s_add_u32 s12, s12, 0x100
	s_addc_u32 s13, s13, 0
	s_cmp_gt_u32 s57, 29
	s_cbranch_scc0 .LBB0_1104
	s_branch .Lpeel_exit_4

; __device__ __forceinline__ unsigned xb_add(unsigned* p, unsigned v) { return __hip_atomic_fetch_add(p, v, __ATOMIC_RELAXED, __HIP_MEMORY_SCOPE_AGENT); }
; __device__ __forceinline__ void xcd_barrier_bg(const XcdBarrier& b, const Frame& F, unsigned char* ws, int Ln, BgState& bg) {
;     ...
;         unsigned nloc = b.st[0], nx = b.st[1];
;         if (nloc == 0u) { xcd_barrier_complete(bar, b.x, nloc, nx); b.st[0] = nloc; b.st[1] = nx; }
;         const unsigned old = xb_add(&bar[XB_XSUB(b.x)], 1u);
;         const unsigned gen = old / nloc;
;         b.st[2] = gen; b.st[3] = (old + 1u == (gen + 1u) * nloc) ? 2u : ((old + BG_LATE >= (gen + 1u) * nloc) ? 1u : 0u);
.LBB0_1142:
	v_readlane_b32 s6, v253, 5
	s_lshl_b32 s6, s6, 2
	s_add_u32 s6, s44, s6
	s_addc_u32 s7, s45, 0
	s_waitcnt lgkmcnt(0)
	v_mov_b32_e32 v1, s6
	v_add_co_u32_e32 v2, vcc, 0x1000, v1
	v_mov_b32_e32 v1, s7
	s_nop 0
	v_addc_co_u32_e32 v3, vcc, 0, v1, vcc
	v_mov_b32_e32 v1, 1
	flat_atomic_add v2, v[2:3], v1 offset:1024 sc0
	v_cvt_f32_u32_e32 v1, v0
	v_sub_u32_e32 v3, 0, v0
	v_readlane_b32 s6, v255, 9
	v_rcp_iflag_f32_e32 v1, v1
	s_nop 0
	v_mul_f32_e32 v1, 0x4f7ffffe, v1
	v_cvt_u32_f32_e32 v1, v1
	v_mul_lo_u32 v3, v3, v1
	v_mul_hi_u32 v3, v1, v3
	v_add_u32_e32 v1, v1, v3
	s_waitcnt vmcnt(0) lgkmcnt(0)
	v_mul_hi_u32 v1, v2, v1
	v_mul_lo_u32 v3, v1, v0
	v_sub_u32_e32 v3, v2, v3
	v_cmp_ge_u32_e32 vcc, v3, v0
	v_add_u32_e32 v4, 1, v1
	s_nop 0
	v_cndmask_b32_e32 v1, v1, v4, vcc
	v_sub_u32_e32 v4, v3, v0
	v_cndmask_b32_e32 v3, v3, v4, vcc
	v_cmp_ge_u32_e32 vcc, v3, v0
	v_add_u32_e32 v3, 1, v1
	s_nop 0
	v_cndmask_b32_e32 v1, v1, v3, vcc
	v_mov_b32_e32 v3, s6
	ds_write_b32 v3, v1
	v_mad_u64_u32 v[0:1], s[6:7], v0, v1, v[0:1]
	v_add_u32_e32 v1, 8, v2
	v_add_u32_e32 v3, 1, v2
	v_cmp_ge_u32_e32 vcc, v1, v0
	v_readlane_b32 s6, v255, 10
	s_nop 0
	v_cndmask_b32_e64 v1, 0, 1, vcc
	v_cmp_ne_u32_e32 vcc, v3, v0
	s_nop 1
	v_cndmask_b32_e32 v0, 2, v1, vcc
	v_mov_b32_e32 v1, s6
	ds_write_b32 v1, v0

; #define PG8_STAGE(bufoff, gbase, voff) do { _Pragma("unroll") for (int _i = 0; _i < 2; ++_i) \
;         dma16((const char*)(gbase), (voff)[_i], ldsb + (bufoff) + ldsw + _i * 8192); } while (0)
; #define PG8_LDA(dst, b, h) do { const int a1_ = opqv(aoff0) ^ 64; _Pragma("unroll") for (int m = 0; m < 4; ++m) { dst[m][0] = *(const LAS bf16x8*)(lds + PG8_SA(b, h) + aoff0 + m * 2048); dst[m][1] = *(const LAS bf16x8*)(lds + PG8_SA(b, h) + a1_ + m * 2048); } } while (0)
; #define PG8_LDB(dst, b, h) do { const int b1_ = opqv(boff0) ^ 64; _Pragma("unroll") for (int n = 0; n < 2; ++n) { dst[n][0] = *(const LAS bf16x8*)(lds + PG8_SB(b, h) + boff0 + n * 2048); dst[n][1] = *(const LAS bf16x8*)(lds + PG8_SB(b, h) + b1_ + n * 2048); } } while (0)
; #define PG8_MMA(ai, bj, At, Bt) do { __builtin_amdgcn_s_setprio(1); _Pragma("unroll") for (int m = 0; m < 4; ++m) _Pragma("unroll") for (int n = 0; n < 2; ++n) _Pragma("unroll") for (int k = 0; k < 2; ++k) \
;         acc[ai][bj][m][n] = __builtin_amdgcn_mfma_f32_16x16x32_bf16(Bt[n][k], At[m][k], acc[ai][bj][m][n], 0, 0, 0); __builtin_amdgcn_s_setprio(0); } while (0)
; #define PG8_WAIT_V(n) asm volatile("s_waitcnt vmcnt(" #n ")" ::: "memory")
; #define PG8_WAIT_L(n) asm volatile("s_waitcnt lgkmcnt(" #n ")" ::: "memory")
; template <class Epi>
; __device__ __forceinline__ void gemm_phase(LAS unsigned char* lds, const Gemm g, const StaticOrder& S, const Epi& E, int wave_) {
;     ...
;             const char* a1 = cA + (size_t)(t + 1) * kstep;
;             const char* a2 = last ? nA : cA + (size_t)(t + 2) * kstep; const char* b2 = last ? nB : cB + (size_t)(t + 2) * kstep;
;             const char* a3 = a2 + kstep; const char* b3 = b2 + kstep;
;             PG8_STAGE(PG8_SA(1, 1), a1 + hstepA, voffA); PG8_LDB(B0, 0, 0); PG8_LDB(B1, 0, 1); PG8_SCHED; PG8_LDA(At, 0, 0);
;             PG8_WAIT_V(8); PG8_WAIT_L(0); PG8_BAR; PG8_MMA(0, 0, At, B0); PG8_MMA(0, 1, At, B1); PG8_BAR; PG8_SCHED;
;             PG8_STAGE(PG8_SB(0, 0), b2, voffB); PG8_STAGE(PG8_SB(0, 1), b2 + hstepB, voffB); PG8_STAGE(PG8_SA(0, 0), a2, voffA); PG8_LDA(At, 0, 1);
;     ...
;         for (int a = 0; a < 2; ++a)
; #pragma unroll
;             for (int b = 0; b < 2; ++b)
; #pragma unroll
;                 for (int m = 0; m < 4; ++m)
; #pragma unroll
;                     for (int n = 0; n < 2; ++n) acc[a][b][m][n] = (f32x4){0.f, 0.f, 0.f, 0.f};
.LBB0_1321:
	s_ashr_i32 s25, s24, 31
	s_lshl_b64 s[16:17], s[24:25], 20
	s_add_u32 s26, s21, s16
	s_addc_u32 s27, s46, s17
	s_and_b64 s[16:17], s[42:43], exec
	s_cselect_b32 s16, s27, s37
	s_cselect_b32 s17, s26, s36
	s_ashr_i32 s19, s18, 31
	s_lshl_b64 s[30:31], s[18:19], 20
	s_add_u32 s30, s47, s30
	s_addc_u32 s31, s48, s31
	s_and_b64 s[40:41], s[42:43], exec
	s_cselect_b32 s19, s31, s13
	s_cselect_b32 s25, s30, s12
	s_add_u32 s55, s12, 0x100
	s_addc_u32 s56, s13, 0
	s_add_u32 s12, s36, 0x80080
	s_addc_u32 s13, s37, 0
	s_mov_b32 s57, -2
	s_add_u32 s36, s12, 0xfff80080
	s_addc_u32 s37, s13, -1
	s_cmp_eq_u32 s57, 28
	s_cselect_b32 s44, s17, s36
	s_cselect_b32 s45, s16, s37
	s_cselect_b32 s40, s25, s55
	s_cselect_b32 s41, s19, s56
	s_add_u32 s36, s44, 0x80
	v_mov_b32_e32 v128, v178
	s_addc_u32 s37, s45, 0
	v_add_u32_e32 v132, s23, v178
	v_xad_u32 v140, v128, 64, s23
	v_mov_b32_e32 v144, v178
	s_add_i32 s60, 0, 0x14000
	ds_read_b128 v[128:131], v132
	ds_read_b128 v[132:135], v132 offset:2048
	ds_read_b128 v[136:139], v140
	ds_read_b128 v[140:143], v140 offset:2048
	v_add_u32_e32 v148, s60, v178
	v_xad_u32 v156, v144, 64, s60
	ds_read_b128 v[144:147], v148
	ds_read_b128 v[148:151], v148 offset:2048
	ds_read_b128 v[152:155], v156
	ds_read_b128 v[156:159], v156 offset:2048
	v_mov_b32_e32 v160, v177
	v_add_u32_e32 v169, 0, v177
	v_xad_u32 v168, v160, 64, 0
	ds_read_b128 v[160:163], v169
	ds_read_b128 v[164:167], v169 offset:2048
	ds_read_b128 v[180:183], v168
	ds_read_b128 v[192:195], v168 offset:2048
	ds_read_b128 v[196:199], v169 offset:4096
	ds_read_b128 v[200:203], v169 offset:6144
	ds_read_b128 v[204:207], v168 offset:4096
	ds_read_b128 v[208:211], v168 offset:6144
	s_mov_b32 m0, s14
	s_nop 0
	global_load_lds_dwordx4 v172, s[12:13]
	s_mov_b32 m0, s15
	s_nop 0
	global_load_lds_dwordx4 v174, s[12:13]
	s_waitcnt vmcnt(8)
	s_waitcnt lgkmcnt(0)
	s_barrier
	s_setprio 1
	s_waitcnt lgkmcnt(0)
	v_mfma_f32_16x16x32_bf16 v[124:127], v[128:131], v[160:163], 0
	v_mfma_f32_16x16x32_bf16 v[120:123], v[132:135], v[160:163], 0
	v_mfma_f32_16x16x32_bf16 v[108:111], v[128:131], v[164:167], 0
	v_mfma_f32_16x16x32_bf16 v[104:107], v[132:135], v[164:167], 0
	v_mfma_f32_16x16x32_bf16 v[92:95], v[128:131], v[196:199], 0
	v_mfma_f32_16x16x32_bf16 v[88:91], v[132:135], v[196:199], 0
	v_mfma_f32_16x16x32_bf16 v[76:79], v[128:131], v[200:203], 0
	v_mfma_f32_16x16x32_bf16 v[72:75], v[132:135], v[200:203], 0
	v_mfma_f32_16x16x32_bf16 v[124:127], v[136:139], v[180:183], v[124:127]
	v_mfma_f32_16x16x32_bf16 v[120:123], v[140:143], v[180:183], v[120:123]
	v_mfma_f32_16x16x32_bf16 v[108:111], v[136:139], v[192:195], v[108:111]
	v_mfma_f32_16x16x32_bf16 v[104:107], v[140:143], v[192:195], v[104:107]
	v_mfma_f32_16x16x32_bf16 v[92:95], v[136:139], v[204:207], v[92:95]
	v_mfma_f32_16x16x32_bf16 v[88:91], v[140:143], v[204:207], v[88:91]
	v_mfma_f32_16x16x32_bf16 v[76:79], v[136:139], v[208:211], v[76:79]
	v_mfma_f32_16x16x32_bf16 v[72:75], v[140:143], v[208:211], v[72:75]
	s_setprio 0
	s_setprio 1
	v_mfma_f32_16x16x32_bf16 v[116:119], v[144:147], v[160:163], 0
	v_mfma_f32_16x16x32_bf16 v[112:115], v[148:151], v[160:163], 0
	v_mfma_f32_16x16x32_bf16 v[100:103], v[144:147], v[164:167], 0
	v_mfma_f32_16x16x32_bf16 v[96:99], v[148:151], v[164:167], 0
	v_mfma_f32_16x16x32_bf16 v[84:87], v[144:147], v[196:199], 0
	v_mfma_f32_16x16x32_bf16 v[80:83], v[148:151], v[196:199], 0
	v_mfma_f32_16x16x32_bf16 v[68:71], v[144:147], v[200:203], 0
	v_mfma_f32_16x16x32_bf16 v[64:67], v[148:151], v[200:203], 0
	v_mfma_f32_16x16x32_bf16 v[116:119], v[152:155], v[180:183], v[116:119]
	v_mfma_f32_16x16x32_bf16 v[112:115], v[156:159], v[180:183], v[112:115]
	v_mfma_f32_16x16x32_bf16 v[100:103], v[152:155], v[192:195], v[100:103]
	v_mfma_f32_16x16x32_bf16 v[96:99], v[156:159], v[192:195], v[96:99]
	v_mfma_f32_16x16x32_bf16 v[84:87], v[152:155], v[204:207], v[84:87]
	v_mfma_f32_16x16x32_bf16 v[80:83], v[156:159], v[204:207], v[80:83]
	v_mfma_f32_16x16x32_bf16 v[68:71], v[152:155], v[208:211], v[68:71]
	v_mfma_f32_16x16x32_bf16 v[64:67], v[156:159], v[208:211], v[64:67]
	s_setprio 0
	s_barrier
	v_mov_b32_e32 v160, v177
	s_add_u32 s60, s40, 0x80000
	s_addc_u32 s61, s41, 0
	s_nop 0
	s_nop 0
	s_nop 0
	v_xad_u32 v168, v160, 64, 0
	ds_read_b128 v[160:163], v169 offset:16384
	ds_read_b128 v[164:167], v169 offset:18432
	ds_read_b128 v[180:183], v168 offset:16384
	ds_read_b128 v[192:195], v168 offset:18432
	ds_read_b128 v[196:199], v169 offset:20480
	ds_read_b128 v[200:203], v169 offset:22528
	ds_read_b128 v[204:207], v168 offset:20480
	ds_read_b128 v[208:211], v168 offset:22528
	s_mov_b32 m0, s80
	s_nop 0
	global_load_lds_dwordx4 v173, s[40:41]
	s_mov_b32 m0, s81
	s_nop 0
	global_load_lds_dwordx4 v175, s[40:41]
	s_mov_b32 m0, s29
	s_nop 0
	global_load_lds_dwordx4 v173, s[60:61]
	s_mov_b32 m0, s88
	s_nop 0
	global_load_lds_dwordx4 v175, s[60:61]
	s_mov_b32 m0, s76
	s_nop 0
	global_load_lds_dwordx4 v172, s[44:45]
	s_mov_b32 m0, s89
	s_nop 0
	global_load_lds_dwordx4 v174, s[44:45]
	s_waitcnt vmcnt(8)
	s_waitcnt lgkmcnt(0)
	s_barrier
; #define PG8_STAGE(bufoff, gbase, voff) do { _Pragma("unroll") for (int _i = 0; _i < 2; ++_i) \
;         dma16((const char*)(gbase), (voff)[_i], ldsb + (bufoff) + ldsw + _i * 8192); } while (0)
; #define PG8_LDA(dst, b, h) do { const int a1_ = opqv(aoff0) ^ 64; _Pragma("unroll") for (int m = 0; m < 4; ++m) { dst[m][0] = *(const LAS bf16x8*)(lds + PG8_SA(b, h) + aoff0 + m * 2048); dst[m][1] = *(const LAS bf16x8*)(lds + PG8_SA(b, h) + a1_ + m * 2048); } } while (0)
; #define PG8_LDB(dst, b, h) do { const int b1_ = opqv(boff0) ^ 64; _Pragma("unroll") for (int n = 0; n < 2; ++n) { dst[n][0] = *(const LAS bf16x8*)(lds + PG8_SB(b, h) + boff0 + n * 2048); dst[n][1] = *(const LAS bf16x8*)(lds + PG8_SB(b, h) + b1_ + n * 2048); } } while (0)
; #define PG8_MMA(ai, bj, At, Bt) do { __builtin_amdgcn_s_setprio(1); _Pragma("unroll") for (int m = 0; m < 4; ++m) _Pragma("unroll") for (int n = 0; n < 2; ++n) _Pragma("unroll") for (int k = 0; k < 2; ++k) \
;         acc[ai][bj][m][n] = __builtin_amdgcn_mfma_f32_16x16x32_bf16(Bt[n][k], At[m][k], acc[ai][bj][m][n], 0, 0, 0); __builtin_amdgcn_s_setprio(0); } while (0)
; #define PG8_WAIT_V(n) asm volatile("s_waitcnt vmcnt(" #n ")" ::: "memory")
; #define PG8_WAIT_L(n) asm volatile("s_waitcnt lgkmcnt(" #n ")" ::: "memory")
; #define PG8_BAR __builtin_amdgcn_s_barrier()
; #define PG8_SCHED __builtin_amdgcn_sched_barrier(0)
; template <class Epi>
; __device__ __forceinline__ void gemm_phase(LAS unsigned char* lds, const Gemm g, const StaticOrder& S, const Epi& E, int wave_) {
;     ...
;             PG8_WAIT_V(8); PG8_WAIT_L(0); PG8_BAR; PG8_MMA(1, 0, At, B0); PG8_MMA(1, 1, At, B1); PG8_BAR; PG8_SCHED;
;             PG8_STAGE(PG8_SA(0, 1), a2 + hstepA, voffA); PG8_LDB(B0, 1, 0); PG8_LDB(B1, 1, 1); PG8_SCHED; PG8_LDA(At, 1, 0);
;             PG8_WAIT_V(8); PG8_WAIT_L(0); PG8_BAR; PG8_MMA(0, 0, At, B0); PG8_MMA(0, 1, At, B1); PG8_BAR; PG8_SCHED;
	s_setprio 1
	s_waitcnt lgkmcnt(0)
	v_mfma_f32_16x16x32_bf16 v[60:63], v[128:131], v[160:163], 0
	v_mfma_f32_16x16x32_bf16 v[56:59], v[132:135], v[160:163], 0
	v_mfma_f32_16x16x32_bf16 v[44:47], v[128:131], v[164:167], 0
	v_mfma_f32_16x16x32_bf16 v[40:43], v[132:135], v[164:167], 0
	v_mfma_f32_16x16x32_bf16 v[28:31], v[128:131], v[196:199], 0
	v_mfma_f32_16x16x32_bf16 v[24:27], v[132:135], v[196:199], 0
	v_mfma_f32_16x16x32_bf16 v[12:15], v[128:131], v[200:203], 0
	v_mfma_f32_16x16x32_bf16 v[8:11], v[132:135], v[200:203], 0
	v_mfma_f32_16x16x32_bf16 v[60:63], v[136:139], v[180:183], v[60:63]
	v_mfma_f32_16x16x32_bf16 v[56:59], v[140:143], v[180:183], v[56:59]
	v_mfma_f32_16x16x32_bf16 v[44:47], v[136:139], v[192:195], v[44:47]
	v_mfma_f32_16x16x32_bf16 v[40:43], v[140:143], v[192:195], v[40:43]
	v_mfma_f32_16x16x32_bf16 v[28:31], v[136:139], v[204:207], v[28:31]
	v_mfma_f32_16x16x32_bf16 v[24:27], v[140:143], v[204:207], v[24:27]
	v_mfma_f32_16x16x32_bf16 v[12:15], v[136:139], v[208:211], v[12:15]
	v_mfma_f32_16x16x32_bf16 v[8:11], v[140:143], v[208:211], v[8:11]
	s_setprio 0
	s_setprio 1
	v_mfma_f32_16x16x32_bf16 v[52:55], v[144:147], v[160:163], 0
	v_mfma_f32_16x16x32_bf16 v[48:51], v[148:151], v[160:163], 0
	v_mfma_f32_16x16x32_bf16 v[36:39], v[144:147], v[164:167], 0
	v_mfma_f32_16x16x32_bf16 v[32:35], v[148:151], v[164:167], 0
	v_mfma_f32_16x16x32_bf16 v[20:23], v[144:147], v[196:199], 0
	v_mfma_f32_16x16x32_bf16 v[16:19], v[148:151], v[196:199], 0
	v_mfma_f32_16x16x32_bf16 v[4:7], v[144:147], v[200:203], 0
	v_mfma_f32_16x16x32_bf16 v[0:3], v[148:151], v[200:203], 0
	v_mfma_f32_16x16x32_bf16 v[52:55], v[152:155], v[180:183], v[52:55]
	v_mfma_f32_16x16x32_bf16 v[48:51], v[156:159], v[180:183], v[48:51]
	v_mfma_f32_16x16x32_bf16 v[36:39], v[152:155], v[192:195], v[36:39]
	v_mfma_f32_16x16x32_bf16 v[32:35], v[156:159], v[192:195], v[32:35]
	v_mfma_f32_16x16x32_bf16 v[20:23], v[152:155], v[204:207], v[20:23]
	v_mfma_f32_16x16x32_bf16 v[16:19], v[156:159], v[204:207], v[16:19]
	v_mfma_f32_16x16x32_bf16 v[4:7], v[152:155], v[208:211], v[4:7]
	v_mfma_f32_16x16x32_bf16 v[0:3], v[156:159], v[208:211], v[0:3]
	s_setprio 0
	s_barrier
	s_add_u32 s44, s44, 0x80000
	s_addc_u32 s45, s45, 0
	s_mov_b32 m0, s1
	s_nop 0
	global_load_lds_dwordx4 v172, s[44:45]
	v_mov_b32_e32 v128, v178
	s_mov_b32 m0, s69
	s_nop 0
	global_load_lds_dwordx4 v174, s[44:45]
	v_add_u32_e32 v132, s34, v178
	v_xad_u32 v140, v128, 64, s34
	v_mov_b32_e32 v144, v178
	s_add_i32 s44, 0, 0x1c000
	ds_read_b128 v[128:131], v132
	ds_read_b128 v[132:135], v132 offset:2048
	ds_read_b128 v[136:139], v140
	ds_read_b128 v[140:143], v140 offset:2048
	v_add_u32_e32 v148, s44, v178
	v_xad_u32 v156, v144, 64, s44
	ds_read_b128 v[144:147], v148
	ds_read_b128 v[148:151], v148 offset:2048
	ds_read_b128 v[152:155], v156
	ds_read_b128 v[156:159], v156 offset:2048
	v_mov_b32_e32 v160, v177
	s_nop 0
	v_xad_u32 v168, v160, 64, 0
	ds_read_b128 v[160:163], v169 offset:32768
	ds_read_b128 v[164:167], v169 offset:34816
	ds_read_b128 v[180:183], v168 offset:32768
	ds_read_b128 v[192:195], v168 offset:34816
	ds_read_b128 v[196:199], v169 offset:36864
	ds_read_b128 v[200:203], v169 offset:38912
	ds_read_b128 v[204:207], v168 offset:36864
	ds_read_b128 v[208:211], v168 offset:38912
	s_waitcnt vmcnt(8)
	s_waitcnt lgkmcnt(0)
	s_barrier
	s_setprio 1
	s_waitcnt lgkmcnt(0)
	v_mfma_f32_16x16x32_bf16 v[124:127], v[128:131], v[160:163], v[124:127]
	v_mfma_f32_16x16x32_bf16 v[120:123], v[132:135], v[160:163], v[120:123]
	v_mfma_f32_16x16x32_bf16 v[108:111], v[128:131], v[164:167], v[108:111]
	v_mfma_f32_16x16x32_bf16 v[104:107], v[132:135], v[164:167], v[104:107]
	v_mfma_f32_16x16x32_bf16 v[92:95], v[128:131], v[196:199], v[92:95]
	v_mfma_f32_16x16x32_bf16 v[88:91], v[132:135], v[196:199], v[88:91]
	v_mfma_f32_16x16x32_bf16 v[76:79], v[128:131], v[200:203], v[76:79]
	v_mfma_f32_16x16x32_bf16 v[72:75], v[132:135], v[200:203], v[72:75]
	v_mfma_f32_16x16x32_bf16 v[124:127], v[136:139], v[180:183], v[124:127]
	v_mfma_f32_16x16x32_bf16 v[120:123], v[140:143], v[180:183], v[120:123]
	v_mfma_f32_16x16x32_bf16 v[108:111], v[136:139], v[192:195], v[108:111]
	v_mfma_f32_16x16x32_bf16 v[104:107], v[140:143], v[192:195], v[104:107]
	v_mfma_f32_16x16x32_bf16 v[92:95], v[136:139], v[204:207], v[92:95]
	v_mfma_f32_16x16x32_bf16 v[88:91], v[140:143], v[204:207], v[88:91]
	v_mfma_f32_16x16x32_bf16 v[76:79], v[136:139], v[208:211], v[76:79]
	v_mfma_f32_16x16x32_bf16 v[72:75], v[140:143], v[208:211], v[72:75]
	s_setprio 0
	s_setprio 1
	v_mfma_f32_16x16x32_bf16 v[116:119], v[144:147], v[160:163], v[116:119]
	s_add_u32 s44, s40, 0x80
	s_addc_u32 s45, s41, 0
	v_mfma_f32_16x16x32_bf16 v[112:115], v[148:151], v[160:163], v[112:115]
	v_mfma_f32_16x16x32_bf16 v[100:103], v[144:147], v[164:167], v[100:103]
	v_mfma_f32_16x16x32_bf16 v[96:99], v[148:151], v[164:167], v[96:99]
	v_mfma_f32_16x16x32_bf16 v[84:87], v[144:147], v[196:199], v[84:87]
	v_mfma_f32_16x16x32_bf16 v[80:83], v[148:151], v[196:199], v[80:83]
	v_mfma_f32_16x16x32_bf16 v[68:71], v[144:147], v[200:203], v[68:71]
	v_mfma_f32_16x16x32_bf16 v[64:67], v[148:151], v[200:203], v[64:67]
	v_mfma_f32_16x16x32_bf16 v[116:119], v[152:155], v[180:183], v[116:119]
	v_mfma_f32_16x16x32_bf16 v[112:115], v[156:159], v[180:183], v[112:115]
	v_mfma_f32_16x16x32_bf16 v[100:103], v[152:155], v[192:195], v[100:103]
	v_mfma_f32_16x16x32_bf16 v[96:99], v[156:159], v[192:195], v[96:99]
	v_mfma_f32_16x16x32_bf16 v[84:87], v[152:155], v[204:207], v[84:87]
	v_mfma_f32_16x16x32_bf16 v[80:83], v[156:159], v[204:207], v[80:83]
	v_mfma_f32_16x16x32_bf16 v[68:71], v[152:155], v[208:211], v[68:71]
	v_mfma_f32_16x16x32_bf16 v[64:67], v[156:159], v[208:211], v[64:67]
	s_setprio 0
	s_barrier
; #define PG8_STAGE(bufoff, gbase, voff) do { _Pragma("unroll") for (int _i = 0; _i < 2; ++_i) \
;         dma16((const char*)(gbase), (voff)[_i], ldsb + (bufoff) + ldsw + _i * 8192); } while (0)
; #define PG8_LDA(dst, b, h) do { const int a1_ = opqv(aoff0) ^ 64; _Pragma("unroll") for (int m = 0; m < 4; ++m) { dst[m][0] = *(const LAS bf16x8*)(lds + PG8_SA(b, h) + aoff0 + m * 2048); dst[m][1] = *(const LAS bf16x8*)(lds + PG8_SA(b, h) + a1_ + m * 2048); } } while (0)
; #define PG8_MMA(ai, bj, At, Bt) do { __builtin_amdgcn_s_setprio(1); _Pragma("unroll") for (int m = 0; m < 4; ++m) _Pragma("unroll") for (int n = 0; n < 2; ++n) _Pragma("unroll") for (int k = 0; k < 2; ++k) \
;         acc[ai][bj][m][n] = __builtin_amdgcn_mfma_f32_16x16x32_bf16(Bt[n][k], At[m][k], acc[ai][bj][m][n], 0, 0, 0); __builtin_amdgcn_s_setprio(0); } while (0)
; #define PG8_WAIT_V(n) asm volatile("s_waitcnt vmcnt(" #n ")" ::: "memory")
; #define PG8_WAIT_L(n) asm volatile("s_waitcnt lgkmcnt(" #n ")" ::: "memory")
; #define PG8_BAR __builtin_amdgcn_s_barrier()
; #define PG8_SCHED __builtin_amdgcn_sched_barrier(0)
; template <class Epi>
; __device__ __forceinline__ void gemm_phase(LAS unsigned char* lds, const Gemm g, const StaticOrder& S, const Epi& E, int wave_) {
;     ...
;             PG8_STAGE(PG8_SB(1, 0), b3, voffB); PG8_STAGE(PG8_SB(1, 1), b3 + hstepB, voffB); PG8_STAGE(PG8_SA(1, 0), a3, voffA); PG8_LDA(At, 1, 1);
;             PG8_WAIT_V(8); PG8_WAIT_L(0); PG8_BAR; PG8_MMA(1, 0, At, B0); PG8_MMA(1, 1, At, B1); PG8_BAR; PG8_SCHED;
	s_add_u32 s40, s40, 0x80080
	s_addc_u32 s41, s41, 0
	v_mov_b32_e32 v160, v177
	s_nop 0
	s_nop 0
	v_xad_u32 v168, v160, 64, 0
	ds_read_b128 v[160:163], v169 offset:49152
	ds_read_b128 v[164:167], v169 offset:51200
	ds_read_b128 v[180:183], v168 offset:49152
	ds_read_b128 v[192:195], v168 offset:51200
	ds_read_b128 v[196:199], v169 offset:53248
	ds_read_b128 v[200:203], v169 offset:55296
	ds_read_b128 v[204:207], v168 offset:53248
	ds_read_b128 v[208:211], v168 offset:55296
	s_mov_b32 m0, s35
	s_nop 0
	global_load_lds_dwordx4 v173, s[44:45]
	s_mov_b32 m0, s33
	s_nop 0
	global_load_lds_dwordx4 v175, s[44:45]
	s_mov_b32 m0, s77
	s_nop 0
	global_load_lds_dwordx4 v173, s[40:41]
	s_mov_b32 m0, s3
	s_nop 0
	global_load_lds_dwordx4 v175, s[40:41]
	s_mov_b32 m0, s22
	s_nop 0
	global_load_lds_dwordx4 v172, s[36:37]
	s_mov_b32 m0, s2
	s_nop 0
	global_load_lds_dwordx4 v174, s[36:37]
	s_waitcnt vmcnt(8)
	s_waitcnt lgkmcnt(0)
	s_barrier
	s_setprio 1
	s_waitcnt lgkmcnt(0)
	v_mfma_f32_16x16x32_bf16 v[60:63], v[128:131], v[160:163], v[60:63]
	v_mfma_f32_16x16x32_bf16 v[56:59], v[132:135], v[160:163], v[56:59]
	v_mfma_f32_16x16x32_bf16 v[44:47], v[128:131], v[164:167], v[44:47]
	v_mfma_f32_16x16x32_bf16 v[40:43], v[132:135], v[164:167], v[40:43]
	v_mfma_f32_16x16x32_bf16 v[28:31], v[128:131], v[196:199], v[28:31]
	v_mfma_f32_16x16x32_bf16 v[24:27], v[132:135], v[196:199], v[24:27]
	v_mfma_f32_16x16x32_bf16 v[12:15], v[128:131], v[200:203], v[12:15]
	v_mfma_f32_16x16x32_bf16 v[8:11], v[132:135], v[200:203], v[8:11]
	v_mfma_f32_16x16x32_bf16 v[60:63], v[136:139], v[180:183], v[60:63]
	v_mfma_f32_16x16x32_bf16 v[56:59], v[140:143], v[180:183], v[56:59]
	v_mfma_f32_16x16x32_bf16 v[44:47], v[136:139], v[192:195], v[44:47]
	v_mfma_f32_16x16x32_bf16 v[40:43], v[140:143], v[192:195], v[40:43]
	v_mfma_f32_16x16x32_bf16 v[28:31], v[136:139], v[204:207], v[28:31]
	v_mfma_f32_16x16x32_bf16 v[24:27], v[140:143], v[204:207], v[24:27]
	v_mfma_f32_16x16x32_bf16 v[12:15], v[136:139], v[208:211], v[12:15]
	v_mfma_f32_16x16x32_bf16 v[8:11], v[140:143], v[208:211], v[8:11]
	s_setprio 0
	s_setprio 1
	v_mfma_f32_16x16x32_bf16 v[52:55], v[144:147], v[160:163], v[52:55]
	v_mfma_f32_16x16x32_bf16 v[48:51], v[148:151], v[160:163], v[48:51]
	v_mfma_f32_16x16x32_bf16 v[36:39], v[144:147], v[164:167], v[36:39]
	v_mfma_f32_16x16x32_bf16 v[32:35], v[148:151], v[164:167], v[32:35]
	v_mfma_f32_16x16x32_bf16 v[20:23], v[144:147], v[196:199], v[20:23]
	v_mfma_f32_16x16x32_bf16 v[16:19], v[148:151], v[196:199], v[16:19]
	v_mfma_f32_16x16x32_bf16 v[4:7], v[144:147], v[200:203], v[4:7]
	v_mfma_f32_16x16x32_bf16 v[0:3], v[148:151], v[200:203], v[0:3]
	v_mfma_f32_16x16x32_bf16 v[52:55], v[152:155], v[180:183], v[52:55]
	v_mfma_f32_16x16x32_bf16 v[48:51], v[156:159], v[180:183], v[48:51]
	v_mfma_f32_16x16x32_bf16 v[36:39], v[152:155], v[192:195], v[36:39]
	v_mfma_f32_16x16x32_bf16 v[32:35], v[156:159], v[192:195], v[32:35]
	v_mfma_f32_16x16x32_bf16 v[20:23], v[152:155], v[204:207], v[20:23]
	v_mfma_f32_16x16x32_bf16 v[16:19], v[156:159], v[204:207], v[16:19]
	v_mfma_f32_16x16x32_bf16 v[4:7], v[152:155], v[208:211], v[4:7]
	v_mfma_f32_16x16x32_bf16 v[0:3], v[156:159], v[208:211], v[0:3]
	s_setprio 0
	s_barrier
	s_add_i32 s57, s57, 2
	s_add_u32 s55, s55, 0x100
	s_addc_u32 s56, s56, 0
	s_add_u32 s12, s12, 0x100
	s_addc_u32 s13, s13, 0
	s_cmp_gt_u32 s57, 29
	s_cbranch_scc0 .LBB0_1322
	s_branch .Lpeel_exit_3

; #define PG8_STAGE(bufoff, gbase, voff) do { _Pragma("unroll") for (int _i = 0; _i < 2; ++_i) \
;         dma16((const char*)(gbase), (voff)[_i], ldsb + (bufoff) + ldsw + _i * 8192); } while (0)
; #define PG8_LDA(dst, b, h) do { const int a1_ = opqv(aoff0) ^ 64; _Pragma("unroll") for (int m = 0; m < 4; ++m) { dst[m][0] = *(const LAS bf16x8*)(lds + PG8_SA(b, h) + aoff0 + m * 2048); dst[m][1] = *(const LAS bf16x8*)(lds + PG8_SA(b, h) + a1_ + m * 2048); } } while (0)
; #define PG8_LDB(dst, b, h) do { const int b1_ = opqv(boff0) ^ 64; _Pragma("unroll") for (int n = 0; n < 2; ++n) { dst[n][0] = *(const LAS bf16x8*)(lds + PG8_SB(b, h) + boff0 + n * 2048); dst[n][1] = *(const LAS bf16x8*)(lds + PG8_SB(b, h) + b1_ + n * 2048); } } while (0)
; #define PG8_MMA(ai, bj, At, Bt) do { __builtin_amdgcn_s_setprio(1); _Pragma("unroll") for (int m = 0; m < 4; ++m) _Pragma("unroll") for (int n = 0; n < 2; ++n) _Pragma("unroll") for (int k = 0; k < 2; ++k) \
;         acc[ai][bj][m][n] = __builtin_amdgcn_mfma_f32_16x16x32_bf16(Bt[n][k], At[m][k], acc[ai][bj][m][n], 0, 0, 0); __builtin_amdgcn_s_setprio(0); } while (0)
; #define PG8_WAIT_V(n) asm volatile("s_waitcnt vmcnt(" #n ")" ::: "memory")
; #define PG8_WAIT_L(n) asm volatile("s_waitcnt lgkmcnt(" #n ")" ::: "memory")
; template <class Epi>
; __device__ __forceinline__ void gemm_phase(LAS unsigned char* lds, const Gemm g, const StaticOrder& S, const Epi& E, int wave_) {
;     ...
;             const char* a1 = cA + (size_t)(t + 1) * kstep;
;             const char* a2 = last ? nA : cA + (size_t)(t + 2) * kstep; const char* b2 = last ? nB : cB + (size_t)(t + 2) * kstep;
;             const char* a3 = a2 + kstep; const char* b3 = b2 + kstep;
;             PG8_STAGE(PG8_SA(1, 1), a1 + hstepA, voffA); PG8_LDB(B0, 0, 0); PG8_LDB(B1, 0, 1); PG8_SCHED; PG8_LDA(At, 0, 0);
;             PG8_WAIT_V(8); PG8_WAIT_L(0); PG8_BAR; PG8_MMA(0, 0, At, B0); PG8_MMA(0, 1, At, B1); PG8_BAR; PG8_SCHED;
;             PG8_STAGE(PG8_SB(0, 0), b2, voffB); PG8_STAGE(PG8_SB(0, 1), b2 + hstepB, voffB); PG8_STAGE(PG8_SA(0, 0), a2, voffA); PG8_LDA(At, 0, 1);
;     ...
;         for (int a = 0; a < 2; ++a)
; #pragma unroll
;             for (int b = 0; b < 2; ++b)
; #pragma unroll
;                 for (int m = 0; m < 4; ++m)
; #pragma unroll
;                     for (int n = 0; n < 2; ++n) acc[a][b][m][n] = (f32x4){0.f, 0.f, 0.f, 0.f};
.LBB0_1341:
	s_ashr_i32 s9, s8, 31
	s_lshl_b64 s[10:11], s[8:9], 17
	s_add_u32 s10, s16, s10
	s_addc_u32 s11, s17, s11
	s_and_b64 s[12:13], s[42:43], exec
	s_cselect_b32 s9, s11, s27
	s_cselect_b32 s61, s10, s26
	s_ashr_i32 s7, s6, 31
	s_lshl_b64 s[12:13], s[6:7], 17
	s_add_u32 s18, s21, s12
	s_addc_u32 s19, s52, s13
	s_and_b64 s[12:13], s[42:43], exec
	s_cselect_b32 s7, s19, s25
	s_cselect_b32 s62, s18, s24
	s_mov_b64 s[30:31], 0
	s_mov_b64 s[12:13], -1
	s_mov_b64 s[36:37], 0
	s_add_u32 s46, s26, s30
	s_addc_u32 s47, s27, s31
	s_add_u32 s44, s46, 0x100
	s_addc_u32 s45, s47, 0
	s_and_b64 s[40:41], s[36:37], exec
	s_cselect_b32 s45, s9, s45
	s_cselect_b32 s44, s61, s44
	s_add_u32 s30, s24, s30
	s_addc_u32 s31, s25, s31
	s_add_u32 s40, s30, 0x100
	s_addc_u32 s41, s31, 0
	s_add_u32 s30, s44, 0x80
	s_addc_u32 s31, s45, 0
	s_add_u32 s56, s46, 0x10080
	s_addc_u32 s57, s47, 0
	s_mov_b32 m0, s14
	s_nop 0
	global_load_lds_dwordx4 v130, s[56:57]
	v_mov_b32_e32 v128, v136
	s_mov_b32 m0, s15
	s_nop 0
	global_load_lds_dwordx4 v132, s[56:57]
	s_and_b64 s[36:37], s[36:37], exec
	v_xad_u32 v128, v128, 64, s23
	v_add_u32_e32 v129, s23, v136
	s_cselect_b32 s49, s7, s41
	s_cselect_b32 s48, s62, s40
	s_add_i32 s37, 0, 0x14000
	ds_read_b128 v[138:141], v129
	ds_read_b128 v[142:145], v129 offset:2048
	ds_read_b128 v[146:149], v128
	ds_read_b128 v[150:153], v128 offset:2048
	v_mov_b32_e32 v128, v136
	v_add_u32_e32 v129, s37, v136
	s_add_u32 s46, s48, 0x10000
	v_xad_u32 v128, v128, 64, s37
	ds_read_b128 v[154:157], v129
	ds_read_b128 v[158:161], v129 offset:2048
	ds_read_b128 v[162:165], v128
	ds_read_b128 v[166:169], v128 offset:2048
	s_addc_u32 s47, s49, 0
	s_add_u32 s40, s44, 0x10000
	s_addc_u32 s41, s45, 0
	s_add_i32 s63, 0, 0x1c000
	s_add_u32 s36, s48, 0x80
	s_addc_u32 s37, s49, 0
	s_add_u32 s56, s48, 0x10080
	s_addc_u32 s57, s49, 0
	v_mov_b32_e32 v128, v135
	v_add_u32_e32 v129, 0, v135
	v_xad_u32 v128, v128, 64, 0
	ds_read_b128 v[172:175], v129
	ds_read_b128 v[176:179], v129 offset:2048
	ds_read_b128 v[180:183], v128
	ds_read_b128 v[192:195], v128 offset:2048
	ds_read_b128 v[196:199], v129 offset:4096
	ds_read_b128 v[200:203], v129 offset:6144
	ds_read_b128 v[204:207], v128 offset:4096
	ds_read_b128 v[208:211], v128 offset:6144
	s_waitcnt vmcnt(8)
	s_waitcnt lgkmcnt(0)
	s_barrier
	s_setprio 1
	s_waitcnt lgkmcnt(0)
	v_mfma_f32_16x16x32_bf16 v[124:127], v[138:141], v[172:175], 0
	v_mfma_f32_16x16x32_bf16 v[120:123], v[142:145], v[172:175], 0
	v_mfma_f32_16x16x32_bf16 v[116:119], v[138:141], v[176:179], 0
	v_mfma_f32_16x16x32_bf16 v[108:111], v[142:145], v[176:179], 0
	v_mfma_f32_16x16x32_bf16 v[100:103], v[138:141], v[196:199], 0
	v_mfma_f32_16x16x32_bf16 v[92:95], v[142:145], v[196:199], 0
	v_mfma_f32_16x16x32_bf16 v[84:87], v[138:141], v[200:203], 0
	v_mfma_f32_16x16x32_bf16 v[76:79], v[142:145], v[200:203], 0
	v_mfma_f32_16x16x32_bf16 v[124:127], v[146:149], v[180:183], v[124:127]
	v_mfma_f32_16x16x32_bf16 v[120:123], v[150:153], v[180:183], v[120:123]
	v_mfma_f32_16x16x32_bf16 v[116:119], v[146:149], v[192:195], v[116:119]
	v_mfma_f32_16x16x32_bf16 v[108:111], v[150:153], v[192:195], v[108:111]
	v_mfma_f32_16x16x32_bf16 v[100:103], v[146:149], v[204:207], v[100:103]
	v_mfma_f32_16x16x32_bf16 v[92:95], v[150:153], v[204:207], v[92:95]
	v_mfma_f32_16x16x32_bf16 v[84:87], v[146:149], v[208:211], v[84:87]
	v_mfma_f32_16x16x32_bf16 v[76:79], v[150:153], v[208:211], v[76:79]
	s_setprio 0
	s_setprio 1
	v_mfma_f32_16x16x32_bf16 v[112:115], v[154:157], v[172:175], 0
	v_mfma_f32_16x16x32_bf16 v[104:107], v[158:161], v[172:175], 0
	v_mfma_f32_16x16x32_bf16 v[96:99], v[154:157], v[176:179], 0
	v_mfma_f32_16x16x32_bf16 v[88:91], v[158:161], v[176:179], 0
	v_mfma_f32_16x16x32_bf16 v[80:83], v[154:157], v[196:199], 0
	v_mfma_f32_16x16x32_bf16 v[72:75], v[158:161], v[196:199], 0
	v_mfma_f32_16x16x32_bf16 v[68:71], v[154:157], v[200:203], 0
	v_mfma_f32_16x16x32_bf16 v[64:67], v[158:161], v[200:203], 0
	v_mfma_f32_16x16x32_bf16 v[112:115], v[162:165], v[180:183], v[112:115]
	v_mfma_f32_16x16x32_bf16 v[104:107], v[166:169], v[180:183], v[104:107]
	v_mfma_f32_16x16x32_bf16 v[96:99], v[162:165], v[192:195], v[96:99]
	v_mfma_f32_16x16x32_bf16 v[88:91], v[166:169], v[192:195], v[88:91]
	v_mfma_f32_16x16x32_bf16 v[80:83], v[162:165], v[204:207], v[80:83]
	v_mfma_f32_16x16x32_bf16 v[72:75], v[166:169], v[204:207], v[72:75]
	v_mfma_f32_16x16x32_bf16 v[68:71], v[162:165], v[208:211], v[68:71]
	v_mfma_f32_16x16x32_bf16 v[64:67], v[166:169], v[208:211], v[64:67]
	s_setprio 0
	s_barrier
	v_mov_b32_e32 v128, v135
	s_nop 0
	s_nop 0
	s_nop 0
	v_xad_u32 v128, v128, 64, 0
	ds_read_b128 v[172:175], v129 offset:16384
	ds_read_b128 v[176:179], v129 offset:18432
	ds_read_b128 v[180:183], v128 offset:16384
	ds_read_b128 v[192:195], v128 offset:18432
	ds_read_b128 v[196:199], v129 offset:20480
	ds_read_b128 v[200:203], v129 offset:22528
	ds_read_b128 v[204:207], v128 offset:20480
	ds_read_b128 v[208:211], v128 offset:22528
	s_mov_b32 m0, s80
	s_nop 0
	global_load_lds_dwordx4 v131, s[48:49]
	s_mov_b32 m0, s81
	s_nop 0
	global_load_lds_dwordx4 v133, s[48:49]
	s_mov_b32 m0, s29
	s_nop 0
	global_load_lds_dwordx4 v131, s[46:47]
	s_mov_b32 m0, s88
	s_nop 0
	global_load_lds_dwordx4 v133, s[46:47]
	s_mov_b32 m0, s76
	s_nop 0
	global_load_lds_dwordx4 v130, s[44:45]
	s_mov_b32 m0, s89
	s_nop 0
	global_load_lds_dwordx4 v132, s[44:45]
	s_waitcnt vmcnt(8)
	s_waitcnt lgkmcnt(0)
	s_barrier
; #define PG8_STAGE(bufoff, gbase, voff) do { _Pragma("unroll") for (int _i = 0; _i < 2; ++_i) \
;         dma16((const char*)(gbase), (voff)[_i], ldsb + (bufoff) + ldsw + _i * 8192); } while (0)
; #define PG8_LDA(dst, b, h) do { const int a1_ = opqv(aoff0) ^ 64; _Pragma("unroll") for (int m = 0; m < 4; ++m) { dst[m][0] = *(const LAS bf16x8*)(lds + PG8_SA(b, h) + aoff0 + m * 2048); dst[m][1] = *(const LAS bf16x8*)(lds + PG8_SA(b, h) + a1_ + m * 2048); } } while (0)
; #define PG8_LDB(dst, b, h) do { const int b1_ = opqv(boff0) ^ 64; _Pragma("unroll") for (int n = 0; n < 2; ++n) { dst[n][0] = *(const LAS bf16x8*)(lds + PG8_SB(b, h) + boff0 + n * 2048); dst[n][1] = *(const LAS bf16x8*)(lds + PG8_SB(b, h) + b1_ + n * 2048); } } while (0)
; #define PG8_MMA(ai, bj, At, Bt) do { __builtin_amdgcn_s_setprio(1); _Pragma("unroll") for (int m = 0; m < 4; ++m) _Pragma("unroll") for (int n = 0; n < 2; ++n) _Pragma("unroll") for (int k = 0; k < 2; ++k) \
;         acc[ai][bj][m][n] = __builtin_amdgcn_mfma_f32_16x16x32_bf16(Bt[n][k], At[m][k], acc[ai][bj][m][n], 0, 0, 0); __builtin_amdgcn_s_setprio(0); } while (0)
; #define PG8_WAIT_V(n) asm volatile("s_waitcnt vmcnt(" #n ")" ::: "memory")
; #define PG8_WAIT_L(n) asm volatile("s_waitcnt lgkmcnt(" #n ")" ::: "memory")
; #define PG8_BAR __builtin_amdgcn_s_barrier()
; #define PG8_SCHED __builtin_amdgcn_sched_barrier(0)
; template <class Epi>
; __device__ __forceinline__ void gemm_phase(LAS unsigned char* lds, const Gemm g, const StaticOrder& S, const Epi& E, int wave_) {
;     ...
;             PG8_WAIT_V(8); PG8_WAIT_L(0); PG8_BAR; PG8_MMA(1, 0, At, B0); PG8_MMA(1, 1, At, B1); PG8_BAR; PG8_SCHED;
;             PG8_STAGE(PG8_SA(0, 1), a2 + hstepA, voffA); PG8_LDB(B0, 1, 0); PG8_LDB(B1, 1, 1); PG8_SCHED; PG8_LDA(At, 1, 0);
;             PG8_WAIT_V(8); PG8_WAIT_L(0); PG8_BAR; PG8_MMA(0, 0, At, B0); PG8_MMA(0, 1, At, B1); PG8_BAR; PG8_SCHED;
	s_setprio 1
	s_waitcnt lgkmcnt(0)
	v_mfma_f32_16x16x32_bf16 v[60:63], v[138:141], v[172:175], 0
	v_mfma_f32_16x16x32_bf16 v[56:59], v[142:145], v[172:175], 0
	v_mfma_f32_16x16x32_bf16 v[52:55], v[138:141], v[176:179], 0
	v_mfma_f32_16x16x32_bf16 v[44:47], v[142:145], v[176:179], 0
	v_mfma_f32_16x16x32_bf16 v[36:39], v[138:141], v[196:199], 0
	v_mfma_f32_16x16x32_bf16 v[28:31], v[142:145], v[196:199], 0
	v_mfma_f32_16x16x32_bf16 v[20:23], v[138:141], v[200:203], 0
	v_mfma_f32_16x16x32_bf16 v[12:15], v[142:145], v[200:203], 0
	v_mfma_f32_16x16x32_bf16 v[60:63], v[146:149], v[180:183], v[60:63]
	v_mfma_f32_16x16x32_bf16 v[56:59], v[150:153], v[180:183], v[56:59]
	v_mfma_f32_16x16x32_bf16 v[52:55], v[146:149], v[192:195], v[52:55]
	v_mfma_f32_16x16x32_bf16 v[44:47], v[150:153], v[192:195], v[44:47]
	v_mfma_f32_16x16x32_bf16 v[36:39], v[146:149], v[204:207], v[36:39]
	v_mfma_f32_16x16x32_bf16 v[28:31], v[150:153], v[204:207], v[28:31]
	v_mfma_f32_16x16x32_bf16 v[20:23], v[146:149], v[208:211], v[20:23]
	v_mfma_f32_16x16x32_bf16 v[12:15], v[150:153], v[208:211], v[12:15]
	s_setprio 0
	s_setprio 1
	v_mfma_f32_16x16x32_bf16 v[48:51], v[154:157], v[172:175], 0
	v_mfma_f32_16x16x32_bf16 v[40:43], v[158:161], v[172:175], 0
	v_mfma_f32_16x16x32_bf16 v[32:35], v[154:157], v[176:179], 0
	v_mfma_f32_16x16x32_bf16 v[24:27], v[158:161], v[176:179], 0
	v_mfma_f32_16x16x32_bf16 v[16:19], v[154:157], v[196:199], 0
	v_mfma_f32_16x16x32_bf16 v[8:11], v[158:161], v[196:199], 0
	v_mfma_f32_16x16x32_bf16 v[4:7], v[154:157], v[200:203], 0
	v_mfma_f32_16x16x32_bf16 v[0:3], v[158:161], v[200:203], 0
	v_mfma_f32_16x16x32_bf16 v[48:51], v[162:165], v[180:183], v[48:51]
	v_mfma_f32_16x16x32_bf16 v[40:43], v[166:169], v[180:183], v[40:43]
	v_mfma_f32_16x16x32_bf16 v[32:35], v[162:165], v[192:195], v[32:35]
	v_mfma_f32_16x16x32_bf16 v[24:27], v[166:169], v[192:195], v[24:27]
	v_mfma_f32_16x16x32_bf16 v[16:19], v[162:165], v[204:207], v[16:19]
	v_mfma_f32_16x16x32_bf16 v[8:11], v[166:169], v[204:207], v[8:11]
	v_mfma_f32_16x16x32_bf16 v[4:7], v[162:165], v[208:211], v[4:7]
	v_mfma_f32_16x16x32_bf16 v[0:3], v[166:169], v[208:211], v[0:3]
	s_setprio 0
	s_barrier
	v_mov_b32_e32 v128, v136
	v_add_u32_e32 v142, s34, v136
	v_xad_u32 v128, v128, 64, s34
	ds_read_b128 v[138:141], v142
	ds_read_b128 v[142:145], v142 offset:2048
	ds_read_b128 v[146:149], v128
	ds_read_b128 v[150:153], v128 offset:2048
	v_mov_b32_e32 v128, v136
	v_add_u32_e32 v158, s63, v136
	v_xad_u32 v128, v128, 64, s63
	ds_read_b128 v[154:157], v158
	ds_read_b128 v[158:161], v158 offset:2048
	ds_read_b128 v[162:165], v128
	ds_read_b128 v[166:169], v128 offset:2048
	v_mov_b32_e32 v128, v135
	s_nop 0
	v_xad_u32 v128, v128, 64, 0
	ds_read_b128 v[172:175], v129 offset:32768
	ds_read_b128 v[176:179], v129 offset:34816
	ds_read_b128 v[180:183], v128 offset:32768
	ds_read_b128 v[192:195], v128 offset:34816
	ds_read_b128 v[196:199], v129 offset:36864
	ds_read_b128 v[200:203], v129 offset:38912
	ds_read_b128 v[204:207], v128 offset:36864
	ds_read_b128 v[208:211], v128 offset:38912
	s_mov_b32 m0, s1
	s_nop 0
	global_load_lds_dwordx4 v130, s[40:41]
	s_mov_b32 m0, s69
	s_nop 0
	global_load_lds_dwordx4 v132, s[40:41]
	s_waitcnt vmcnt(8)
	s_waitcnt lgkmcnt(0)
	s_barrier
	s_setprio 1
	s_waitcnt lgkmcnt(0)
	v_mfma_f32_16x16x32_bf16 v[124:127], v[138:141], v[172:175], v[124:127]
	v_mfma_f32_16x16x32_bf16 v[120:123], v[142:145], v[172:175], v[120:123]
	v_mfma_f32_16x16x32_bf16 v[116:119], v[138:141], v[176:179], v[116:119]
	v_mfma_f32_16x16x32_bf16 v[108:111], v[142:145], v[176:179], v[108:111]
	v_mfma_f32_16x16x32_bf16 v[100:103], v[138:141], v[196:199], v[100:103]
	v_mfma_f32_16x16x32_bf16 v[92:95], v[142:145], v[196:199], v[92:95]
	v_mfma_f32_16x16x32_bf16 v[84:87], v[138:141], v[200:203], v[84:87]
	v_mfma_f32_16x16x32_bf16 v[76:79], v[142:145], v[200:203], v[76:79]
	v_mfma_f32_16x16x32_bf16 v[124:127], v[146:149], v[180:183], v[124:127]
	v_mfma_f32_16x16x32_bf16 v[120:123], v[150:153], v[180:183], v[120:123]
	v_mfma_f32_16x16x32_bf16 v[116:119], v[146:149], v[192:195], v[116:119]
	v_mfma_f32_16x16x32_bf16 v[108:111], v[150:153], v[192:195], v[108:111]
	v_mfma_f32_16x16x32_bf16 v[100:103], v[146:149], v[204:207], v[100:103]
	v_mfma_f32_16x16x32_bf16 v[92:95], v[150:153], v[204:207], v[92:95]
	v_mfma_f32_16x16x32_bf16 v[84:87], v[146:149], v[208:211], v[84:87]
	v_mfma_f32_16x16x32_bf16 v[76:79], v[150:153], v[208:211], v[76:79]
	s_setprio 0
	s_setprio 1
	v_mfma_f32_16x16x32_bf16 v[112:115], v[154:157], v[172:175], v[112:115]
	v_mfma_f32_16x16x32_bf16 v[104:107], v[158:161], v[172:175], v[104:107]
	v_mfma_f32_16x16x32_bf16 v[96:99], v[154:157], v[176:179], v[96:99]
	v_mfma_f32_16x16x32_bf16 v[88:91], v[158:161], v[176:179], v[88:91]
	v_mfma_f32_16x16x32_bf16 v[80:83], v[154:157], v[196:199], v[80:83]
	v_mfma_f32_16x16x32_bf16 v[72:75], v[158:161], v[196:199], v[72:75]
	v_mfma_f32_16x16x32_bf16 v[68:71], v[154:157], v[200:203], v[68:71]
	v_mfma_f32_16x16x32_bf16 v[64:67], v[158:161], v[200:203], v[64:67]
	v_mfma_f32_16x16x32_bf16 v[112:115], v[162:165], v[180:183], v[112:115]
	v_mfma_f32_16x16x32_bf16 v[104:107], v[166:169], v[180:183], v[104:107]
	v_mfma_f32_16x16x32_bf16 v[96:99], v[162:165], v[192:195], v[96:99]
	v_mfma_f32_16x16x32_bf16 v[88:91], v[166:169], v[192:195], v[88:91]
	v_mfma_f32_16x16x32_bf16 v[80:83], v[162:165], v[204:207], v[80:83]
	v_mfma_f32_16x16x32_bf16 v[72:75], v[166:169], v[204:207], v[72:75]
	v_mfma_f32_16x16x32_bf16 v[68:71], v[162:165], v[208:211], v[68:71]
	v_mfma_f32_16x16x32_bf16 v[64:67], v[166:169], v[208:211], v[64:67]
	s_setprio 0
	s_barrier
; #define PG8_STAGE(bufoff, gbase, voff) do { _Pragma("unroll") for (int _i = 0; _i < 2; ++_i) \
;         dma16((const char*)(gbase), (voff)[_i], ldsb + (bufoff) + ldsw + _i * 8192); } while (0)
; #define PG8_LDA(dst, b, h) do { const int a1_ = opqv(aoff0) ^ 64; _Pragma("unroll") for (int m = 0; m < 4; ++m) { dst[m][0] = *(const LAS bf16x8*)(lds + PG8_SA(b, h) + aoff0 + m * 2048); dst[m][1] = *(const LAS bf16x8*)(lds + PG8_SA(b, h) + a1_ + m * 2048); } } while (0)
; #define PG8_MMA(ai, bj, At, Bt) do { __builtin_amdgcn_s_setprio(1); _Pragma("unroll") for (int m = 0; m < 4; ++m) _Pragma("unroll") for (int n = 0; n < 2; ++n) _Pragma("unroll") for (int k = 0; k < 2; ++k) \
;         acc[ai][bj][m][n] = __builtin_amdgcn_mfma_f32_16x16x32_bf16(Bt[n][k], At[m][k], acc[ai][bj][m][n], 0, 0, 0); __builtin_amdgcn_s_setprio(0); } while (0)
; #define PG8_WAIT_V(n) asm volatile("s_waitcnt vmcnt(" #n ")" ::: "memory")
; #define PG8_WAIT_L(n) asm volatile("s_waitcnt lgkmcnt(" #n ")" ::: "memory")
; #define PG8_BAR __builtin_amdgcn_s_barrier()
; #define PG8_SCHED __builtin_amdgcn_sched_barrier(0)
; template <class Epi>
; __device__ __forceinline__ void gemm_phase(LAS unsigned char* lds, const Gemm g, const StaticOrder& S, const Epi& E, int wave_) {
;     ...
;             PG8_STAGE(PG8_SB(1, 0), b3, voffB); PG8_STAGE(PG8_SB(1, 1), b3 + hstepB, voffB); PG8_STAGE(PG8_SA(1, 0), a3, voffA); PG8_LDA(At, 1, 1);
;             PG8_WAIT_V(8); PG8_WAIT_L(0); PG8_BAR; PG8_MMA(1, 0, At, B0); PG8_MMA(1, 1, At, B1); PG8_BAR; PG8_SCHED;
	v_mov_b32_e32 v128, v135
	s_nop 0
	s_nop 0
	s_nop 0
	s_nop 0
	v_xad_u32 v128, v128, 64, 0
	ds_read_b128 v[172:175], v129 offset:49152
	ds_read_b128 v[176:179], v129 offset:51200
	ds_read_b128 v[180:183], v128 offset:49152
	ds_read_b128 v[192:195], v128 offset:51200
	ds_read_b128 v[196:199], v129 offset:53248
	ds_read_b128 v[200:203], v129 offset:55296
	ds_read_b128 v[204:207], v128 offset:53248
	ds_read_b128 v[208:211], v128 offset:55296
	s_mov_b32 m0, s35
	s_nop 0
	global_load_lds_dwordx4 v131, s[36:37]
	s_mov_b32 m0, s33
	s_nop 0
	global_load_lds_dwordx4 v133, s[36:37]
	s_mov_b32 m0, s77
	s_nop 0
	global_load_lds_dwordx4 v131, s[56:57]
	s_mov_b32 m0, s3
	s_nop 0
	global_load_lds_dwordx4 v133, s[56:57]
	s_mov_b32 m0, s22
	s_nop 0
	global_load_lds_dwordx4 v130, s[30:31]
	s_mov_b32 m0, s2
	s_nop 0
	global_load_lds_dwordx4 v132, s[30:31]
	s_waitcnt vmcnt(8)
	s_waitcnt lgkmcnt(0)
	s_barrier
	s_setprio 1
	s_waitcnt lgkmcnt(0)
	v_mfma_f32_16x16x32_bf16 v[60:63], v[138:141], v[172:175], v[60:63]
	v_mfma_f32_16x16x32_bf16 v[56:59], v[142:145], v[172:175], v[56:59]
	v_mfma_f32_16x16x32_bf16 v[52:55], v[138:141], v[176:179], v[52:55]
	v_mfma_f32_16x16x32_bf16 v[44:47], v[142:145], v[176:179], v[44:47]
	v_mfma_f32_16x16x32_bf16 v[36:39], v[138:141], v[196:199], v[36:39]
	v_mfma_f32_16x16x32_bf16 v[28:31], v[142:145], v[196:199], v[28:31]
	v_mfma_f32_16x16x32_bf16 v[20:23], v[138:141], v[200:203], v[20:23]
	v_mfma_f32_16x16x32_bf16 v[12:15], v[142:145], v[200:203], v[12:15]
	v_mfma_f32_16x16x32_bf16 v[60:63], v[146:149], v[180:183], v[60:63]
	v_mfma_f32_16x16x32_bf16 v[56:59], v[150:153], v[180:183], v[56:59]
	v_mfma_f32_16x16x32_bf16 v[52:55], v[146:149], v[192:195], v[52:55]
	v_mfma_f32_16x16x32_bf16 v[44:47], v[150:153], v[192:195], v[44:47]
	v_mfma_f32_16x16x32_bf16 v[36:39], v[146:149], v[204:207], v[36:39]
	v_mfma_f32_16x16x32_bf16 v[28:31], v[150:153], v[204:207], v[28:31]
	v_mfma_f32_16x16x32_bf16 v[20:23], v[146:149], v[208:211], v[20:23]
	v_mfma_f32_16x16x32_bf16 v[12:15], v[150:153], v[208:211], v[12:15]
	s_setprio 0
	s_setprio 1
	v_mfma_f32_16x16x32_bf16 v[48:51], v[154:157], v[172:175], v[48:51]
	v_mfma_f32_16x16x32_bf16 v[40:43], v[158:161], v[172:175], v[40:43]
	v_mfma_f32_16x16x32_bf16 v[32:35], v[154:157], v[176:179], v[32:35]
	v_mfma_f32_16x16x32_bf16 v[24:27], v[158:161], v[176:179], v[24:27]
	v_mfma_f32_16x16x32_bf16 v[16:19], v[154:157], v[196:199], v[16:19]
	v_mfma_f32_16x16x32_bf16 v[8:11], v[158:161], v[196:199], v[8:11]
	v_mfma_f32_16x16x32_bf16 v[4:7], v[154:157], v[200:203], v[4:7]
	v_mfma_f32_16x16x32_bf16 v[0:3], v[158:161], v[200:203], v[0:3]
	v_mfma_f32_16x16x32_bf16 v[48:51], v[162:165], v[180:183], v[48:51]
	v_mfma_f32_16x16x32_bf16 v[40:43], v[166:169], v[180:183], v[40:43]
	v_mfma_f32_16x16x32_bf16 v[32:35], v[162:165], v[192:195], v[32:35]
	v_mfma_f32_16x16x32_bf16 v[24:27], v[166:169], v[192:195], v[24:27]
	v_mfma_f32_16x16x32_bf16 v[16:19], v[162:165], v[204:207], v[16:19]
	v_mfma_f32_16x16x32_bf16 v[8:11], v[166:169], v[204:207], v[8:11]
	v_mfma_f32_16x16x32_bf16 v[4:7], v[162:165], v[208:211], v[4:7]
	v_mfma_f32_16x16x32_bf16 v[0:3], v[166:169], v[208:211], v[0:3]
	s_setprio 0
	s_barrier
	s_andn2_b64 vcc, exec, s[12:13]
	s_mov_b64 s[36:37], -1
	s_mov_b64 s[12:13], 0
	s_mov_b64 s[30:31], 0x100
	s_cbranch_vccz .LBB0_1342
	s_branch .Lpeel_exit_2

; #define PG8_BAR __builtin_amdgcn_s_barrier()
; template <class Epi>
; __device__ __forceinline__ void gemm_phase(LAS unsigned char* lds, const Gemm g, const StaticOrder& S, const Epi& E, int wave_) {
;     ...
;         if (wr == 0) PG8_BAR;
.Lpeel_exit_2:
	v_readlane_b32 s12, v253, 13
	v_readlane_b32 s13, v253, 14
	s_and_b64 vcc, exec, s[12:13]
	v_readlane_b32 s61, v255, 16
	s_cbranch_vccz .LBB0_1345
	s_barrier

; #define PG8_STAGE(bufoff, gbase, voff) do { _Pragma("unroll") for (int _i = 0; _i < 2; ++_i) \
;         dma16((const char*)(gbase), (voff)[_i], ldsb + (bufoff) + ldsw + _i * 8192); } while (0)
; #define PG8_LDA(dst, b, h) do { const int a1_ = opqv(aoff0) ^ 64; _Pragma("unroll") for (int m = 0; m < 4; ++m) { dst[m][0] = *(const LAS bf16x8*)(lds + PG8_SA(b, h) + aoff0 + m * 2048); dst[m][1] = *(const LAS bf16x8*)(lds + PG8_SA(b, h) + a1_ + m * 2048); } } while (0)
; #define PG8_LDB(dst, b, h) do { const int b1_ = opqv(boff0) ^ 64; _Pragma("unroll") for (int n = 0; n < 2; ++n) { dst[n][0] = *(const LAS bf16x8*)(lds + PG8_SB(b, h) + boff0 + n * 2048); dst[n][1] = *(const LAS bf16x8*)(lds + PG8_SB(b, h) + b1_ + n * 2048); } } while (0)
; #define PG8_MMA(ai, bj, At, Bt) do { __builtin_amdgcn_s_setprio(1); _Pragma("unroll") for (int m = 0; m < 4; ++m) _Pragma("unroll") for (int n = 0; n < 2; ++n) _Pragma("unroll") for (int k = 0; k < 2; ++k) \
;         acc[ai][bj][m][n] = __builtin_amdgcn_mfma_f32_16x16x32_bf16(Bt[n][k], At[m][k], acc[ai][bj][m][n], 0, 0, 0); __builtin_amdgcn_s_setprio(0); } while (0)
; #define PG8_WAIT_V(n) asm volatile("s_waitcnt vmcnt(" #n ")" ::: "memory")
; #define PG8_WAIT_L(n) asm volatile("s_waitcnt lgkmcnt(" #n ")" ::: "memory")
; template <class Epi>
; __device__ __forceinline__ void gemm_phase(LAS unsigned char* lds, const Gemm g, const StaticOrder& S, const Epi& E, int wave_) {
;     ...
;             const char* a1 = cA + (size_t)(t + 1) * kstep;
;             const char* a2 = last ? nA : cA + (size_t)(t + 2) * kstep; const char* b2 = last ? nB : cB + (size_t)(t + 2) * kstep;
;             const char* a3 = a2 + kstep; const char* b3 = b2 + kstep;
;             PG8_STAGE(PG8_SA(1, 1), a1 + hstepA, voffA); PG8_LDB(B0, 0, 0); PG8_LDB(B1, 0, 1); PG8_SCHED; PG8_LDA(At, 0, 0);
;             PG8_WAIT_V(8); PG8_WAIT_L(0); PG8_BAR; PG8_MMA(0, 0, At, B0); PG8_MMA(0, 1, At, B1); PG8_BAR; PG8_SCHED;
;             PG8_STAGE(PG8_SB(0, 0), b2, voffB); PG8_STAGE(PG8_SB(0, 1), b2 + hstepB, voffB); PG8_STAGE(PG8_SA(0, 0), a2, voffA); PG8_LDA(At, 0, 1);
;     ...
;         for (int a = 0; a < 2; ++a)
; #pragma unroll
;             for (int b = 0; b < 2; ++b)
; #pragma unroll
;                 for (int m = 0; m < 4; ++m)
; #pragma unroll
;                     for (int n = 0; n < 2; ++n) acc[a][b][m][n] = (f32x4){0.f, 0.f, 0.f, 0.f};
.LBB0_1551:
	s_add_u32 s16, s12, 0x100
	s_addc_u32 s17, s13, 0
	s_add_u32 s12, s36, 0x160080
	s_addc_u32 s13, s37, 0
	s_mov_b32 s59, -2
	s_add_u32 s36, s12, 0xffea0080
	s_addc_u32 s37, s13, -1
	s_cmpk_eq_i32 s59, 0x54
	s_cselect_b32 s46, s26, s36
	s_cselect_b32 s47, s27, s37
	s_cselect_b32 s40, s30, s16
	s_cselect_b32 s41, s31, s17
	s_add_u32 s36, s46, 0x80
	v_mov_b32_e32 v64, v219
	s_addc_u32 s37, s47, 0
	v_add_u32_e32 v68, s23, v219
	v_xad_u32 v76, v64, 64, s23
	v_mov_b32_e32 v80, v219
	s_add_i32 s60, 0, 0x14000
	ds_read_b128 v[64:67], v68
	ds_read_b128 v[68:71], v68 offset:2048
	ds_read_b128 v[72:75], v76
	ds_read_b128 v[76:79], v76 offset:2048
	v_add_u32_e32 v84, s60, v219
	v_xad_u32 v92, v80, 64, s60
	ds_read_b128 v[80:83], v84
	ds_read_b128 v[84:87], v84 offset:2048
	ds_read_b128 v[88:91], v92
	ds_read_b128 v[92:95], v92 offset:2048
	v_mov_b32_e32 v160, v218
	v_add_u32_e32 v191, 0, v218
	v_xad_u32 v190, v160, 64, 0
	ds_read_b128 v[160:163], v191
	ds_read_b128 v[164:167], v191 offset:2048
	ds_read_b128 v[168:171], v190
	ds_read_b128 v[172:175], v190 offset:2048
	ds_read_b128 v[176:179], v191 offset:4096
	ds_read_b128 v[180:183], v191 offset:6144
	ds_read_b128 v[192:195], v190 offset:4096
	ds_read_b128 v[196:199], v190 offset:6144
	s_mov_b32 m0, s14
	s_nop 0
	global_load_lds_dwordx4 v184, s[12:13]
	s_mov_b32 m0, s15
	s_nop 0
	global_load_lds_dwordx4 v215, s[12:13]
	s_waitcnt vmcnt(8)
	s_waitcnt lgkmcnt(0)
	s_barrier
	s_setprio 1
	s_waitcnt lgkmcnt(0)
	v_mfma_f32_16x16x32_bf16 v[156:159], v[64:67], v[160:163], 0
	v_mfma_f32_16x16x32_bf16 v[152:155], v[68:71], v[160:163], 0
	v_mfma_f32_16x16x32_bf16 v[140:143], v[64:67], v[164:167], 0
	v_mfma_f32_16x16x32_bf16 v[136:139], v[68:71], v[164:167], 0
	v_mfma_f32_16x16x32_bf16 v[124:127], v[64:67], v[176:179], 0
	v_mfma_f32_16x16x32_bf16 v[120:123], v[68:71], v[176:179], 0
	v_mfma_f32_16x16x32_bf16 v[108:111], v[64:67], v[180:183], 0
	v_mfma_f32_16x16x32_bf16 v[104:107], v[68:71], v[180:183], 0
	v_mfma_f32_16x16x32_bf16 v[156:159], v[72:75], v[168:171], v[156:159]
	v_mfma_f32_16x16x32_bf16 v[152:155], v[76:79], v[168:171], v[152:155]
	v_mfma_f32_16x16x32_bf16 v[140:143], v[72:75], v[172:175], v[140:143]
	v_mfma_f32_16x16x32_bf16 v[136:139], v[76:79], v[172:175], v[136:139]
	v_mfma_f32_16x16x32_bf16 v[124:127], v[72:75], v[192:195], v[124:127]
	v_mfma_f32_16x16x32_bf16 v[120:123], v[76:79], v[192:195], v[120:123]
	v_mfma_f32_16x16x32_bf16 v[108:111], v[72:75], v[196:199], v[108:111]
	v_mfma_f32_16x16x32_bf16 v[104:107], v[76:79], v[196:199], v[104:107]
	s_setprio 0
	s_setprio 1
	v_mfma_f32_16x16x32_bf16 v[148:151], v[80:83], v[160:163], 0
	v_mfma_f32_16x16x32_bf16 v[144:147], v[84:87], v[160:163], 0
	v_mfma_f32_16x16x32_bf16 v[132:135], v[80:83], v[164:167], 0
	v_mfma_f32_16x16x32_bf16 v[128:131], v[84:87], v[164:167], 0
	v_mfma_f32_16x16x32_bf16 v[116:119], v[80:83], v[176:179], 0
	v_mfma_f32_16x16x32_bf16 v[112:115], v[84:87], v[176:179], 0
	v_mfma_f32_16x16x32_bf16 v[100:103], v[80:83], v[180:183], 0
	v_mfma_f32_16x16x32_bf16 v[96:99], v[84:87], v[180:183], 0
	v_mfma_f32_16x16x32_bf16 v[148:151], v[88:91], v[168:171], v[148:151]
	v_mfma_f32_16x16x32_bf16 v[144:147], v[92:95], v[168:171], v[144:147]
	v_mfma_f32_16x16x32_bf16 v[132:135], v[88:91], v[172:175], v[132:135]
	v_mfma_f32_16x16x32_bf16 v[128:131], v[92:95], v[172:175], v[128:131]
	v_mfma_f32_16x16x32_bf16 v[116:119], v[88:91], v[192:195], v[116:119]
	v_mfma_f32_16x16x32_bf16 v[112:115], v[92:95], v[192:195], v[112:115]
	v_mfma_f32_16x16x32_bf16 v[100:103], v[88:91], v[196:199], v[100:103]
	v_mfma_f32_16x16x32_bf16 v[96:99], v[92:95], v[196:199], v[96:99]
	s_setprio 0
	s_barrier
	v_mov_b32_e32 v160, v218
	s_add_u32 s60, s40, 0x160000
	s_addc_u32 s61, s41, 0
	s_nop 0
	s_nop 0
	s_nop 0
	v_xad_u32 v190, v160, 64, 0
	ds_read_b128 v[160:163], v191 offset:16384
	ds_read_b128 v[164:167], v191 offset:18432
	ds_read_b128 v[168:171], v190 offset:16384
	ds_read_b128 v[172:175], v190 offset:18432
	ds_read_b128 v[176:179], v191 offset:20480
	ds_read_b128 v[180:183], v191 offset:22528
	ds_read_b128 v[192:195], v190 offset:20480
	ds_read_b128 v[196:199], v190 offset:22528
	s_mov_b32 m0, s80
	s_nop 0
	global_load_lds_dwordx4 v214, s[40:41]
	s_mov_b32 m0, s81
	s_nop 0
	global_load_lds_dwordx4 v216, s[40:41]
	s_mov_b32 m0, s29
	s_nop 0
	global_load_lds_dwordx4 v214, s[60:61]
	s_mov_b32 m0, s88
	s_nop 0
	global_load_lds_dwordx4 v216, s[60:61]
	s_mov_b32 m0, s76
	s_nop 0
	global_load_lds_dwordx4 v184, s[46:47]
	s_mov_b32 m0, s89
	s_nop 0
	global_load_lds_dwordx4 v215, s[46:47]
	s_waitcnt vmcnt(8)
	s_waitcnt lgkmcnt(0)
	s_barrier
; #define PG8_STAGE(bufoff, gbase, voff) do { _Pragma("unroll") for (int _i = 0; _i < 2; ++_i) \
;         dma16((const char*)(gbase), (voff)[_i], ldsb + (bufoff) + ldsw + _i * 8192); } while (0)
; #define PG8_LDA(dst, b, h) do { const int a1_ = opqv(aoff0) ^ 64; _Pragma("unroll") for (int m = 0; m < 4; ++m) { dst[m][0] = *(const LAS bf16x8*)(lds + PG8_SA(b, h) + aoff0 + m * 2048); dst[m][1] = *(const LAS bf16x8*)(lds + PG8_SA(b, h) + a1_ + m * 2048); } } while (0)
; #define PG8_LDB(dst, b, h) do { const int b1_ = opqv(boff0) ^ 64; _Pragma("unroll") for (int n = 0; n < 2; ++n) { dst[n][0] = *(const LAS bf16x8*)(lds + PG8_SB(b, h) + boff0 + n * 2048); dst[n][1] = *(const LAS bf16x8*)(lds + PG8_SB(b, h) + b1_ + n * 2048); } } while (0)
; #define PG8_MMA(ai, bj, At, Bt) do { __builtin_amdgcn_s_setprio(1); _Pragma("unroll") for (int m = 0; m < 4; ++m) _Pragma("unroll") for (int n = 0; n < 2; ++n) _Pragma("unroll") for (int k = 0; k < 2; ++k) \
;         acc[ai][bj][m][n] = __builtin_amdgcn_mfma_f32_16x16x32_bf16(Bt[n][k], At[m][k], acc[ai][bj][m][n], 0, 0, 0); __builtin_amdgcn_s_setprio(0); } while (0)
; #define PG8_WAIT_V(n) asm volatile("s_waitcnt vmcnt(" #n ")" ::: "memory")
; #define PG8_WAIT_L(n) asm volatile("s_waitcnt lgkmcnt(" #n ")" ::: "memory")
; #define PG8_BAR __builtin_amdgcn_s_barrier()
; #define PG8_SCHED __builtin_amdgcn_sched_barrier(0)
; template <class Epi>
; __device__ __forceinline__ void gemm_phase(LAS unsigned char* lds, const Gemm g, const StaticOrder& S, const Epi& E, int wave_) {
;     ...
;             PG8_WAIT_V(8); PG8_WAIT_L(0); PG8_BAR; PG8_MMA(1, 0, At, B0); PG8_MMA(1, 1, At, B1); PG8_BAR; PG8_SCHED;
;             PG8_STAGE(PG8_SA(0, 1), a2 + hstepA, voffA); PG8_LDB(B0, 1, 0); PG8_LDB(B1, 1, 1); PG8_SCHED; PG8_LDA(At, 1, 0);
;             PG8_WAIT_V(8); PG8_WAIT_L(0); PG8_BAR; PG8_MMA(0, 0, At, B0); PG8_MMA(0, 1, At, B1); PG8_BAR; PG8_SCHED;
	s_setprio 1
	s_waitcnt lgkmcnt(0)
	v_mfma_f32_16x16x32_bf16 v[60:63], v[64:67], v[160:163], 0
	v_mfma_f32_16x16x32_bf16 v[56:59], v[68:71], v[160:163], 0
	v_mfma_f32_16x16x32_bf16 v[44:47], v[64:67], v[164:167], 0
	v_mfma_f32_16x16x32_bf16 v[40:43], v[68:71], v[164:167], 0
	v_mfma_f32_16x16x32_bf16 v[28:31], v[64:67], v[176:179], 0
	v_mfma_f32_16x16x32_bf16 v[24:27], v[68:71], v[176:179], 0
	v_mfma_f32_16x16x32_bf16 v[12:15], v[64:67], v[180:183], 0
	v_mfma_f32_16x16x32_bf16 v[8:11], v[68:71], v[180:183], 0
	v_mfma_f32_16x16x32_bf16 v[60:63], v[72:75], v[168:171], v[60:63]
	v_mfma_f32_16x16x32_bf16 v[56:59], v[76:79], v[168:171], v[56:59]
	v_mfma_f32_16x16x32_bf16 v[44:47], v[72:75], v[172:175], v[44:47]
	v_mfma_f32_16x16x32_bf16 v[40:43], v[76:79], v[172:175], v[40:43]
	v_mfma_f32_16x16x32_bf16 v[28:31], v[72:75], v[192:195], v[28:31]
	v_mfma_f32_16x16x32_bf16 v[24:27], v[76:79], v[192:195], v[24:27]
	v_mfma_f32_16x16x32_bf16 v[12:15], v[72:75], v[196:199], v[12:15]
	v_mfma_f32_16x16x32_bf16 v[8:11], v[76:79], v[196:199], v[8:11]
	s_setprio 0
	s_setprio 1
	v_mfma_f32_16x16x32_bf16 v[52:55], v[80:83], v[160:163], 0
	v_mfma_f32_16x16x32_bf16 v[48:51], v[84:87], v[160:163], 0
	v_mfma_f32_16x16x32_bf16 v[36:39], v[80:83], v[164:167], 0
	v_mfma_f32_16x16x32_bf16 v[32:35], v[84:87], v[164:167], 0
	v_mfma_f32_16x16x32_bf16 v[20:23], v[80:83], v[176:179], 0
	v_mfma_f32_16x16x32_bf16 v[16:19], v[84:87], v[176:179], 0
	v_mfma_f32_16x16x32_bf16 v[4:7], v[80:83], v[180:183], 0
	v_mfma_f32_16x16x32_bf16 v[0:3], v[84:87], v[180:183], 0
	v_mfma_f32_16x16x32_bf16 v[52:55], v[88:91], v[168:171], v[52:55]
	v_mfma_f32_16x16x32_bf16 v[48:51], v[92:95], v[168:171], v[48:51]
	v_mfma_f32_16x16x32_bf16 v[36:39], v[88:91], v[172:175], v[36:39]
	v_mfma_f32_16x16x32_bf16 v[32:35], v[92:95], v[172:175], v[32:35]
	v_mfma_f32_16x16x32_bf16 v[20:23], v[88:91], v[192:195], v[20:23]
	v_mfma_f32_16x16x32_bf16 v[16:19], v[92:95], v[192:195], v[16:19]
	v_mfma_f32_16x16x32_bf16 v[4:7], v[88:91], v[196:199], v[4:7]
	v_mfma_f32_16x16x32_bf16 v[0:3], v[92:95], v[196:199], v[0:3]
	s_setprio 0
	s_barrier
	s_add_u32 s46, s46, 0x160000
	s_addc_u32 s47, s47, 0
	s_mov_b32 m0, s1
	s_nop 0
	global_load_lds_dwordx4 v184, s[46:47]
	v_mov_b32_e32 v64, v219
	s_mov_b32 m0, s69
	s_nop 0
	global_load_lds_dwordx4 v215, s[46:47]
	v_add_u32_e32 v68, s34, v219
	v_xad_u32 v76, v64, 64, s34
	v_mov_b32_e32 v80, v219
	s_add_i32 s46, 0, 0x1c000
	ds_read_b128 v[64:67], v68
	ds_read_b128 v[68:71], v68 offset:2048
	ds_read_b128 v[72:75], v76
	ds_read_b128 v[76:79], v76 offset:2048
	v_add_u32_e32 v84, s46, v219
	v_xad_u32 v92, v80, 64, s46
	ds_read_b128 v[80:83], v84
	ds_read_b128 v[84:87], v84 offset:2048
	ds_read_b128 v[88:91], v92
	ds_read_b128 v[92:95], v92 offset:2048
	v_mov_b32_e32 v160, v218
	s_nop 0
	v_xad_u32 v190, v160, 64, 0
	ds_read_b128 v[160:163], v191 offset:32768
	ds_read_b128 v[164:167], v191 offset:34816
	ds_read_b128 v[168:171], v190 offset:32768
	ds_read_b128 v[172:175], v190 offset:34816
	ds_read_b128 v[176:179], v191 offset:36864
	ds_read_b128 v[180:183], v191 offset:38912
	ds_read_b128 v[192:195], v190 offset:36864
	ds_read_b128 v[196:199], v190 offset:38912
	s_waitcnt vmcnt(8)
	s_waitcnt lgkmcnt(0)
	s_barrier
	s_setprio 1
	s_waitcnt lgkmcnt(0)
	v_mfma_f32_16x16x32_bf16 v[156:159], v[64:67], v[160:163], v[156:159]
	v_mfma_f32_16x16x32_bf16 v[152:155], v[68:71], v[160:163], v[152:155]
	v_mfma_f32_16x16x32_bf16 v[140:143], v[64:67], v[164:167], v[140:143]
	v_mfma_f32_16x16x32_bf16 v[136:139], v[68:71], v[164:167], v[136:139]
	v_mfma_f32_16x16x32_bf16 v[124:127], v[64:67], v[176:179], v[124:127]
	v_mfma_f32_16x16x32_bf16 v[120:123], v[68:71], v[176:179], v[120:123]
	v_mfma_f32_16x16x32_bf16 v[108:111], v[64:67], v[180:183], v[108:111]
	v_mfma_f32_16x16x32_bf16 v[104:107], v[68:71], v[180:183], v[104:107]
	v_mfma_f32_16x16x32_bf16 v[156:159], v[72:75], v[168:171], v[156:159]
	v_mfma_f32_16x16x32_bf16 v[152:155], v[76:79], v[168:171], v[152:155]
	v_mfma_f32_16x16x32_bf16 v[140:143], v[72:75], v[172:175], v[140:143]
	v_mfma_f32_16x16x32_bf16 v[136:139], v[76:79], v[172:175], v[136:139]
	v_mfma_f32_16x16x32_bf16 v[124:127], v[72:75], v[192:195], v[124:127]
	v_mfma_f32_16x16x32_bf16 v[120:123], v[76:79], v[192:195], v[120:123]
	v_mfma_f32_16x16x32_bf16 v[108:111], v[72:75], v[196:199], v[108:111]
	v_mfma_f32_16x16x32_bf16 v[104:107], v[76:79], v[196:199], v[104:107]
	s_setprio 0
	s_setprio 1
	v_mfma_f32_16x16x32_bf16 v[148:151], v[80:83], v[160:163], v[148:151]
	s_add_u32 s46, s40, 0x80
	s_addc_u32 s47, s41, 0
	v_mfma_f32_16x16x32_bf16 v[144:147], v[84:87], v[160:163], v[144:147]
	v_mfma_f32_16x16x32_bf16 v[132:135], v[80:83], v[164:167], v[132:135]
	v_mfma_f32_16x16x32_bf16 v[128:131], v[84:87], v[164:167], v[128:131]
	v_mfma_f32_16x16x32_bf16 v[116:119], v[80:83], v[176:179], v[116:119]
	v_mfma_f32_16x16x32_bf16 v[112:115], v[84:87], v[176:179], v[112:115]
	v_mfma_f32_16x16x32_bf16 v[100:103], v[80:83], v[180:183], v[100:103]
	v_mfma_f32_16x16x32_bf16 v[96:99], v[84:87], v[180:183], v[96:99]
	v_mfma_f32_16x16x32_bf16 v[148:151], v[88:91], v[168:171], v[148:151]
	v_mfma_f32_16x16x32_bf16 v[144:147], v[92:95], v[168:171], v[144:147]
	v_mfma_f32_16x16x32_bf16 v[132:135], v[88:91], v[172:175], v[132:135]
	v_mfma_f32_16x16x32_bf16 v[128:131], v[92:95], v[172:175], v[128:131]
	v_mfma_f32_16x16x32_bf16 v[116:119], v[88:91], v[192:195], v[116:119]
	v_mfma_f32_16x16x32_bf16 v[112:115], v[92:95], v[192:195], v[112:115]
	v_mfma_f32_16x16x32_bf16 v[100:103], v[88:91], v[196:199], v[100:103]
	v_mfma_f32_16x16x32_bf16 v[96:99], v[92:95], v[196:199], v[96:99]
	s_setprio 0
	s_barrier
; #define PG8_STAGE(bufoff, gbase, voff) do { _Pragma("unroll") for (int _i = 0; _i < 2; ++_i) \
;         dma16((const char*)(gbase), (voff)[_i], ldsb + (bufoff) + ldsw + _i * 8192); } while (0)
; #define PG8_LDA(dst, b, h) do { const int a1_ = opqv(aoff0) ^ 64; _Pragma("unroll") for (int m = 0; m < 4; ++m) { dst[m][0] = *(const LAS bf16x8*)(lds + PG8_SA(b, h) + aoff0 + m * 2048); dst[m][1] = *(const LAS bf16x8*)(lds + PG8_SA(b, h) + a1_ + m * 2048); } } while (0)
; #define PG8_MMA(ai, bj, At, Bt) do { __builtin_amdgcn_s_setprio(1); _Pragma("unroll") for (int m = 0; m < 4; ++m) _Pragma("unroll") for (int n = 0; n < 2; ++n) _Pragma("unroll") for (int k = 0; k < 2; ++k) \
;         acc[ai][bj][m][n] = __builtin_amdgcn_mfma_f32_16x16x32_bf16(Bt[n][k], At[m][k], acc[ai][bj][m][n], 0, 0, 0); __builtin_amdgcn_s_setprio(0); } while (0)
; #define PG8_WAIT_V(n) asm volatile("s_waitcnt vmcnt(" #n ")" ::: "memory")
; #define PG8_WAIT_L(n) asm volatile("s_waitcnt lgkmcnt(" #n ")" ::: "memory")
; #define PG8_BAR __builtin_amdgcn_s_barrier()
; #define PG8_SCHED __builtin_amdgcn_sched_barrier(0)
; template <class Epi>
; __device__ __forceinline__ void gemm_phase(LAS unsigned char* lds, const Gemm g, const StaticOrder& S, const Epi& E, int wave_) {
;     ...
;             PG8_STAGE(PG8_SB(1, 0), b3, voffB); PG8_STAGE(PG8_SB(1, 1), b3 + hstepB, voffB); PG8_STAGE(PG8_SA(1, 0), a3, voffA); PG8_LDA(At, 1, 1);
;             PG8_WAIT_V(8); PG8_WAIT_L(0); PG8_BAR; PG8_MMA(1, 0, At, B0); PG8_MMA(1, 1, At, B1); PG8_BAR; PG8_SCHED;
	s_add_u32 s40, s40, 0x160080
	s_addc_u32 s41, s41, 0
	v_mov_b32_e32 v160, v218
	s_nop 0
	s_nop 0
	v_xad_u32 v190, v160, 64, 0
	ds_read_b128 v[160:163], v191 offset:49152
	ds_read_b128 v[164:167], v191 offset:51200
	ds_read_b128 v[168:171], v190 offset:49152
	ds_read_b128 v[172:175], v190 offset:51200
	ds_read_b128 v[176:179], v191 offset:53248
	ds_read_b128 v[180:183], v191 offset:55296
	ds_read_b128 v[192:195], v190 offset:53248
	ds_read_b128 v[196:199], v190 offset:55296
	s_mov_b32 m0, s35
	s_nop 0
	global_load_lds_dwordx4 v214, s[46:47]
	s_mov_b32 m0, s33
	s_nop 0
	global_load_lds_dwordx4 v216, s[46:47]
	s_mov_b32 m0, s77
	s_nop 0
	global_load_lds_dwordx4 v214, s[40:41]
	s_mov_b32 m0, s3
	s_nop 0
	global_load_lds_dwordx4 v216, s[40:41]
	s_mov_b32 m0, s22
	s_nop 0
	global_load_lds_dwordx4 v184, s[36:37]
	s_mov_b32 m0, s2
	s_nop 0
	global_load_lds_dwordx4 v215, s[36:37]
	s_waitcnt vmcnt(8)
	s_waitcnt lgkmcnt(0)
	s_barrier
	s_setprio 1
	s_waitcnt lgkmcnt(0)
	v_mfma_f32_16x16x32_bf16 v[60:63], v[64:67], v[160:163], v[60:63]
	v_mfma_f32_16x16x32_bf16 v[56:59], v[68:71], v[160:163], v[56:59]
	v_mfma_f32_16x16x32_bf16 v[44:47], v[64:67], v[164:167], v[44:47]
	v_mfma_f32_16x16x32_bf16 v[40:43], v[68:71], v[164:167], v[40:43]
	v_mfma_f32_16x16x32_bf16 v[28:31], v[64:67], v[176:179], v[28:31]
	v_mfma_f32_16x16x32_bf16 v[24:27], v[68:71], v[176:179], v[24:27]
	v_mfma_f32_16x16x32_bf16 v[12:15], v[64:67], v[180:183], v[12:15]
	v_mfma_f32_16x16x32_bf16 v[8:11], v[68:71], v[180:183], v[8:11]
	v_mfma_f32_16x16x32_bf16 v[60:63], v[72:75], v[168:171], v[60:63]
	v_mfma_f32_16x16x32_bf16 v[56:59], v[76:79], v[168:171], v[56:59]
	v_mfma_f32_16x16x32_bf16 v[44:47], v[72:75], v[172:175], v[44:47]
	v_mfma_f32_16x16x32_bf16 v[40:43], v[76:79], v[172:175], v[40:43]
	v_mfma_f32_16x16x32_bf16 v[28:31], v[72:75], v[192:195], v[28:31]
	v_mfma_f32_16x16x32_bf16 v[24:27], v[76:79], v[192:195], v[24:27]
	v_mfma_f32_16x16x32_bf16 v[12:15], v[72:75], v[196:199], v[12:15]
	v_mfma_f32_16x16x32_bf16 v[8:11], v[76:79], v[196:199], v[8:11]
	s_setprio 0
	s_setprio 1
	v_mfma_f32_16x16x32_bf16 v[52:55], v[80:83], v[160:163], v[52:55]
	v_mfma_f32_16x16x32_bf16 v[48:51], v[84:87], v[160:163], v[48:51]
	v_mfma_f32_16x16x32_bf16 v[36:39], v[80:83], v[164:167], v[36:39]
	v_mfma_f32_16x16x32_bf16 v[32:35], v[84:87], v[164:167], v[32:35]
	v_mfma_f32_16x16x32_bf16 v[20:23], v[80:83], v[176:179], v[20:23]
	v_mfma_f32_16x16x32_bf16 v[16:19], v[84:87], v[176:179], v[16:19]
	v_mfma_f32_16x16x32_bf16 v[4:7], v[80:83], v[180:183], v[4:7]
	v_mfma_f32_16x16x32_bf16 v[0:3], v[84:87], v[180:183], v[0:3]
	v_mfma_f32_16x16x32_bf16 v[52:55], v[88:91], v[168:171], v[52:55]
	v_mfma_f32_16x16x32_bf16 v[48:51], v[92:95], v[168:171], v[48:51]
	v_mfma_f32_16x16x32_bf16 v[36:39], v[88:91], v[172:175], v[36:39]
	v_mfma_f32_16x16x32_bf16 v[32:35], v[92:95], v[172:175], v[32:35]
	v_mfma_f32_16x16x32_bf16 v[20:23], v[88:91], v[192:195], v[20:23]
	v_mfma_f32_16x16x32_bf16 v[16:19], v[92:95], v[192:195], v[16:19]
	v_mfma_f32_16x16x32_bf16 v[4:7], v[88:91], v[196:199], v[4:7]
	v_mfma_f32_16x16x32_bf16 v[0:3], v[92:95], v[196:199], v[0:3]
	s_setprio 0
	s_barrier
	s_add_i32 s59, s59, 2
	s_add_u32 s16, s16, 0x100
	s_addc_u32 s17, s17, 0
	s_add_u32 s12, s12, 0x100
	s_addc_u32 s13, s13, 0
	s_cmpk_gt_u32 s59, 0x55
	s_cbranch_scc0 .LBB0_1552
	s_branch .Lpeel_exit_1

; #define PG8_STAGE(bufoff, gbase, voff) do { _Pragma("unroll") for (int _i = 0; _i < 2; ++_i) \
;         dma16((const char*)(gbase), (voff)[_i], ldsb + (bufoff) + ldsw + _i * 8192); } while (0)
; #define PG8_LDA(dst, b, h) do { const int a1_ = opqv(aoff0) ^ 64; _Pragma("unroll") for (int m = 0; m < 4; ++m) { dst[m][0] = *(const LAS bf16x8*)(lds + PG8_SA(b, h) + aoff0 + m * 2048); dst[m][1] = *(const LAS bf16x8*)(lds + PG8_SA(b, h) + a1_ + m * 2048); } } while (0)
; #define PG8_LDB(dst, b, h) do { const int b1_ = opqv(boff0) ^ 64; _Pragma("unroll") for (int n = 0; n < 2; ++n) { dst[n][0] = *(const LAS bf16x8*)(lds + PG8_SB(b, h) + boff0 + n * 2048); dst[n][1] = *(const LAS bf16x8*)(lds + PG8_SB(b, h) + b1_ + n * 2048); } } while (0)
; #define PG8_MMA(ai, bj, At, Bt) do { __builtin_amdgcn_s_setprio(1); _Pragma("unroll") for (int m = 0; m < 4; ++m) _Pragma("unroll") for (int n = 0; n < 2; ++n) _Pragma("unroll") for (int k = 0; k < 2; ++k) \
;         acc[ai][bj][m][n] = __builtin_amdgcn_mfma_f32_16x16x32_bf16(Bt[n][k], At[m][k], acc[ai][bj][m][n], 0, 0, 0); __builtin_amdgcn_s_setprio(0); } while (0)
; #define PG8_WAIT_V(n) asm volatile("s_waitcnt vmcnt(" #n ")" ::: "memory")
; #define PG8_WAIT_L(n) asm volatile("s_waitcnt lgkmcnt(" #n ")" ::: "memory")
; template <class Epi>
; __device__ __forceinline__ void gemm_phase(LAS unsigned char* lds, const Gemm g, const StaticOrder& S, const Epi& E, int wave_) {
;     ...
;             const char* a1 = cA + (size_t)(t + 1) * kstep;
;             const char* a2 = last ? nA : cA + (size_t)(t + 2) * kstep; const char* b2 = last ? nB : cB + (size_t)(t + 2) * kstep;
;             const char* a3 = a2 + kstep; const char* b3 = b2 + kstep;
;             PG8_STAGE(PG8_SA(1, 1), a1 + hstepA, voffA); PG8_LDB(B0, 0, 0); PG8_LDB(B1, 0, 1); PG8_SCHED; PG8_LDA(At, 0, 0);
;             PG8_WAIT_V(8); PG8_WAIT_L(0); PG8_BAR; PG8_MMA(0, 0, At, B0); PG8_MMA(0, 1, At, B1); PG8_BAR; PG8_SCHED;
;             PG8_STAGE(PG8_SB(0, 0), b2, voffB); PG8_STAGE(PG8_SB(0, 1), b2 + hstepB, voffB); PG8_STAGE(PG8_SA(0, 0), a2, voffA); PG8_LDA(At, 0, 1);
;     ...
;         for (int a = 0; a < 2; ++a)
; #pragma unroll
;             for (int b = 0; b < 2; ++b)
; #pragma unroll
;                 for (int m = 0; m < 4; ++m)
; #pragma unroll
;                     for (int n = 0; n < 2; ++n) acc[a][b][m][n] = (f32x4){0.f, 0.f, 0.f, 0.f};
.LBB0_1775:
	s_ashr_i32 s59, s58, 31
	s_lshl_b64 s[16:17], s[58:59], 20
	s_add_u32 s60, s21, s16
	s_addc_u32 s61, s52, s17
	s_and_b64 s[16:17], s[44:45], exec
	s_cselect_b32 s16, s61, s47
	s_cselect_b32 s17, s60, s46
	s_ashr_i32 s57, s56, 31
	s_lshl_b64 s[48:49], s[56:57], 20
	s_add_u32 s62, s66, s48
	s_addc_u32 s63, s67, s49
	s_and_b64 s[48:49], s[44:45], exec
	s_cselect_b32 s57, s63, s13
	s_cselect_b32 s59, s62, s12
	s_add_u32 s75, s12, 0x100
	s_addc_u32 s78, s13, 0
	s_add_u32 s12, s46, 0x80080
	s_addc_u32 s13, s47, 0
	s_mov_b32 s79, -2
	s_add_u32 s46, s12, 0xfff80080
	s_addc_u32 s47, s13, -1
	s_cmp_eq_u32 s79, 28
	s_cselect_b32 s64, s17, s46
	s_cselect_b32 s65, s16, s47
	s_cselect_b32 s48, s59, s75
	s_cselect_b32 s49, s57, s78
	s_add_u32 s46, s64, 0x80
	v_mov_b32_e32 v88, v238
	s_addc_u32 s47, s65, 0
	v_add_u32_e32 v92, s23, v238
	v_xad_u32 v100, v88, 64, s23
	v_mov_b32_e32 v108, v238
	s_add_i32 s82, 0, 0x14000
	ds_read_b128 v[88:91], v92
	ds_read_b128 v[92:95], v92 offset:2048
	ds_read_b128 v[96:99], v100
	ds_read_b128 v[100:103], v100 offset:2048
	v_add_u32_e32 v112, s82, v238
	v_xad_u32 v124, v108, 64, s82
	ds_read_b128 v[108:111], v112
	ds_read_b128 v[112:115], v112 offset:2048
	ds_read_b128 v[120:123], v124
	ds_read_b128 v[124:127], v124 offset:2048
	v_mov_b32_e32 v160, v237
	v_add_u32_e32 v191, 0, v237
	v_xad_u32 v190, v160, 64, 0
	ds_read_b128 v[160:163], v191
	ds_read_b128 v[164:167], v191 offset:2048
	ds_read_b128 v[168:171], v190
	ds_read_b128 v[172:175], v190 offset:2048
	ds_read_b128 v[176:179], v191 offset:4096
	ds_read_b128 v[180:183], v191 offset:6144
	ds_read_b128 v[192:195], v190 offset:4096
	ds_read_b128 v[196:199], v190 offset:6144
	s_mov_b32 m0, s14
	s_nop 0
	global_load_lds_dwordx4 v184, s[12:13]
	s_mov_b32 m0, s15
	s_nop 0
	global_load_lds_dwordx4 v234, s[12:13]
	s_waitcnt vmcnt(8)
	s_waitcnt lgkmcnt(0)
	s_barrier
	s_setprio 1
	s_waitcnt lgkmcnt(0)
	v_mfma_f32_16x16x32_bf16 v[156:159], v[88:91], v[160:163], 0
	v_mfma_f32_16x16x32_bf16 v[152:155], v[92:95], v[160:163], 0
	v_mfma_f32_16x16x32_bf16 v[148:151], v[88:91], v[164:167], 0
	v_mfma_f32_16x16x32_bf16 v[144:147], v[92:95], v[164:167], 0
	v_mfma_f32_16x16x32_bf16 v[140:143], v[88:91], v[176:179], 0
	v_mfma_f32_16x16x32_bf16 v[136:139], v[92:95], v[176:179], 0
	v_mfma_f32_16x16x32_bf16 v[132:135], v[88:91], v[180:183], 0
	v_mfma_f32_16x16x32_bf16 v[128:131], v[92:95], v[180:183], 0
	v_mfma_f32_16x16x32_bf16 v[156:159], v[96:99], v[168:171], v[156:159]
	v_mfma_f32_16x16x32_bf16 v[152:155], v[100:103], v[168:171], v[152:155]
	v_mfma_f32_16x16x32_bf16 v[148:151], v[96:99], v[172:175], v[148:151]
	v_mfma_f32_16x16x32_bf16 v[144:147], v[100:103], v[172:175], v[144:147]
	v_mfma_f32_16x16x32_bf16 v[140:143], v[96:99], v[192:195], v[140:143]
	v_mfma_f32_16x16x32_bf16 v[136:139], v[100:103], v[192:195], v[136:139]
	v_mfma_f32_16x16x32_bf16 v[132:135], v[96:99], v[196:199], v[132:135]
	v_mfma_f32_16x16x32_bf16 v[128:131], v[100:103], v[196:199], v[128:131]
	s_setprio 0
	s_setprio 1
	v_mfma_f32_16x16x32_bf16 v[60:63], v[108:111], v[160:163], 0
	v_mfma_f32_16x16x32_bf16 v[56:59], v[112:115], v[160:163], 0
	v_mfma_f32_16x16x32_bf16 v[52:55], v[108:111], v[164:167], 0
	v_mfma_f32_16x16x32_bf16 v[48:51], v[112:115], v[164:167], 0
	v_mfma_f32_16x16x32_bf16 v[44:47], v[108:111], v[176:179], 0
	v_mfma_f32_16x16x32_bf16 v[40:43], v[112:115], v[176:179], 0
	v_mfma_f32_16x16x32_bf16 v[36:39], v[108:111], v[180:183], 0
	v_mfma_f32_16x16x32_bf16 v[32:35], v[112:115], v[180:183], 0
	v_mfma_f32_16x16x32_bf16 v[60:63], v[120:123], v[168:171], v[60:63]
	v_mfma_f32_16x16x32_bf16 v[56:59], v[124:127], v[168:171], v[56:59]
	v_mfma_f32_16x16x32_bf16 v[52:55], v[120:123], v[172:175], v[52:55]
	v_mfma_f32_16x16x32_bf16 v[48:51], v[124:127], v[172:175], v[48:51]
	v_mfma_f32_16x16x32_bf16 v[44:47], v[120:123], v[192:195], v[44:47]
	v_mfma_f32_16x16x32_bf16 v[40:43], v[124:127], v[192:195], v[40:43]
	v_mfma_f32_16x16x32_bf16 v[36:39], v[120:123], v[196:199], v[36:39]
	v_mfma_f32_16x16x32_bf16 v[32:35], v[124:127], v[196:199], v[32:35]
	s_setprio 0
	s_barrier
	v_mov_b32_e32 v160, v237
	s_add_u32 s82, s48, 0x80000
	s_addc_u32 s83, s49, 0
	s_nop 0
	s_nop 0
	s_nop 0
	v_xad_u32 v190, v160, 64, 0
	ds_read_b128 v[160:163], v191 offset:16384
	ds_read_b128 v[164:167], v191 offset:18432
	ds_read_b128 v[168:171], v190 offset:16384
	ds_read_b128 v[172:175], v190 offset:18432
	ds_read_b128 v[176:179], v191 offset:20480
	ds_read_b128 v[180:183], v191 offset:22528
	ds_read_b128 v[192:195], v190 offset:20480
	ds_read_b128 v[196:199], v190 offset:22528
	s_mov_b32 m0, s80
	s_nop 0
	global_load_lds_dwordx4 v233, s[48:49]
	s_mov_b32 m0, s81
	s_nop 0
	global_load_lds_dwordx4 v235, s[48:49]
	s_mov_b32 m0, s29
	s_nop 0
	global_load_lds_dwordx4 v233, s[82:83]
	s_mov_b32 m0, s88
	s_nop 0
	global_load_lds_dwordx4 v235, s[82:83]
	s_mov_b32 m0, s76
	s_nop 0
	global_load_lds_dwordx4 v184, s[64:65]
	s_mov_b32 m0, s89
	s_nop 0
	global_load_lds_dwordx4 v234, s[64:65]
	s_waitcnt vmcnt(8)
	s_waitcnt lgkmcnt(0)
	s_barrier
; #define PG8_STAGE(bufoff, gbase, voff) do { _Pragma("unroll") for (int _i = 0; _i < 2; ++_i) \
;         dma16((const char*)(gbase), (voff)[_i], ldsb + (bufoff) + ldsw + _i * 8192); } while (0)
; #define PG8_LDA(dst, b, h) do { const int a1_ = opqv(aoff0) ^ 64; _Pragma("unroll") for (int m = 0; m < 4; ++m) { dst[m][0] = *(const LAS bf16x8*)(lds + PG8_SA(b, h) + aoff0 + m * 2048); dst[m][1] = *(const LAS bf16x8*)(lds + PG8_SA(b, h) + a1_ + m * 2048); } } while (0)
; #define PG8_LDB(dst, b, h) do { const int b1_ = opqv(boff0) ^ 64; _Pragma("unroll") for (int n = 0; n < 2; ++n) { dst[n][0] = *(const LAS bf16x8*)(lds + PG8_SB(b, h) + boff0 + n * 2048); dst[n][1] = *(const LAS bf16x8*)(lds + PG8_SB(b, h) + b1_ + n * 2048); } } while (0)
; #define PG8_MMA(ai, bj, At, Bt) do { __builtin_amdgcn_s_setprio(1); _Pragma("unroll") for (int m = 0; m < 4; ++m) _Pragma("unroll") for (int n = 0; n < 2; ++n) _Pragma("unroll") for (int k = 0; k < 2; ++k) \
;         acc[ai][bj][m][n] = __builtin_amdgcn_mfma_f32_16x16x32_bf16(Bt[n][k], At[m][k], acc[ai][bj][m][n], 0, 0, 0); __builtin_amdgcn_s_setprio(0); } while (0)
; #define PG8_WAIT_V(n) asm volatile("s_waitcnt vmcnt(" #n ")" ::: "memory")
; #define PG8_WAIT_L(n) asm volatile("s_waitcnt lgkmcnt(" #n ")" ::: "memory")
; #define PG8_BAR __builtin_amdgcn_s_barrier()
; #define PG8_SCHED __builtin_amdgcn_sched_barrier(0)
; template <class Epi>
; __device__ __forceinline__ void gemm_phase(LAS unsigned char* lds, const Gemm g, const StaticOrder& S, const Epi& E, int wave_) {
;     ...
;             PG8_WAIT_V(8); PG8_WAIT_L(0); PG8_BAR; PG8_MMA(1, 0, At, B0); PG8_MMA(1, 1, At, B1); PG8_BAR; PG8_SCHED;
;             PG8_STAGE(PG8_SA(0, 1), a2 + hstepA, voffA); PG8_LDB(B0, 1, 0); PG8_LDB(B1, 1, 1); PG8_SCHED; PG8_LDA(At, 1, 0);
;             PG8_WAIT_V(8); PG8_WAIT_L(0); PG8_BAR; PG8_MMA(0, 0, At, B0); PG8_MMA(0, 1, At, B1); PG8_BAR; PG8_SCHED;
	s_setprio 1
	s_waitcnt lgkmcnt(0)
	v_mfma_f32_16x16x32_bf16 v[116:119], v[88:91], v[160:163], 0
	v_mfma_f32_16x16x32_bf16 v[104:107], v[92:95], v[160:163], 0
	v_mfma_f32_16x16x32_bf16 v[84:87], v[88:91], v[164:167], 0
	v_mfma_f32_16x16x32_bf16 v[80:83], v[92:95], v[164:167], 0
	v_mfma_f32_16x16x32_bf16 v[76:79], v[88:91], v[176:179], 0
	v_mfma_f32_16x16x32_bf16 v[72:75], v[92:95], v[176:179], 0
	v_mfma_f32_16x16x32_bf16 v[68:71], v[88:91], v[180:183], 0
	v_mfma_f32_16x16x32_bf16 v[64:67], v[92:95], v[180:183], 0
	v_mfma_f32_16x16x32_bf16 v[116:119], v[96:99], v[168:171], v[116:119]
	v_mfma_f32_16x16x32_bf16 v[104:107], v[100:103], v[168:171], v[104:107]
	v_mfma_f32_16x16x32_bf16 v[84:87], v[96:99], v[172:175], v[84:87]
	v_mfma_f32_16x16x32_bf16 v[80:83], v[100:103], v[172:175], v[80:83]
	v_mfma_f32_16x16x32_bf16 v[76:79], v[96:99], v[192:195], v[76:79]
	v_mfma_f32_16x16x32_bf16 v[72:75], v[100:103], v[192:195], v[72:75]
	v_mfma_f32_16x16x32_bf16 v[68:71], v[96:99], v[196:199], v[68:71]
	v_mfma_f32_16x16x32_bf16 v[64:67], v[100:103], v[196:199], v[64:67]
	s_setprio 0
	s_setprio 1
	v_mfma_f32_16x16x32_bf16 v[28:31], v[108:111], v[160:163], 0
	v_mfma_f32_16x16x32_bf16 v[24:27], v[112:115], v[160:163], 0
	v_mfma_f32_16x16x32_bf16 v[20:23], v[108:111], v[164:167], 0
	v_mfma_f32_16x16x32_bf16 v[16:19], v[112:115], v[164:167], 0
	v_mfma_f32_16x16x32_bf16 v[12:15], v[108:111], v[176:179], 0
	v_mfma_f32_16x16x32_bf16 v[8:11], v[112:115], v[176:179], 0
	v_mfma_f32_16x16x32_bf16 v[4:7], v[108:111], v[180:183], 0
	v_mfma_f32_16x16x32_bf16 v[0:3], v[112:115], v[180:183], 0
	v_mfma_f32_16x16x32_bf16 v[28:31], v[120:123], v[168:171], v[28:31]
	v_mfma_f32_16x16x32_bf16 v[24:27], v[124:127], v[168:171], v[24:27]
	v_mfma_f32_16x16x32_bf16 v[20:23], v[120:123], v[172:175], v[20:23]
	v_mfma_f32_16x16x32_bf16 v[16:19], v[124:127], v[172:175], v[16:19]
	v_mfma_f32_16x16x32_bf16 v[12:15], v[120:123], v[192:195], v[12:15]
	v_mfma_f32_16x16x32_bf16 v[8:11], v[124:127], v[192:195], v[8:11]
	v_mfma_f32_16x16x32_bf16 v[4:7], v[120:123], v[196:199], v[4:7]
	v_mfma_f32_16x16x32_bf16 v[0:3], v[124:127], v[196:199], v[0:3]
	s_setprio 0
	s_barrier
	s_add_u32 s64, s64, 0x80000
	s_addc_u32 s65, s65, 0
	s_mov_b32 m0, s1
	s_nop 0
	global_load_lds_dwordx4 v184, s[64:65]
	v_mov_b32_e32 v88, v238
	s_mov_b32 m0, s69
	s_nop 0
	global_load_lds_dwordx4 v234, s[64:65]
	v_add_u32_e32 v92, s34, v238
	v_xad_u32 v100, v88, 64, s34
	v_mov_b32_e32 v108, v238
	s_add_i32 s64, 0, 0x1c000
	ds_read_b128 v[88:91], v92
	ds_read_b128 v[92:95], v92 offset:2048
	ds_read_b128 v[96:99], v100
	ds_read_b128 v[100:103], v100 offset:2048
	v_add_u32_e32 v112, s64, v238
	v_xad_u32 v124, v108, 64, s64
	ds_read_b128 v[108:111], v112
	ds_read_b128 v[112:115], v112 offset:2048
	ds_read_b128 v[120:123], v124
	ds_read_b128 v[124:127], v124 offset:2048
	v_mov_b32_e32 v160, v237
	s_nop 0
	v_xad_u32 v190, v160, 64, 0
	ds_read_b128 v[160:163], v191 offset:32768
	ds_read_b128 v[164:167], v191 offset:34816
	ds_read_b128 v[168:171], v190 offset:32768
	ds_read_b128 v[172:175], v190 offset:34816
	ds_read_b128 v[176:179], v191 offset:36864
	ds_read_b128 v[180:183], v191 offset:38912
	ds_read_b128 v[192:195], v190 offset:36864
	ds_read_b128 v[196:199], v190 offset:38912
	s_waitcnt vmcnt(8)
	s_waitcnt lgkmcnt(0)
	s_barrier
	s_setprio 1
	s_waitcnt lgkmcnt(0)
	v_mfma_f32_16x16x32_bf16 v[156:159], v[88:91], v[160:163], v[156:159]
	v_mfma_f32_16x16x32_bf16 v[152:155], v[92:95], v[160:163], v[152:155]
	v_mfma_f32_16x16x32_bf16 v[148:151], v[88:91], v[164:167], v[148:151]
	v_mfma_f32_16x16x32_bf16 v[144:147], v[92:95], v[164:167], v[144:147]
	v_mfma_f32_16x16x32_bf16 v[140:143], v[88:91], v[176:179], v[140:143]
	v_mfma_f32_16x16x32_bf16 v[136:139], v[92:95], v[176:179], v[136:139]
	v_mfma_f32_16x16x32_bf16 v[132:135], v[88:91], v[180:183], v[132:135]
	v_mfma_f32_16x16x32_bf16 v[128:131], v[92:95], v[180:183], v[128:131]
	v_mfma_f32_16x16x32_bf16 v[156:159], v[96:99], v[168:171], v[156:159]
	v_mfma_f32_16x16x32_bf16 v[152:155], v[100:103], v[168:171], v[152:155]
	v_mfma_f32_16x16x32_bf16 v[148:151], v[96:99], v[172:175], v[148:151]
	v_mfma_f32_16x16x32_bf16 v[144:147], v[100:103], v[172:175], v[144:147]
	v_mfma_f32_16x16x32_bf16 v[140:143], v[96:99], v[192:195], v[140:143]
	v_mfma_f32_16x16x32_bf16 v[136:139], v[100:103], v[192:195], v[136:139]
	v_mfma_f32_16x16x32_bf16 v[132:135], v[96:99], v[196:199], v[132:135]
	v_mfma_f32_16x16x32_bf16 v[128:131], v[100:103], v[196:199], v[128:131]
	s_setprio 0
	s_setprio 1
	v_mfma_f32_16x16x32_bf16 v[60:63], v[108:111], v[160:163], v[60:63]
	s_add_u32 s64, s48, 0x80
	s_addc_u32 s65, s49, 0
	v_mfma_f32_16x16x32_bf16 v[56:59], v[112:115], v[160:163], v[56:59]
	v_mfma_f32_16x16x32_bf16 v[52:55], v[108:111], v[164:167], v[52:55]
	v_mfma_f32_16x16x32_bf16 v[48:51], v[112:115], v[164:167], v[48:51]
	v_mfma_f32_16x16x32_bf16 v[44:47], v[108:111], v[176:179], v[44:47]
	v_mfma_f32_16x16x32_bf16 v[40:43], v[112:115], v[176:179], v[40:43]
	v_mfma_f32_16x16x32_bf16 v[36:39], v[108:111], v[180:183], v[36:39]
	v_mfma_f32_16x16x32_bf16 v[32:35], v[112:115], v[180:183], v[32:35]
	v_mfma_f32_16x16x32_bf16 v[60:63], v[120:123], v[168:171], v[60:63]
	v_mfma_f32_16x16x32_bf16 v[56:59], v[124:127], v[168:171], v[56:59]
	v_mfma_f32_16x16x32_bf16 v[52:55], v[120:123], v[172:175], v[52:55]
	v_mfma_f32_16x16x32_bf16 v[48:51], v[124:127], v[172:175], v[48:51]
	v_mfma_f32_16x16x32_bf16 v[44:47], v[120:123], v[192:195], v[44:47]
	v_mfma_f32_16x16x32_bf16 v[40:43], v[124:127], v[192:195], v[40:43]
	v_mfma_f32_16x16x32_bf16 v[36:39], v[120:123], v[196:199], v[36:39]
	v_mfma_f32_16x16x32_bf16 v[32:35], v[124:127], v[196:199], v[32:35]
	s_setprio 0
	s_barrier
; #define PG8_STAGE(bufoff, gbase, voff) do { _Pragma("unroll") for (int _i = 0; _i < 2; ++_i) \
;         dma16((const char*)(gbase), (voff)[_i], ldsb + (bufoff) + ldsw + _i * 8192); } while (0)
; #define PG8_LDA(dst, b, h) do { const int a1_ = opqv(aoff0) ^ 64; _Pragma("unroll") for (int m = 0; m < 4; ++m) { dst[m][0] = *(const LAS bf16x8*)(lds + PG8_SA(b, h) + aoff0 + m * 2048); dst[m][1] = *(const LAS bf16x8*)(lds + PG8_SA(b, h) + a1_ + m * 2048); } } while (0)
; #define PG8_MMA(ai, bj, At, Bt) do { __builtin_amdgcn_s_setprio(1); _Pragma("unroll") for (int m = 0; m < 4; ++m) _Pragma("unroll") for (int n = 0; n < 2; ++n) _Pragma("unroll") for (int k = 0; k < 2; ++k) \
;         acc[ai][bj][m][n] = __builtin_amdgcn_mfma_f32_16x16x32_bf16(Bt[n][k], At[m][k], acc[ai][bj][m][n], 0, 0, 0); __builtin_amdgcn_s_setprio(0); } while (0)
; #define PG8_WAIT_V(n) asm volatile("s_waitcnt vmcnt(" #n ")" ::: "memory")
; #define PG8_WAIT_L(n) asm volatile("s_waitcnt lgkmcnt(" #n ")" ::: "memory")
; #define PG8_BAR __builtin_amdgcn_s_barrier()
; #define PG8_SCHED __builtin_amdgcn_sched_barrier(0)
; template <class Epi>
; __device__ __forceinline__ void gemm_phase(LAS unsigned char* lds, const Gemm g, const StaticOrder& S, const Epi& E, int wave_) {
;     ...
;             PG8_STAGE(PG8_SB(1, 0), b3, voffB); PG8_STAGE(PG8_SB(1, 1), b3 + hstepB, voffB); PG8_STAGE(PG8_SA(1, 0), a3, voffA); PG8_LDA(At, 1, 1);
;             PG8_WAIT_V(8); PG8_WAIT_L(0); PG8_BAR; PG8_MMA(1, 0, At, B0); PG8_MMA(1, 1, At, B1); PG8_BAR; PG8_SCHED;
	s_add_u32 s48, s48, 0x80080
	s_addc_u32 s49, s49, 0
	v_mov_b32_e32 v160, v237
	s_nop 0
	s_nop 0
	v_xad_u32 v190, v160, 64, 0
	ds_read_b128 v[160:163], v191 offset:49152
	ds_read_b128 v[164:167], v191 offset:51200
	ds_read_b128 v[168:171], v190 offset:49152
	ds_read_b128 v[172:175], v190 offset:51200
	ds_read_b128 v[176:179], v191 offset:53248
	ds_read_b128 v[180:183], v191 offset:55296
	ds_read_b128 v[192:195], v190 offset:53248
	ds_read_b128 v[196:199], v190 offset:55296
	s_mov_b32 m0, s35
	s_nop 0
	global_load_lds_dwordx4 v233, s[64:65]
	s_mov_b32 m0, s33
	s_nop 0
	global_load_lds_dwordx4 v235, s[64:65]
	s_mov_b32 m0, s77
	s_nop 0
	global_load_lds_dwordx4 v233, s[48:49]
	s_mov_b32 m0, s3
	s_nop 0
	global_load_lds_dwordx4 v235, s[48:49]
	s_mov_b32 m0, s22
	s_nop 0
	global_load_lds_dwordx4 v184, s[46:47]
	s_mov_b32 m0, s2
	s_nop 0
	global_load_lds_dwordx4 v234, s[46:47]
	s_waitcnt vmcnt(8)
	s_waitcnt lgkmcnt(0)
	s_barrier
	s_setprio 1
	s_waitcnt lgkmcnt(0)
	v_mfma_f32_16x16x32_bf16 v[116:119], v[88:91], v[160:163], v[116:119]
	v_mfma_f32_16x16x32_bf16 v[104:107], v[92:95], v[160:163], v[104:107]
	v_mfma_f32_16x16x32_bf16 v[84:87], v[88:91], v[164:167], v[84:87]
	v_mfma_f32_16x16x32_bf16 v[80:83], v[92:95], v[164:167], v[80:83]
	v_mfma_f32_16x16x32_bf16 v[76:79], v[88:91], v[176:179], v[76:79]
	v_mfma_f32_16x16x32_bf16 v[72:75], v[92:95], v[176:179], v[72:75]
	v_mfma_f32_16x16x32_bf16 v[68:71], v[88:91], v[180:183], v[68:71]
	v_mfma_f32_16x16x32_bf16 v[64:67], v[92:95], v[180:183], v[64:67]
	v_mfma_f32_16x16x32_bf16 v[116:119], v[96:99], v[168:171], v[116:119]
	v_mfma_f32_16x16x32_bf16 v[104:107], v[100:103], v[168:171], v[104:107]
	v_mfma_f32_16x16x32_bf16 v[84:87], v[96:99], v[172:175], v[84:87]
	v_mfma_f32_16x16x32_bf16 v[80:83], v[100:103], v[172:175], v[80:83]
	v_mfma_f32_16x16x32_bf16 v[76:79], v[96:99], v[192:195], v[76:79]
	v_mfma_f32_16x16x32_bf16 v[72:75], v[100:103], v[192:195], v[72:75]
	v_mfma_f32_16x16x32_bf16 v[68:71], v[96:99], v[196:199], v[68:71]
	v_mfma_f32_16x16x32_bf16 v[64:67], v[100:103], v[196:199], v[64:67]
	s_setprio 0
	s_setprio 1
	v_mfma_f32_16x16x32_bf16 v[28:31], v[108:111], v[160:163], v[28:31]
	v_mfma_f32_16x16x32_bf16 v[24:27], v[112:115], v[160:163], v[24:27]
	v_mfma_f32_16x16x32_bf16 v[20:23], v[108:111], v[164:167], v[20:23]
	v_mfma_f32_16x16x32_bf16 v[16:19], v[112:115], v[164:167], v[16:19]
	v_mfma_f32_16x16x32_bf16 v[12:15], v[108:111], v[176:179], v[12:15]
	v_mfma_f32_16x16x32_bf16 v[8:11], v[112:115], v[176:179], v[8:11]
	v_mfma_f32_16x16x32_bf16 v[4:7], v[108:111], v[180:183], v[4:7]
	v_mfma_f32_16x16x32_bf16 v[0:3], v[112:115], v[180:183], v[0:3]
	v_mfma_f32_16x16x32_bf16 v[28:31], v[120:123], v[168:171], v[28:31]
	v_mfma_f32_16x16x32_bf16 v[24:27], v[124:127], v[168:171], v[24:27]
	v_mfma_f32_16x16x32_bf16 v[20:23], v[120:123], v[172:175], v[20:23]
	v_mfma_f32_16x16x32_bf16 v[16:19], v[124:127], v[172:175], v[16:19]
	v_mfma_f32_16x16x32_bf16 v[12:15], v[120:123], v[192:195], v[12:15]
	v_mfma_f32_16x16x32_bf16 v[8:11], v[124:127], v[192:195], v[8:11]
	v_mfma_f32_16x16x32_bf16 v[4:7], v[120:123], v[196:199], v[4:7]
	v_mfma_f32_16x16x32_bf16 v[0:3], v[124:127], v[196:199], v[0:3]
	s_setprio 0
	s_barrier
	s_add_i32 s79, s79, 2
	s_add_u32 s75, s75, 0x100
	s_addc_u32 s78, s78, 0
	s_add_u32 s12, s12, 0x100
	s_addc_u32 s13, s13, 0
	s_cmp_gt_u32 s79, 29
	s_cbranch_scc0 .LBB0_1776
	s_branch .Lpeel_exit_0
